# replace ds_bpermute xor-16/32 row-sum shuffles by v_permlane16/32_swap in all epilogues
# speedup vs baseline: 1.0998x; 1.0017x over previous
.LBB0_52:
	s_waitcnt lgkmcnt(0)
	global_load_dwordx4 v[14:17], v[6:7], off offset:-2048 nt
	global_load_dwordx4 v[18:21], v[6:7], off offset:-1024 nt
	global_load_dwordx4 v[22:25], v[6:7], off nt
	global_load_dwordx4 v[26:29], v[6:7], off offset:1024 nt
	s_waitcnt vmcnt(3)
	v_mul_f32_e32 v2, v15, v15
	v_mul_f32_e32 v30, v17, v17
	s_waitcnt vmcnt(2)
	v_mul_f32_e32 v31, v19, v19
	v_mul_f32_e32 v32, v21, v21
	s_waitcnt vmcnt(1)
	v_mul_f32_e32 v33, v23, v23
	v_mul_f32_e32 v34, v25, v25
	v_fmac_f32_e32 v2, v14, v14
	v_fmac_f32_e32 v30, v16, v16
	v_fmac_f32_e32 v31, v18, v18
	v_fmac_f32_e32 v32, v20, v20
	s_waitcnt vmcnt(0)
	v_mul_f32_e32 v35, v27, v27
	v_mul_f32_e32 v36, v29, v29
	v_fmac_f32_e32 v33, v22, v22
	v_fmac_f32_e32 v34, v24, v24
	v_add_f32_e32 v2, v2, v30
	v_add_f32_e32 v30, v31, v32
	v_fmac_f32_e32 v35, v26, v26
	v_fmac_f32_e32 v36, v28, v28
	v_add_f32_e32 v31, v33, v34
	v_add_f32_e32 v2, v2, v30
	v_add_f32_e32 v32, v35, v36
	v_add_f32_e32 v2, v2, v31
	v_add_f32_e32 v2, v2, v32
	ds_bpermute_b32 v30, v8, v2
	v_bfe_u32 v37, v14, 16, 1
	v_bfe_u32 v39, v16, 16, 1
	v_bfe_u32 v43, v20, 16, 1
	v_bfe_u32 v38, v15, 16, 1
	s_waitcnt lgkmcnt(0)
	v_add_f32_e32 v2, v2, v30
	ds_bpermute_b32 v30, v9, v2
	v_bfe_u32 v40, v17, 16, 1
	v_bfe_u32 v44, v21, 16, 1
	v_add3_u32 v14, v14, v37, s26
	v_add3_u32 v16, v16, v39, s26
	s_waitcnt lgkmcnt(0)
	v_add_f32_e32 v2, v2, v30
	ds_bpermute_b32 v30, v10, v2
	v_add3_u32 v20, v20, v43, s26
	v_add3_u32 v15, v15, v38, s26
	v_add3_u32 v17, v17, v40, s26
	v_add3_u32 v21, v21, v44, s26
	s_waitcnt lgkmcnt(0)
	v_add_f32_e32 v2, v2, v30
	ds_bpermute_b32 v30, v11, v2
	v_lshrrev_b32_e32 v14, 16, v14
	v_lshrrev_b32_e32 v16, 16, v16
	v_lshrrev_b32_e32 v20, 16, v20
	v_and_or_b32 v14, v15, s27, v14
	s_waitcnt lgkmcnt(0)
	v_add_f32_e32 v2, v2, v30
	v_and_or_b32 v15, v17, s27, v16
	v_and_or_b32 v17, v21, s27, v20
	v_mov_b32_e32 v21, v2
	s_nop 1
	v_permlane16_swap_b32_e32 v21, v2
	v_bfe_u32 v41, v18, 16, 1
	v_bfe_u32 v45, v22, 16, 1
	v_bfe_u32 v47, v24, 16, 1
	v_bfe_u32 v42, v19, 16, 1
	v_bfe_u32 v46, v23, 16, 1
	v_bfe_u32 v48, v25, 16, 1
	v_add3_u32 v18, v18, v41, s26
	v_add3_u32 v22, v22, v45, s26
	v_add3_u32 v24, v24, v47, s26
	v_add3_u32 v19, v19, v42, s26
	v_add3_u32 v23, v23, v46, s26
	v_add3_u32 v25, v25, v48, s26
	v_lshrrev_b32_e32 v18, 16, v18
	v_lshrrev_b32_e32 v22, 16, v22
	v_lshrrev_b32_e32 v24, 16, v24
	s_waitcnt lgkmcnt(0)
	v_add_f32_e32 v2, v2, v21
	v_and_or_b32 v16, v19, s27, v18
	v_and_or_b32 v18, v23, s27, v22
	v_and_or_b32 v19, v25, s27, v24
	global_store_dwordx2 v[4:5], v[14:15], off offset:-1536
	global_store_dwordx2 v[4:5], v[16:17], off offset:-1024
	global_store_dwordx2 v[4:5], v[18:19], off offset:-512
	v_mov_b32_e32 v14, v2
	s_nop 1
	v_permlane32_swap_b32_e32 v14, v2
	v_bfe_u32 v49, v26, 16, 1
	v_bfe_u32 v51, v28, 16, 1
	v_bfe_u32 v50, v27, 16, 1
	v_add3_u32 v26, v26, v49, s26
	v_add3_u32 v28, v28, v51, s26
	v_bfe_u32 v16, v29, 16, 1
	v_add3_u32 v27, v27, v50, s26
	v_lshrrev_b32_e32 v26, 16, v26
	v_lshrrev_b32_e32 v15, 16, v28
	v_add3_u32 v16, v29, v16, s26
	v_and_or_b32 v20, v27, s27, v26
	v_and_or_b32 v21, v16, s27, v15
	global_store_dwordx2 v[4:5], v[20:21], off
	s_and_saveexec_b64 s[24:25], vcc
	s_cbranch_execz .LBB0_51
	s_waitcnt lgkmcnt(0)
	v_add_f32_e32 v2, v2, v14
	global_store_dword v3, v2, s[4:5]
	s_branch .LBB0_51

.LBB0_254:
	s_lshl_b32 s44, s68, 8
	v_lshl_add_u32 v238, s67, 8, v243
	s_ashr_i32 s45, s44, 31
	s_lshl_b64 s[46:47], s[44:45], 1
	v_ashrrev_i32_e32 v239, 31, v238
	v_lshl_add_u64 v[126:127], v[204:205], 0, s[46:47]
	v_lshlrev_b64 v[240:241], 11, v[238:239]
	v_lshl_add_u64 v[122:123], v[126:127], 0, v[240:241]
	global_load_dwordx4 v[190:193], v[122:123], off
	global_load_dwordx4 v[186:189], v[122:123], off offset:256
	v_or_b32_e32 v234, 16, v238
	v_ashrrev_i32_e32 v235, 31, v234
	v_or_b32_e32 v230, 32, v238
	v_lshlrev_b64 v[236:237], 11, v[234:235]
	v_ashrrev_i32_e32 v231, 31, v230
	v_or_b32_e32 v226, 48, v238
	v_lshl_add_u64 v[122:123], v[126:127], 0, v[236:237]
	v_lshlrev_b64 v[232:233], 11, v[230:231]
	v_ashrrev_i32_e32 v227, 31, v226
	v_add_u32_e32 v222, 0x80, v238
	global_load_dwordx4 v[182:185], v[122:123], off
	global_load_dwordx4 v[178:181], v[122:123], off offset:256
	v_lshl_add_u64 v[122:123], v[126:127], 0, v[232:233]
	v_lshlrev_b64 v[228:229], 11, v[226:227]
	v_ashrrev_i32_e32 v223, 31, v222
	v_add_u32_e32 v218, 0x90, v238
	global_load_dwordx4 v[174:177], v[122:123], off
	global_load_dwordx4 v[170:173], v[122:123], off offset:256
	v_lshl_add_u64 v[122:123], v[126:127], 0, v[228:229]
	v_lshlrev_b64 v[224:225], 11, v[222:223]
	v_ashrrev_i32_e32 v219, 31, v218
	v_add_u32_e32 v212, 0xa0, v238
	v_add_u32_e32 v210, 0xb0, v238
	global_load_dwordx4 v[166:169], v[122:123], off
	global_load_dwordx4 v[162:165], v[122:123], off offset:256
	v_lshl_add_u64 v[122:123], v[126:127], 0, v[224:225]
	v_lshlrev_b64 v[220:221], 11, v[218:219]
	v_ashrrev_i32_e32 v213, 31, v212
	v_ashrrev_i32_e32 v211, 31, v210
	global_load_dwordx4 v[158:161], v[122:123], off
	global_load_dwordx4 v[146:149], v[122:123], off offset:256
	v_lshl_add_u64 v[122:123], v[126:127], 0, v[220:221]
	v_lshlrev_b64 v[216:217], 11, v[212:213]
	v_lshlrev_b64 v[214:215], 11, v[210:211]
	global_load_dwordx4 v[142:145], v[122:123], off
	global_load_dwordx4 v[138:141], v[122:123], off offset:256
	v_lshl_add_u64 v[122:123], v[126:127], 0, v[216:217]
	v_lshl_add_u64 v[126:127], v[126:127], 0, v[214:215]
	global_load_dwordx4 v[130:133], v[122:123], off
	s_nop 0
	global_load_dwordx4 v[122:125], v[122:123], off offset:256
	s_nop 0
	global_load_dwordx4 v[134:137], v[126:127], off
	s_nop 0
	global_load_dwordx4 v[126:129], v[126:127], off offset:256
	v_lshl_add_u64 v[240:241], s[14:15], 0, v[240:241]
	v_lshl_add_u64 v[240:241], v[240:241], 0, s[46:47]
	v_lshl_add_u64 v[240:241], v[240:241], 0, v[202:203]
	v_and_b32_e32 v250, 64, v248
	v_xor_b32_e32 v249, 16, v248
	v_add_u32_e32 v250, 64, v250
	v_cmp_lt_i32_e32 vcc, v249, v250
	v_xor_b32_e32 v251, 32, v248
	s_waitcnt vmcnt(0)
	v_lshlrev_b32_e32 v252, 16, v190
	v_and_b32_e32 v253, 0xffff0000, v190
	v_lshlrev_b32_e32 v190, 16, v191
	v_and_b32_e32 v191, 0xffff0000, v191
	v_lshlrev_b32_e32 v254, 16, v192
	v_and_b32_e32 v255, 0xffff0000, v192
	v_lshlrev_b32_e32 v192, 16, v193
	v_and_b32_e32 v193, 0xffff0000, v193
	v_pk_fma_f32 v[156:157], v[156:157], 0.5, v[190:191] op_sel_hi:[1,0,1]
	v_pk_fma_f32 v[154:155], v[154:155], 0.5, v[252:253] op_sel_hi:[1,0,1]
	v_pk_fma_f32 v[190:191], v[152:153], 0.5, v[192:193] op_sel_hi:[1,0,1]
	v_pk_fma_f32 v[192:193], v[150:151], 0.5, v[254:255] op_sel_hi:[1,0,1]
	v_cvt_pk_bf16_f32 v150, v154, v155
	v_cvt_pk_bf16_f32 v151, v156, v157
	v_cvt_pk_bf16_f32 v152, v192, v193
	v_cvt_pk_bf16_f32 v153, v190, v191
	global_store_dwordx4 v[240:241], v[150:153], off
	v_cndmask_b32_e32 v249, v248, v249, vcc
	v_lshlrev_b32_e32 v249, 2, v249
	v_mul_f32_e32 v150, v155, v155
	v_mul_f32_e32 v151, v157, v157
	v_fmac_f32_e32 v150, v154, v154
	v_fmac_f32_e32 v151, v156, v156
	v_add_f32_e32 v150, v150, v151
	v_mul_f32_e32 v151, v193, v193
	v_mul_f32_e32 v152, v191, v191
	v_fmac_f32_e32 v151, v192, v192
	v_fmac_f32_e32 v152, v190, v190
	v_add_f32_e32 v151, v151, v152
	v_add_f32_e32 v190, v150, v151
	v_lshlrev_b32_e32 v150, 16, v186
	v_and_b32_e32 v151, 0xffff0000, v186
	v_lshlrev_b32_e32 v152, 16, v187
	v_and_b32_e32 v153, 0xffff0000, v187
	v_lshlrev_b32_e32 v154, 16, v188
	v_and_b32_e32 v155, 0xffff0000, v188
	v_lshlrev_b32_e32 v156, 16, v189
	v_and_b32_e32 v157, 0xffff0000, v189
	v_pk_fma_f32 v[120:121], v[120:121], 0.5, v[152:153] op_sel_hi:[1,0,1]
	v_pk_fma_f32 v[118:119], v[118:119], 0.5, v[150:151] op_sel_hi:[1,0,1]
	v_pk_fma_f32 v[150:151], v[116:117], 0.5, v[156:157] op_sel_hi:[1,0,1]
	v_pk_fma_f32 v[152:153], v[114:115], 0.5, v[154:155] op_sel_hi:[1,0,1]
	v_cvt_pk_bf16_f32 v114, v118, v119
	v_cvt_pk_bf16_f32 v115, v120, v121
	v_cvt_pk_bf16_f32 v116, v152, v153
	v_cvt_pk_bf16_f32 v117, v150, v151
	global_store_dwordx4 v[240:241], v[114:117], off offset:256
	v_cmp_lt_i32_e32 vcc, v251, v250
	s_nop 0
	v_mul_f32_e32 v114, v119, v119
	v_mul_f32_e32 v115, v121, v121
	v_fmac_f32_e32 v114, v118, v118
	v_fmac_f32_e32 v115, v120, v120
	v_add_f32_e32 v114, v114, v115
	v_mul_f32_e32 v115, v153, v153
	v_mul_f32_e32 v116, v151, v151
	v_fmac_f32_e32 v115, v152, v152
	v_fmac_f32_e32 v116, v150, v150
	v_add_f32_e32 v115, v115, v116
	v_add_f32_e32 v114, v114, v115
	v_add_f32_e32 v114, v190, v114
	v_mov_b32_e32 v115, v114
	s_nop 1
	v_permlane16_swap_b32_e32 v115, v114
	v_cndmask_b32_e32 v250, v248, v251, vcc
	v_lshlrev_b32_e32 v250, 2, v250
	s_waitcnt lgkmcnt(0)
	v_add_f32_e32 v114, v114, v115
	v_mov_b32_e32 v115, v114
	s_nop 1
	v_permlane32_swap_b32_e32 v115, v114
	s_and_saveexec_b64 s[46:47], s[4:5]
	s_cbranch_execz .LBB0_256
	v_lshl_add_u64 v[116:117], v[238:239], 2, s[16:17]
	s_waitcnt lgkmcnt(0)
	v_add_f32_e32 v114, v114, v115
	global_atomic_add_f32 v[116:117], v114, off
.LBB0_256:
	s_or_b64 exec, exec, s[46:47]
	v_lshlrev_b32_e32 v114, 16, v182
	s_waitcnt lgkmcnt(0)
	v_and_b32_e32 v115, 0xffff0000, v182
	v_lshlrev_b32_e32 v116, 16, v183
	v_and_b32_e32 v117, 0xffff0000, v183
	v_lshlrev_b32_e32 v118, 16, v184
	v_and_b32_e32 v119, 0xffff0000, v184
	v_pk_fma_f32 v[110:111], v[110:111], 0.5, v[114:115] op_sel_hi:[1,0,1]
	v_pk_fma_f32 v[112:113], v[112:113], 0.5, v[116:117] op_sel_hi:[1,0,1]
	v_pk_fma_f32 v[116:117], v[106:107], 0.5, v[118:119] op_sel_hi:[1,0,1]
	v_cvt_pk_bf16_f32 v106, v110, v111
	v_mul_f32_e32 v111, v111, v111
	v_lshlrev_b32_e32 v120, 16, v185
	v_and_b32_e32 v121, 0xffff0000, v185
	v_fmac_f32_e32 v111, v110, v110
	v_mul_f32_e32 v110, v113, v113
	v_pk_fma_f32 v[114:115], v[108:109], 0.5, v[120:121] op_sel_hi:[1,0,1]
	v_fmac_f32_e32 v110, v112, v112
	v_cvt_pk_bf16_f32 v107, v112, v113
	v_add_f32_e32 v110, v111, v110
	v_mul_f32_e32 v111, v117, v117
	v_mul_f32_e32 v112, v115, v115
	v_fmac_f32_e32 v111, v116, v116
	v_fmac_f32_e32 v112, v114, v114
	v_add_f32_e32 v111, v111, v112
	v_add_f32_e32 v120, v110, v111
	v_lshlrev_b32_e32 v110, 16, v178
	v_and_b32_e32 v111, 0xffff0000, v178
	v_lshlrev_b32_e32 v112, 16, v179
	v_and_b32_e32 v113, 0xffff0000, v179
	v_cvt_pk_bf16_f32 v109, v114, v115
	v_lshlrev_b32_e32 v114, 16, v180
	v_and_b32_e32 v115, 0xffff0000, v180
	v_pk_fma_f32 v[104:105], v[104:105], 0.5, v[112:113] op_sel_hi:[1,0,1]
	v_pk_fma_f32 v[102:103], v[102:103], 0.5, v[110:111] op_sel_hi:[1,0,1]
	v_cvt_pk_bf16_f32 v108, v116, v117
	v_lshlrev_b32_e32 v116, 16, v181
	v_and_b32_e32 v117, 0xffff0000, v181
	v_pk_fma_f32 v[112:113], v[98:99], 0.5, v[114:115] op_sel_hi:[1,0,1]
	v_mul_f32_e32 v98, v103, v103
	v_mul_f32_e32 v99, v105, v105
	v_pk_fma_f32 v[110:111], v[100:101], 0.5, v[116:117] op_sel_hi:[1,0,1]
	v_fmac_f32_e32 v98, v102, v102
	v_fmac_f32_e32 v99, v104, v104
	v_add_f32_e32 v98, v98, v99
	v_mul_f32_e32 v99, v113, v113
	v_mul_f32_e32 v100, v111, v111
	v_fmac_f32_e32 v99, v112, v112
	v_fmac_f32_e32 v100, v110, v110
	v_add_f32_e32 v99, v99, v100
	v_add_f32_e32 v98, v98, v99
	v_add_f32_e32 v101, v120, v98
	v_mov_b32_e32 v116, v101
	s_nop 1
	v_permlane16_swap_b32_e32 v116, v101
	v_lshl_add_u64 v[118:119], s[14:15], 0, v[236:237]
	v_lshl_add_u64 v[98:99], s[44:45], 1, v[118:119]
	v_lshl_add_u64 v[114:115], v[98:99], 0, v[202:203]
	v_cvt_pk_bf16_f32 v100, v102, v103
	s_waitcnt lgkmcnt(0)
	v_add_f32_e32 v98, v101, v116
	v_mov_b32_e32 v99, v98
	s_nop 1
	v_permlane32_swap_b32_e32 v99, v98
	v_cvt_pk_bf16_f32 v101, v104, v105
	v_cvt_pk_bf16_f32 v102, v112, v113
	v_cvt_pk_bf16_f32 v103, v110, v111
	global_store_dwordx4 v[114:115], v[106:109], off
	global_store_dwordx4 v[114:115], v[100:103], off offset:256
	s_and_saveexec_b64 s[46:47], s[4:5]
	s_cbranch_execz .LBB0_258
	v_lshl_add_u64 v[100:101], v[234:235], 2, s[16:17]
	s_waitcnt lgkmcnt(0)
	v_add_f32_e32 v98, v98, v99
	global_atomic_add_f32 v[100:101], v98, off
.LBB0_258:
	s_or_b64 exec, exec, s[46:47]
	v_lshlrev_b32_e32 v98, 16, v174
	s_waitcnt lgkmcnt(0)
	v_and_b32_e32 v99, 0xffff0000, v174
	v_lshlrev_b32_e32 v100, 16, v175
	v_and_b32_e32 v101, 0xffff0000, v175
	v_lshlrev_b32_e32 v102, 16, v176
	v_and_b32_e32 v103, 0xffff0000, v176
	v_pk_fma_f32 v[94:95], v[94:95], 0.5, v[98:99] op_sel_hi:[1,0,1]
	v_pk_fma_f32 v[96:97], v[96:97], 0.5, v[100:101] op_sel_hi:[1,0,1]
	v_pk_fma_f32 v[100:101], v[90:91], 0.5, v[102:103] op_sel_hi:[1,0,1]
	v_cvt_pk_bf16_f32 v90, v94, v95
	v_mul_f32_e32 v95, v95, v95
	v_lshlrev_b32_e32 v104, 16, v177
	v_and_b32_e32 v105, 0xffff0000, v177
	v_fmac_f32_e32 v95, v94, v94
	v_mul_f32_e32 v94, v97, v97
	v_pk_fma_f32 v[98:99], v[92:93], 0.5, v[104:105] op_sel_hi:[1,0,1]
	v_fmac_f32_e32 v94, v96, v96
	v_cvt_pk_bf16_f32 v91, v96, v97
	v_add_f32_e32 v94, v95, v94
	v_mul_f32_e32 v95, v101, v101
	v_mul_f32_e32 v96, v99, v99
	v_fmac_f32_e32 v95, v100, v100
	v_fmac_f32_e32 v96, v98, v98
	v_add_f32_e32 v95, v95, v96
	v_add_f32_e32 v104, v94, v95
	v_lshlrev_b32_e32 v94, 16, v170
	v_and_b32_e32 v95, 0xffff0000, v170
	v_lshlrev_b32_e32 v96, 16, v171
	v_and_b32_e32 v97, 0xffff0000, v171
	v_cvt_pk_bf16_f32 v93, v98, v99
	v_lshlrev_b32_e32 v98, 16, v172
	v_and_b32_e32 v99, 0xffff0000, v172
	v_pk_fma_f32 v[88:89], v[88:89], 0.5, v[96:97] op_sel_hi:[1,0,1]
	v_pk_fma_f32 v[86:87], v[86:87], 0.5, v[94:95] op_sel_hi:[1,0,1]
	v_cvt_pk_bf16_f32 v92, v100, v101
	v_lshlrev_b32_e32 v100, 16, v173
	v_and_b32_e32 v101, 0xffff0000, v173
	v_pk_fma_f32 v[96:97], v[82:83], 0.5, v[98:99] op_sel_hi:[1,0,1]
	v_mul_f32_e32 v82, v87, v87
	v_mul_f32_e32 v83, v89, v89
	v_pk_fma_f32 v[94:95], v[84:85], 0.5, v[100:101] op_sel_hi:[1,0,1]
	v_fmac_f32_e32 v82, v86, v86
	v_fmac_f32_e32 v83, v88, v88
	v_add_f32_e32 v82, v82, v83
	v_mul_f32_e32 v83, v97, v97
	v_mul_f32_e32 v84, v95, v95
	v_fmac_f32_e32 v83, v96, v96
	v_fmac_f32_e32 v84, v94, v94
	v_add_f32_e32 v83, v83, v84
	v_add_f32_e32 v82, v82, v83
	v_add_f32_e32 v85, v104, v82
	v_mov_b32_e32 v100, v85
	s_nop 1
	v_permlane16_swap_b32_e32 v100, v85
	v_lshl_add_u64 v[102:103], s[14:15], 0, v[232:233]
	v_lshl_add_u64 v[82:83], s[44:45], 1, v[102:103]
	v_lshl_add_u64 v[98:99], v[82:83], 0, v[202:203]
	v_cvt_pk_bf16_f32 v84, v86, v87
	s_waitcnt lgkmcnt(0)
	v_add_f32_e32 v82, v85, v100
	v_mov_b32_e32 v83, v82
	s_nop 1
	v_permlane32_swap_b32_e32 v83, v82
	v_cvt_pk_bf16_f32 v85, v88, v89
	v_cvt_pk_bf16_f32 v86, v96, v97
	v_cvt_pk_bf16_f32 v87, v94, v95
	global_store_dwordx4 v[98:99], v[90:93], off
	global_store_dwordx4 v[98:99], v[84:87], off offset:256
	s_and_saveexec_b64 s[46:47], s[4:5]
	s_cbranch_execz .LBB0_260
	v_lshl_add_u64 v[84:85], v[230:231], 2, s[16:17]
	s_waitcnt lgkmcnt(0)
	v_add_f32_e32 v82, v82, v83
	global_atomic_add_f32 v[84:85], v82, off
.LBB0_260:
	s_or_b64 exec, exec, s[46:47]
	v_lshlrev_b32_e32 v82, 16, v166
	s_waitcnt lgkmcnt(0)
	v_and_b32_e32 v83, 0xffff0000, v166
	v_lshlrev_b32_e32 v84, 16, v167
	v_and_b32_e32 v85, 0xffff0000, v167
	v_lshlrev_b32_e32 v86, 16, v168
	v_and_b32_e32 v87, 0xffff0000, v168
	v_pk_fma_f32 v[78:79], v[78:79], 0.5, v[82:83] op_sel_hi:[1,0,1]
	v_pk_fma_f32 v[80:81], v[80:81], 0.5, v[84:85] op_sel_hi:[1,0,1]
	v_pk_fma_f32 v[84:85], v[74:75], 0.5, v[86:87] op_sel_hi:[1,0,1]
	v_cvt_pk_bf16_f32 v74, v78, v79
	v_mul_f32_e32 v79, v79, v79
	v_lshlrev_b32_e32 v88, 16, v169
	v_and_b32_e32 v89, 0xffff0000, v169
	v_fmac_f32_e32 v79, v78, v78
	v_mul_f32_e32 v78, v81, v81
	v_pk_fma_f32 v[82:83], v[76:77], 0.5, v[88:89] op_sel_hi:[1,0,1]
	v_fmac_f32_e32 v78, v80, v80
	v_cvt_pk_bf16_f32 v75, v80, v81
	v_add_f32_e32 v78, v79, v78
	v_mul_f32_e32 v79, v85, v85
	v_mul_f32_e32 v80, v83, v83
	v_fmac_f32_e32 v79, v84, v84
	v_fmac_f32_e32 v80, v82, v82
	v_add_f32_e32 v79, v79, v80
	v_add_f32_e32 v88, v78, v79
	v_lshlrev_b32_e32 v78, 16, v162
	v_and_b32_e32 v79, 0xffff0000, v162
	v_lshlrev_b32_e32 v80, 16, v163
	v_and_b32_e32 v81, 0xffff0000, v163
	v_cvt_pk_bf16_f32 v77, v82, v83
	v_lshlrev_b32_e32 v82, 16, v164
	v_and_b32_e32 v83, 0xffff0000, v164
	v_pk_fma_f32 v[72:73], v[72:73], 0.5, v[80:81] op_sel_hi:[1,0,1]
	v_pk_fma_f32 v[70:71], v[70:71], 0.5, v[78:79] op_sel_hi:[1,0,1]
	v_cvt_pk_bf16_f32 v76, v84, v85
	v_lshlrev_b32_e32 v84, 16, v165
	v_and_b32_e32 v85, 0xffff0000, v165
	v_pk_fma_f32 v[80:81], v[66:67], 0.5, v[82:83] op_sel_hi:[1,0,1]
	v_mul_f32_e32 v66, v71, v71
	v_mul_f32_e32 v67, v73, v73
	v_pk_fma_f32 v[78:79], v[68:69], 0.5, v[84:85] op_sel_hi:[1,0,1]
	v_fmac_f32_e32 v66, v70, v70
	v_fmac_f32_e32 v67, v72, v72
	v_add_f32_e32 v66, v66, v67
	v_mul_f32_e32 v67, v81, v81
	v_mul_f32_e32 v68, v79, v79
	v_fmac_f32_e32 v67, v80, v80
	v_fmac_f32_e32 v68, v78, v78
	v_add_f32_e32 v67, v67, v68
	v_add_f32_e32 v66, v66, v67
	v_add_f32_e32 v69, v88, v66
	v_mov_b32_e32 v84, v69
	s_nop 1
	v_permlane16_swap_b32_e32 v84, v69
	v_lshl_add_u64 v[86:87], s[14:15], 0, v[228:229]
	v_lshl_add_u64 v[66:67], s[44:45], 1, v[86:87]
	v_lshl_add_u64 v[82:83], v[66:67], 0, v[202:203]
	v_cvt_pk_bf16_f32 v68, v70, v71
	s_waitcnt lgkmcnt(0)
	v_add_f32_e32 v66, v69, v84
	v_mov_b32_e32 v67, v66
	s_nop 1
	v_permlane32_swap_b32_e32 v67, v66
	v_cvt_pk_bf16_f32 v69, v72, v73
	v_cvt_pk_bf16_f32 v70, v80, v81
	v_cvt_pk_bf16_f32 v71, v78, v79
	global_store_dwordx4 v[82:83], v[74:77], off
	global_store_dwordx4 v[82:83], v[68:71], off offset:256
	s_and_saveexec_b64 s[46:47], s[4:5]
	s_cbranch_execz .LBB0_262
	v_lshl_add_u64 v[68:69], v[226:227], 2, s[16:17]
	s_waitcnt lgkmcnt(0)
	v_add_f32_e32 v66, v66, v67
	global_atomic_add_f32 v[68:69], v66, off
.LBB0_262:
	s_or_b64 exec, exec, s[46:47]
	v_lshlrev_b32_e32 v66, 16, v158
	s_waitcnt lgkmcnt(0)
	v_and_b32_e32 v67, 0xffff0000, v158
	v_lshlrev_b32_e32 v68, 16, v159
	v_and_b32_e32 v69, 0xffff0000, v159
	v_lshlrev_b32_e32 v70, 16, v160
	v_and_b32_e32 v71, 0xffff0000, v160
	v_pk_fma_f32 v[62:63], v[62:63], 0.5, v[66:67] op_sel_hi:[1,0,1]
	v_pk_fma_f32 v[64:65], v[64:65], 0.5, v[68:69] op_sel_hi:[1,0,1]
	v_pk_fma_f32 v[68:69], v[58:59], 0.5, v[70:71] op_sel_hi:[1,0,1]
	v_cvt_pk_bf16_f32 v58, v62, v63
	v_mul_f32_e32 v63, v63, v63
	v_lshlrev_b32_e32 v72, 16, v161
	v_and_b32_e32 v73, 0xffff0000, v161
	v_fmac_f32_e32 v63, v62, v62
	v_mul_f32_e32 v62, v65, v65
	v_pk_fma_f32 v[66:67], v[60:61], 0.5, v[72:73] op_sel_hi:[1,0,1]
	v_fmac_f32_e32 v62, v64, v64
	v_cvt_pk_bf16_f32 v59, v64, v65
	v_add_f32_e32 v62, v63, v62
	v_mul_f32_e32 v63, v69, v69
	v_mul_f32_e32 v64, v67, v67
	v_fmac_f32_e32 v63, v68, v68
	v_fmac_f32_e32 v64, v66, v66
	v_add_f32_e32 v63, v63, v64
	v_add_f32_e32 v72, v62, v63
	v_lshlrev_b32_e32 v62, 16, v146
	v_and_b32_e32 v63, 0xffff0000, v146
	v_lshlrev_b32_e32 v64, 16, v147
	v_and_b32_e32 v65, 0xffff0000, v147
	v_cvt_pk_bf16_f32 v61, v66, v67
	v_lshlrev_b32_e32 v66, 16, v148
	v_and_b32_e32 v67, 0xffff0000, v148
	v_pk_fma_f32 v[56:57], v[56:57], 0.5, v[64:65] op_sel_hi:[1,0,1]
	v_pk_fma_f32 v[54:55], v[54:55], 0.5, v[62:63] op_sel_hi:[1,0,1]
	v_cvt_pk_bf16_f32 v60, v68, v69
	v_lshlrev_b32_e32 v68, 16, v149
	v_and_b32_e32 v69, 0xffff0000, v149
	v_pk_fma_f32 v[64:65], v[50:51], 0.5, v[66:67] op_sel_hi:[1,0,1]
	v_mul_f32_e32 v50, v55, v55
	v_mul_f32_e32 v51, v57, v57
	v_pk_fma_f32 v[62:63], v[52:53], 0.5, v[68:69] op_sel_hi:[1,0,1]
	v_fmac_f32_e32 v50, v54, v54
	v_fmac_f32_e32 v51, v56, v56
	v_add_f32_e32 v50, v50, v51
	v_mul_f32_e32 v51, v65, v65
	v_mul_f32_e32 v52, v63, v63
	v_fmac_f32_e32 v51, v64, v64
	v_fmac_f32_e32 v52, v62, v62
	v_add_f32_e32 v51, v51, v52
	v_add_f32_e32 v50, v50, v51
	v_add_f32_e32 v53, v72, v50
	v_mov_b32_e32 v68, v53
	s_nop 1
	v_permlane16_swap_b32_e32 v68, v53
	v_lshl_add_u64 v[70:71], s[14:15], 0, v[224:225]
	v_lshl_add_u64 v[50:51], s[44:45], 1, v[70:71]
	v_lshl_add_u64 v[66:67], v[50:51], 0, v[202:203]
	v_cvt_pk_bf16_f32 v52, v54, v55
	s_waitcnt lgkmcnt(0)
	v_add_f32_e32 v50, v53, v68
	v_mov_b32_e32 v51, v50
	s_nop 1
	v_permlane32_swap_b32_e32 v51, v50
	v_cvt_pk_bf16_f32 v53, v56, v57
	v_cvt_pk_bf16_f32 v54, v64, v65
	v_cvt_pk_bf16_f32 v55, v62, v63
	global_store_dwordx4 v[66:67], v[58:61], off
	global_store_dwordx4 v[66:67], v[52:55], off offset:256
	s_and_saveexec_b64 s[46:47], s[4:5]
	s_cbranch_execz .LBB0_264
	v_lshl_add_u64 v[52:53], v[222:223], 2, s[16:17]
	s_waitcnt lgkmcnt(0)
	v_add_f32_e32 v50, v50, v51
	global_atomic_add_f32 v[52:53], v50, off
.LBB0_264:
	s_or_b64 exec, exec, s[46:47]
	v_lshlrev_b32_e32 v50, 16, v142
	s_waitcnt lgkmcnt(0)
	v_and_b32_e32 v51, 0xffff0000, v142
	v_lshlrev_b32_e32 v52, 16, v143
	v_and_b32_e32 v53, 0xffff0000, v143
	v_lshlrev_b32_e32 v54, 16, v144
	v_and_b32_e32 v55, 0xffff0000, v144
	v_pk_fma_f32 v[46:47], v[46:47], 0.5, v[50:51] op_sel_hi:[1,0,1]
	v_pk_fma_f32 v[48:49], v[48:49], 0.5, v[52:53] op_sel_hi:[1,0,1]
	v_pk_fma_f32 v[52:53], v[42:43], 0.5, v[54:55] op_sel_hi:[1,0,1]
	v_cvt_pk_bf16_f32 v42, v46, v47
	v_mul_f32_e32 v47, v47, v47
	v_lshlrev_b32_e32 v56, 16, v145
	v_and_b32_e32 v57, 0xffff0000, v145
	v_fmac_f32_e32 v47, v46, v46
	v_mul_f32_e32 v46, v49, v49
	v_pk_fma_f32 v[50:51], v[44:45], 0.5, v[56:57] op_sel_hi:[1,0,1]
	v_fmac_f32_e32 v46, v48, v48
	v_cvt_pk_bf16_f32 v43, v48, v49
	v_add_f32_e32 v46, v47, v46
	v_mul_f32_e32 v47, v53, v53
	v_mul_f32_e32 v48, v51, v51
	v_fmac_f32_e32 v47, v52, v52
	v_fmac_f32_e32 v48, v50, v50
	v_add_f32_e32 v47, v47, v48
	v_add_f32_e32 v56, v46, v47
	v_lshlrev_b32_e32 v46, 16, v138
	v_and_b32_e32 v47, 0xffff0000, v138
	v_lshlrev_b32_e32 v48, 16, v139
	v_and_b32_e32 v49, 0xffff0000, v139
	v_cvt_pk_bf16_f32 v45, v50, v51
	v_lshlrev_b32_e32 v50, 16, v140
	v_and_b32_e32 v51, 0xffff0000, v140
	v_pk_fma_f32 v[40:41], v[40:41], 0.5, v[48:49] op_sel_hi:[1,0,1]
	v_pk_fma_f32 v[38:39], v[38:39], 0.5, v[46:47] op_sel_hi:[1,0,1]
	v_cvt_pk_bf16_f32 v44, v52, v53
	v_lshlrev_b32_e32 v52, 16, v141
	v_and_b32_e32 v53, 0xffff0000, v141
	v_pk_fma_f32 v[48:49], v[34:35], 0.5, v[50:51] op_sel_hi:[1,0,1]
	v_mul_f32_e32 v34, v39, v39
	v_mul_f32_e32 v35, v41, v41
	v_pk_fma_f32 v[46:47], v[36:37], 0.5, v[52:53] op_sel_hi:[1,0,1]
	v_fmac_f32_e32 v34, v38, v38
	v_fmac_f32_e32 v35, v40, v40
	v_add_f32_e32 v34, v34, v35
	v_mul_f32_e32 v35, v49, v49
	v_mul_f32_e32 v36, v47, v47
	v_fmac_f32_e32 v35, v48, v48
	v_fmac_f32_e32 v36, v46, v46
	v_add_f32_e32 v35, v35, v36
	v_add_f32_e32 v34, v34, v35
	v_add_f32_e32 v37, v56, v34
	v_mov_b32_e32 v52, v37
	s_nop 1
	v_permlane16_swap_b32_e32 v52, v37
	v_lshl_add_u64 v[54:55], s[14:15], 0, v[220:221]
	v_lshl_add_u64 v[34:35], s[44:45], 1, v[54:55]
	v_lshl_add_u64 v[50:51], v[34:35], 0, v[202:203]
	v_cvt_pk_bf16_f32 v36, v38, v39
	s_waitcnt lgkmcnt(0)
	v_add_f32_e32 v34, v37, v52
	v_mov_b32_e32 v35, v34
	s_nop 1
	v_permlane32_swap_b32_e32 v35, v34
	v_cvt_pk_bf16_f32 v37, v40, v41
	v_cvt_pk_bf16_f32 v38, v48, v49
	v_cvt_pk_bf16_f32 v39, v46, v47
	global_store_dwordx4 v[50:51], v[42:45], off
	global_store_dwordx4 v[50:51], v[36:39], off offset:256
	s_and_saveexec_b64 s[46:47], s[4:5]
	s_cbranch_execz .LBB0_266
	v_lshl_add_u64 v[36:37], v[218:219], 2, s[16:17]
	s_waitcnt lgkmcnt(0)
	v_add_f32_e32 v34, v34, v35
	global_atomic_add_f32 v[36:37], v34, off
.LBB0_266:
	s_or_b64 exec, exec, s[46:47]
	v_lshlrev_b32_e32 v34, 16, v130
	s_waitcnt lgkmcnt(0)
	v_and_b32_e32 v35, 0xffff0000, v130
	v_lshlrev_b32_e32 v36, 16, v131
	v_and_b32_e32 v37, 0xffff0000, v131
	v_lshlrev_b32_e32 v38, 16, v132
	v_and_b32_e32 v39, 0xffff0000, v132
	v_pk_fma_f32 v[30:31], v[30:31], 0.5, v[34:35] op_sel_hi:[1,0,1]
	v_pk_fma_f32 v[32:33], v[32:33], 0.5, v[36:37] op_sel_hi:[1,0,1]
	v_pk_fma_f32 v[36:37], v[26:27], 0.5, v[38:39] op_sel_hi:[1,0,1]
	v_cvt_pk_bf16_f32 v26, v30, v31
	v_mul_f32_e32 v31, v31, v31
	v_lshlrev_b32_e32 v40, 16, v133
	v_and_b32_e32 v41, 0xffff0000, v133
	v_fmac_f32_e32 v31, v30, v30
	v_mul_f32_e32 v30, v33, v33
	v_pk_fma_f32 v[34:35], v[28:29], 0.5, v[40:41] op_sel_hi:[1,0,1]
	v_fmac_f32_e32 v30, v32, v32
	v_cvt_pk_bf16_f32 v27, v32, v33
	v_add_f32_e32 v30, v31, v30
	v_mul_f32_e32 v31, v37, v37
	v_mul_f32_e32 v32, v35, v35
	v_fmac_f32_e32 v31, v36, v36
	v_fmac_f32_e32 v32, v34, v34
	v_add_f32_e32 v31, v31, v32
	v_add_f32_e32 v40, v30, v31
	v_lshlrev_b32_e32 v30, 16, v122
	v_and_b32_e32 v31, 0xffff0000, v122
	v_lshlrev_b32_e32 v32, 16, v123
	v_and_b32_e32 v33, 0xffff0000, v123
	v_cvt_pk_bf16_f32 v29, v34, v35
	v_lshlrev_b32_e32 v34, 16, v124
	v_and_b32_e32 v35, 0xffff0000, v124
	v_pk_fma_f32 v[24:25], v[24:25], 0.5, v[32:33] op_sel_hi:[1,0,1]
	v_pk_fma_f32 v[22:23], v[22:23], 0.5, v[30:31] op_sel_hi:[1,0,1]
	v_cvt_pk_bf16_f32 v28, v36, v37
	v_lshlrev_b32_e32 v36, 16, v125
	v_and_b32_e32 v37, 0xffff0000, v125
	v_pk_fma_f32 v[32:33], v[18:19], 0.5, v[34:35] op_sel_hi:[1,0,1]
	v_mul_f32_e32 v18, v23, v23
	v_mul_f32_e32 v19, v25, v25
	v_pk_fma_f32 v[30:31], v[20:21], 0.5, v[36:37] op_sel_hi:[1,0,1]
	v_fmac_f32_e32 v18, v22, v22
	v_fmac_f32_e32 v19, v24, v24
	v_add_f32_e32 v18, v18, v19
	v_mul_f32_e32 v19, v33, v33
	v_mul_f32_e32 v20, v31, v31
	v_fmac_f32_e32 v19, v32, v32
	v_fmac_f32_e32 v20, v30, v30
	v_add_f32_e32 v19, v19, v20
	v_add_f32_e32 v18, v18, v19
	v_add_f32_e32 v21, v40, v18
	v_mov_b32_e32 v36, v21
	s_nop 1
	v_permlane16_swap_b32_e32 v36, v21
	v_lshl_add_u64 v[38:39], s[14:15], 0, v[216:217]
	v_lshl_add_u64 v[18:19], s[44:45], 1, v[38:39]
	v_lshl_add_u64 v[34:35], v[18:19], 0, v[202:203]
	v_cvt_pk_bf16_f32 v20, v22, v23
	s_waitcnt lgkmcnt(0)
	v_add_f32_e32 v18, v21, v36
	v_mov_b32_e32 v19, v18
	s_nop 1
	v_permlane32_swap_b32_e32 v19, v18
	v_cvt_pk_bf16_f32 v21, v24, v25
	v_cvt_pk_bf16_f32 v22, v32, v33
	v_cvt_pk_bf16_f32 v23, v30, v31
	global_store_dwordx4 v[34:35], v[26:29], off
	global_store_dwordx4 v[34:35], v[20:23], off offset:256
	s_and_saveexec_b64 s[46:47], s[4:5]
	s_cbranch_execz .LBB0_268
	v_lshl_add_u64 v[20:21], v[212:213], 2, s[16:17]
	s_waitcnt lgkmcnt(0)
	v_add_f32_e32 v18, v18, v19
	global_atomic_add_f32 v[20:21], v18, off
.LBB0_268:
	s_or_b64 exec, exec, s[46:47]
	v_lshlrev_b32_e32 v18, 16, v134
	s_waitcnt lgkmcnt(0)
	v_and_b32_e32 v19, 0xffff0000, v134
	v_lshlrev_b32_e32 v20, 16, v135
	v_and_b32_e32 v21, 0xffff0000, v135
	v_lshlrev_b32_e32 v22, 16, v136
	v_and_b32_e32 v23, 0xffff0000, v136
	v_pk_fma_f32 v[14:15], v[14:15], 0.5, v[18:19] op_sel_hi:[1,0,1]
	v_pk_fma_f32 v[16:17], v[16:17], 0.5, v[20:21] op_sel_hi:[1,0,1]
	v_pk_fma_f32 v[20:21], v[10:11], 0.5, v[22:23] op_sel_hi:[1,0,1]
	v_cvt_pk_bf16_f32 v10, v14, v15
	v_mul_f32_e32 v15, v15, v15
	v_lshlrev_b32_e32 v24, 16, v137
	v_and_b32_e32 v25, 0xffff0000, v137
	v_fmac_f32_e32 v15, v14, v14
	v_mul_f32_e32 v14, v17, v17
	v_pk_fma_f32 v[18:19], v[12:13], 0.5, v[24:25] op_sel_hi:[1,0,1]
	v_fmac_f32_e32 v14, v16, v16
	v_cvt_pk_bf16_f32 v11, v16, v17
	v_add_f32_e32 v14, v15, v14
	v_mul_f32_e32 v15, v21, v21
	v_mul_f32_e32 v16, v19, v19
	v_fmac_f32_e32 v15, v20, v20
	v_fmac_f32_e32 v16, v18, v18
	v_add_f32_e32 v15, v15, v16
	v_add_f32_e32 v24, v14, v15
	v_lshlrev_b32_e32 v14, 16, v126
	v_and_b32_e32 v15, 0xffff0000, v126
	v_lshlrev_b32_e32 v16, 16, v127
	v_and_b32_e32 v17, 0xffff0000, v127
	v_cvt_pk_bf16_f32 v13, v18, v19
	v_lshlrev_b32_e32 v18, 16, v128
	v_and_b32_e32 v19, 0xffff0000, v128
	v_pk_fma_f32 v[8:9], v[8:9], 0.5, v[16:17] op_sel_hi:[1,0,1]
	v_pk_fma_f32 v[6:7], v[6:7], 0.5, v[14:15] op_sel_hi:[1,0,1]
	v_cvt_pk_bf16_f32 v12, v20, v21
	v_lshlrev_b32_e32 v20, 16, v129
	v_and_b32_e32 v21, 0xffff0000, v129
	v_pk_fma_f32 v[16:17], v[2:3], 0.5, v[18:19] op_sel_hi:[1,0,1]
	v_mul_f32_e32 v2, v7, v7
	v_mul_f32_e32 v3, v9, v9
	v_pk_fma_f32 v[14:15], v[4:5], 0.5, v[20:21] op_sel_hi:[1,0,1]
	v_fmac_f32_e32 v2, v6, v6
	v_fmac_f32_e32 v3, v8, v8
	v_add_f32_e32 v2, v2, v3
	v_mul_f32_e32 v3, v17, v17
	v_mul_f32_e32 v4, v15, v15
	v_fmac_f32_e32 v3, v16, v16
	v_fmac_f32_e32 v4, v14, v14
	v_add_f32_e32 v3, v3, v4
	v_add_f32_e32 v2, v2, v3
	v_add_f32_e32 v5, v24, v2
	v_mov_b32_e32 v20, v5
	s_nop 1
	v_permlane16_swap_b32_e32 v20, v5
	v_lshl_add_u64 v[22:23], s[14:15], 0, v[214:215]
	v_lshl_add_u64 v[2:3], s[44:45], 1, v[22:23]
	v_lshl_add_u64 v[18:19], v[2:3], 0, v[202:203]
	v_cvt_pk_bf16_f32 v4, v6, v7
	s_waitcnt lgkmcnt(0)
	v_add_f32_e32 v2, v5, v20
	v_mov_b32_e32 v3, v2
	s_nop 1
	v_permlane32_swap_b32_e32 v3, v2
	v_cvt_pk_bf16_f32 v5, v8, v9
	v_cvt_pk_bf16_f32 v6, v16, v17
	v_cvt_pk_bf16_f32 v7, v14, v15
	global_store_dwordx4 v[18:19], v[10:13], off
	global_store_dwordx4 v[18:19], v[4:7], off offset:256
	s_and_saveexec_b64 s[44:45], s[4:5]
	s_cbranch_execz .LBB0_270
	v_lshl_add_u64 v[4:5], v[210:211], 2, s[16:17]
	s_waitcnt lgkmcnt(0)
	v_add_f32_e32 v2, v2, v3
	global_atomic_add_f32 v[4:5], v2, off

.LBB0_466:
	v_mov_b32_e32 v2, v172
	s_nop 1
	v_permlane32_swap_b32_e32 v2, v172
	v_lshl_add_u64 v[4:5], s[52:53], 0, v[122:123]
	v_mov_b32_e32 v119, v3
	v_lshl_add_u64 v[4:5], s[16:17], 1, v[4:5]
	s_sub_i32 s16, s92, s2
	s_waitcnt lgkmcnt(0)
	v_add_f32_e32 v2, v172, v2
	v_div_scale_f32 v6, s[26:27], v2, v2, 1.0
	v_rcp_f32_e32 v7, v6
	v_div_scale_f32 v8, vcc, 1.0, v2, 1.0
	s_ashr_i32 s17, s16, 31
	v_fma_f32 v9, -v6, v7, 1.0
	v_fmac_f32_e32 v7, v9, v7
	v_mul_f32_e32 v9, v8, v7
	v_fma_f32 v10, -v6, v9, v8
	v_fmac_f32_e32 v9, v10, v7
	v_fma_f32 v6, -v6, v9, v8
	v_div_fmas_f32 v6, v6, v7, v9
	v_div_fixup_f32 v2, v6, v2, 1.0
	v_lshl_add_u64 v[8:9], v[4:5], 0, v[118:119]
	v_pk_mul_f32 v[4:5], v[34:35], v[2:3] op_sel_hi:[1,0]
	v_pk_mul_f32 v[6:7], v[36:37], v[2:3] op_sel_hi:[1,0]
	s_abs_i32 s16, s16
	v_cvt_pk_bf16_f32 v4, v4, v5
	v_cvt_pk_bf16_f32 v5, v6, v7
	v_pk_mul_f32 v[6:7], v[38:39], v[2:3] op_sel_hi:[1,0]
	v_pk_mul_f32 v[10:11], v[40:41], v[2:3] op_sel_hi:[1,0]
	s_mul_hi_u32 s23, s16, s54
	v_cvt_pk_bf16_f32 v6, v6, v7
	v_cvt_pk_bf16_f32 v7, v10, v11
	s_mul_i32 s23, s23, s31
	v_permlane32_swap_b32_e32 v4, v6
	v_permlane32_swap_b32_e32 v5, v7
	s_sub_i32 s16, s16, s23
	global_store_dwordx4 v[8:9], v[4:7], off
	s_sub_i32 s23, s16, s31
	v_pk_mul_f32 v[10:11], v[48:49], v[2:3] op_sel_hi:[1,0]
	v_pk_mul_f32 v[4:5], v[42:43], v[2:3] op_sel_hi:[1,0]
	v_pk_mul_f32 v[6:7], v[44:45], v[2:3] op_sel_hi:[1,0]
	v_cvt_pk_bf16_f32 v4, v4, v5
	v_cvt_pk_bf16_f32 v5, v6, v7
	v_pk_mul_f32 v[6:7], v[46:47], v[2:3] op_sel_hi:[1,0]
	s_cmp_ge_u32 s16, s31
	v_cvt_pk_bf16_f32 v6, v6, v7
	v_cvt_pk_bf16_f32 v7, v10, v11
	s_cselect_b32 s16, s23, s16
	v_permlane32_swap_b32_e32 v4, v6
	v_permlane32_swap_b32_e32 v5, v7
	s_sub_i32 s23, s16, s31
	global_store_dwordx4 v[8:9], v[4:7], off offset:32
	s_cmp_ge_u32 s16, s31
	v_pk_mul_f32 v[10:11], v[24:25], v[2:3] op_sel_hi:[1,0]
	v_pk_mul_f32 v[4:5], v[18:19], v[2:3] op_sel_hi:[1,0]
	v_pk_mul_f32 v[6:7], v[20:21], v[2:3] op_sel_hi:[1,0]
	v_cvt_pk_bf16_f32 v4, v4, v5
	v_cvt_pk_bf16_f32 v5, v6, v7
	v_pk_mul_f32 v[6:7], v[22:23], v[2:3] op_sel_hi:[1,0]
	s_cselect_b32 s16, s23, s16
	v_cvt_pk_bf16_f32 v6, v6, v7
	v_cvt_pk_bf16_f32 v7, v10, v11
	s_xor_b32 s16, s16, s17
	v_permlane32_swap_b32_e32 v4, v6
	v_permlane32_swap_b32_e32 v5, v7
	s_sub_i32 s16, s17, s16
	global_store_dwordx4 v[8:9], v[4:7], off offset:64
	s_add_i32 s16, s92, s16
	v_pk_mul_f32 v[10:11], v[32:33], v[2:3] op_sel_hi:[1,0]
	v_pk_mul_f32 v[4:5], v[26:27], v[2:3] op_sel_hi:[1,0]
	v_pk_mul_f32 v[6:7], v[28:29], v[2:3] op_sel_hi:[1,0]
	v_cvt_pk_bf16_f32 v4, v4, v5
	v_cvt_pk_bf16_f32 v5, v6, v7
	v_pk_mul_f32 v[6:7], v[30:31], v[2:3] op_sel_hi:[1,0]
	s_lshl_b32 s23, s16, 3
	v_cvt_pk_bf16_f32 v6, v6, v7
	v_cvt_pk_bf16_f32 v7, v10, v11
	s_add_i32 s23, s23, s3
	v_permlane32_swap_b32_e32 v4, v6
	v_permlane32_swap_b32_e32 v5, v7
	s_cmpk_lt_i32 s23, 0xed0
	global_store_dwordx4 v[8:9], v[4:7], off offset:96
	s_barrier
	s_cbranch_scc0 .LBB0_434
	s_cmpk_gt_i32 s23, 0x83f
	s_mov_b64 s[16:17], -1
	s_cbranch_scc0 .LBB0_532
	s_cmpk_gt_u32 s23, 0xc5f
	s_cbranch_scc0 .LBB0_522
	s_cmpk_gt_u32 s23, 0xcdf
	s_cbranch_scc0 .LBB0_519
	s_cmpk_gt_u32 s23, 0xd5f
	s_cbranch_scc0 .LBB0_516
	s_cmpk_gt_u32 s23, 0xd9f
	s_cbranch_scc0 .LBB0_501
	s_cmpk_gt_u32 s23, 0xddf
	s_cbranch_scc0 .LBB0_490
	s_cmpk_gt_u32 s23, 0xe3f
	s_cbranch_scc0 .LBB0_487
	s_add_i32 s24, s23, 0xffc0
	s_and_b32 s60, s24, 0xff
	s_mulk_i32 s60, 0xab
	s_bfe_u32 s66, s60, 0x5000b
	s_mul_i32 s60, s66, 12
	s_sub_i32 s24, s24, s60
	s_and_b32 s67, s24, 0xff
	s_lshl_b32 s24, s67, 7
	s_mov_b64 s[16:17], s[0:1]
	s_mov_b64 s[26:27], s[0:1]
	s_mov_b64 s[62:63], s[0:1]
	s_cmp_gt_u32 s67, 7
	s_mov_b64 s[64:65], -1
	s_cbranch_scc0 .LBB0_476
	s_add_i32 s60, s24, 0xfffffc00
	s_lshr_b32 s60, s60, 6
	s_and_b32 s60, s60, 0x3fffffc
	v_or_b32_e32 v2, s60, v115
	s_movk_i32 s60, 0xc0
	v_mul_lo_u32 v2, v2, s60
	s_lshl_b32 s60, s67, 5
	v_and_or_b32 v2, s60, 32, v2
	v_add_u32_e32 v2, 0x80, v2
	s_mov_b64 s[64:65], 0

.LBB0_742:
	v_lshl_add_u32 v238, s48, 8, v243
	s_lshl_b32 s48, s50, 8
	s_ashr_i32 s49, s48, 31
	s_lshl_b64 s[50:51], s[48:49], 1
	v_ashrrev_i32_e32 v239, 31, v238
	v_lshl_add_u64 v[126:127], v[204:205], 0, s[50:51]
	v_lshlrev_b64 v[240:241], 11, v[238:239]
	v_lshl_add_u64 v[122:123], v[126:127], 0, v[240:241]
	global_load_dwordx4 v[190:193], v[122:123], off
	global_load_dwordx4 v[186:189], v[122:123], off offset:256
	v_or_b32_e32 v234, 16, v238
	v_ashrrev_i32_e32 v235, 31, v234
	v_or_b32_e32 v230, 32, v238
	v_lshlrev_b64 v[236:237], 11, v[234:235]
	v_ashrrev_i32_e32 v231, 31, v230
	v_or_b32_e32 v226, 48, v238
	v_lshl_add_u64 v[122:123], v[126:127], 0, v[236:237]
	v_lshlrev_b64 v[232:233], 11, v[230:231]
	v_ashrrev_i32_e32 v227, 31, v226
	v_add_u32_e32 v222, 0x80, v238
	global_load_dwordx4 v[182:185], v[122:123], off
	global_load_dwordx4 v[178:181], v[122:123], off offset:256
	v_lshl_add_u64 v[122:123], v[126:127], 0, v[232:233]
	v_lshlrev_b64 v[228:229], 11, v[226:227]
	v_ashrrev_i32_e32 v223, 31, v222
	v_add_u32_e32 v218, 0x90, v238
	global_load_dwordx4 v[174:177], v[122:123], off
	global_load_dwordx4 v[170:173], v[122:123], off offset:256
	v_lshl_add_u64 v[122:123], v[126:127], 0, v[228:229]
	v_lshlrev_b64 v[224:225], 11, v[222:223]
	v_ashrrev_i32_e32 v219, 31, v218
	v_add_u32_e32 v212, 0xa0, v238
	v_add_u32_e32 v210, 0xb0, v238
	global_load_dwordx4 v[166:169], v[122:123], off
	global_load_dwordx4 v[162:165], v[122:123], off offset:256
	v_lshl_add_u64 v[122:123], v[126:127], 0, v[224:225]
	v_lshlrev_b64 v[220:221], 11, v[218:219]
	v_ashrrev_i32_e32 v213, 31, v212
	v_ashrrev_i32_e32 v211, 31, v210
	global_load_dwordx4 v[158:161], v[122:123], off
	global_load_dwordx4 v[146:149], v[122:123], off offset:256
	v_lshl_add_u64 v[122:123], v[126:127], 0, v[220:221]
	v_lshlrev_b64 v[216:217], 11, v[212:213]
	v_lshlrev_b64 v[214:215], 11, v[210:211]
	global_load_dwordx4 v[142:145], v[122:123], off
	global_load_dwordx4 v[138:141], v[122:123], off offset:256
	v_lshl_add_u64 v[122:123], v[126:127], 0, v[216:217]
	v_lshl_add_u64 v[126:127], v[126:127], 0, v[214:215]
	global_load_dwordx4 v[130:133], v[122:123], off
	s_nop 0
	global_load_dwordx4 v[122:125], v[122:123], off offset:256
	s_nop 0
	global_load_dwordx4 v[134:137], v[126:127], off
	s_nop 0
	global_load_dwordx4 v[126:129], v[126:127], off offset:256
	v_lshl_add_u64 v[240:241], s[12:13], 0, v[240:241]
	v_lshl_add_u64 v[240:241], v[240:241], 0, s[50:51]
	v_lshl_add_u64 v[240:241], v[240:241], 0, v[202:203]
	v_and_b32_e32 v250, 64, v248
	v_xor_b32_e32 v249, 16, v248
	v_add_u32_e32 v250, 64, v250
	v_cmp_lt_i32_e32 vcc, v249, v250
	v_xor_b32_e32 v251, 32, v248
	s_waitcnt vmcnt(0)
	v_lshlrev_b32_e32 v252, 16, v190
	v_and_b32_e32 v253, 0xffff0000, v190
	v_lshlrev_b32_e32 v190, 16, v191
	v_and_b32_e32 v191, 0xffff0000, v191
	v_lshlrev_b32_e32 v254, 16, v192
	v_and_b32_e32 v255, 0xffff0000, v192
	v_lshlrev_b32_e32 v192, 16, v193
	v_and_b32_e32 v193, 0xffff0000, v193
	v_pk_add_f32 v[156:157], v[156:157], v[190:191]
	v_pk_add_f32 v[154:155], v[154:155], v[252:253]
	v_pk_add_f32 v[190:191], v[152:153], v[192:193]
	v_pk_add_f32 v[192:193], v[150:151], v[254:255]
	v_cvt_pk_bf16_f32 v150, v154, v155
	v_cvt_pk_bf16_f32 v151, v156, v157
	v_cvt_pk_bf16_f32 v152, v192, v193
	v_cvt_pk_bf16_f32 v153, v190, v191
	global_store_dwordx4 v[240:241], v[150:153], off
	v_cndmask_b32_e32 v249, v248, v249, vcc
	v_lshlrev_b32_e32 v249, 2, v249
	v_mul_f32_e32 v150, v155, v155
	v_mul_f32_e32 v151, v157, v157
	v_fmac_f32_e32 v150, v154, v154
	v_fmac_f32_e32 v151, v156, v156
	v_add_f32_e32 v150, v150, v151
	v_mul_f32_e32 v151, v193, v193
	v_mul_f32_e32 v152, v191, v191
	v_fmac_f32_e32 v151, v192, v192
	v_fmac_f32_e32 v152, v190, v190
	v_add_f32_e32 v151, v151, v152
	v_add_f32_e32 v190, v150, v151
	v_lshlrev_b32_e32 v150, 16, v186
	v_and_b32_e32 v151, 0xffff0000, v186
	v_lshlrev_b32_e32 v152, 16, v187
	v_and_b32_e32 v153, 0xffff0000, v187
	v_lshlrev_b32_e32 v154, 16, v188
	v_and_b32_e32 v155, 0xffff0000, v188
	v_lshlrev_b32_e32 v156, 16, v189
	v_and_b32_e32 v157, 0xffff0000, v189
	v_pk_add_f32 v[120:121], v[120:121], v[152:153]
	v_pk_add_f32 v[118:119], v[118:119], v[150:151]
	v_pk_add_f32 v[150:151], v[116:117], v[156:157]
	v_pk_add_f32 v[152:153], v[114:115], v[154:155]
	v_cvt_pk_bf16_f32 v114, v118, v119
	v_cvt_pk_bf16_f32 v115, v120, v121
	v_cvt_pk_bf16_f32 v116, v152, v153
	v_cvt_pk_bf16_f32 v117, v150, v151
	global_store_dwordx4 v[240:241], v[114:117], off offset:256
	v_cmp_lt_i32_e32 vcc, v251, v250
	s_nop 0
	v_mul_f32_e32 v114, v119, v119
	v_mul_f32_e32 v115, v121, v121
	v_fmac_f32_e32 v114, v118, v118
	v_fmac_f32_e32 v115, v120, v120
	v_add_f32_e32 v114, v114, v115
	v_mul_f32_e32 v115, v153, v153
	v_mul_f32_e32 v116, v151, v151
	v_fmac_f32_e32 v115, v152, v152
	v_fmac_f32_e32 v116, v150, v150
	v_add_f32_e32 v115, v115, v116
	v_add_f32_e32 v114, v114, v115
	v_add_f32_e32 v114, v190, v114
	v_mov_b32_e32 v115, v114
	s_nop 1
	v_permlane16_swap_b32_e32 v115, v114
	v_cndmask_b32_e32 v250, v248, v251, vcc
	v_lshlrev_b32_e32 v250, 2, v250
	s_waitcnt lgkmcnt(0)
	v_add_f32_e32 v114, v114, v115
	v_mov_b32_e32 v115, v114
	s_nop 1
	v_permlane32_swap_b32_e32 v115, v114
	s_and_saveexec_b64 s[50:51], s[4:5]
	s_cbranch_execz .LBB0_744
	v_lshl_add_u64 v[116:117], v[238:239], 2, s[14:15]
	s_waitcnt lgkmcnt(0)
	v_add_f32_e32 v114, v114, v115
	global_atomic_add_f32 v[116:117], v114, off
.LBB0_744:
	s_or_b64 exec, exec, s[50:51]
	v_lshlrev_b32_e32 v114, 16, v182
	s_waitcnt lgkmcnt(0)
	v_and_b32_e32 v115, 0xffff0000, v182
	v_lshlrev_b32_e32 v116, 16, v183
	v_and_b32_e32 v117, 0xffff0000, v183
	v_lshlrev_b32_e32 v118, 16, v184
	v_and_b32_e32 v119, 0xffff0000, v184
	v_pk_add_f32 v[110:111], v[110:111], v[114:115]
	v_pk_add_f32 v[112:113], v[112:113], v[116:117]
	v_pk_add_f32 v[116:117], v[106:107], v[118:119]
	v_cvt_pk_bf16_f32 v106, v110, v111
	v_mul_f32_e32 v111, v111, v111
	v_lshlrev_b32_e32 v120, 16, v185
	v_and_b32_e32 v121, 0xffff0000, v185
	v_fmac_f32_e32 v111, v110, v110
	v_mul_f32_e32 v110, v113, v113
	v_pk_add_f32 v[114:115], v[108:109], v[120:121]
	v_fmac_f32_e32 v110, v112, v112
	v_cvt_pk_bf16_f32 v107, v112, v113
	v_add_f32_e32 v110, v111, v110
	v_mul_f32_e32 v111, v117, v117
	v_mul_f32_e32 v112, v115, v115
	v_fmac_f32_e32 v111, v116, v116
	v_fmac_f32_e32 v112, v114, v114
	v_add_f32_e32 v111, v111, v112
	v_add_f32_e32 v120, v110, v111
	v_lshlrev_b32_e32 v110, 16, v178
	v_and_b32_e32 v111, 0xffff0000, v178
	v_lshlrev_b32_e32 v112, 16, v179
	v_and_b32_e32 v113, 0xffff0000, v179
	v_cvt_pk_bf16_f32 v109, v114, v115
	v_lshlrev_b32_e32 v114, 16, v180
	v_and_b32_e32 v115, 0xffff0000, v180
	v_pk_add_f32 v[104:105], v[104:105], v[112:113]
	v_pk_add_f32 v[102:103], v[102:103], v[110:111]
	v_cvt_pk_bf16_f32 v108, v116, v117
	v_lshlrev_b32_e32 v116, 16, v181
	v_and_b32_e32 v117, 0xffff0000, v181
	v_pk_add_f32 v[112:113], v[98:99], v[114:115]
	v_mul_f32_e32 v98, v103, v103
	v_mul_f32_e32 v99, v105, v105
	v_pk_add_f32 v[110:111], v[100:101], v[116:117]
	v_fmac_f32_e32 v98, v102, v102
	v_fmac_f32_e32 v99, v104, v104
	v_add_f32_e32 v98, v98, v99
	v_mul_f32_e32 v99, v113, v113
	v_mul_f32_e32 v100, v111, v111
	v_fmac_f32_e32 v99, v112, v112
	v_fmac_f32_e32 v100, v110, v110
	v_add_f32_e32 v99, v99, v100
	v_add_f32_e32 v98, v98, v99
	v_add_f32_e32 v101, v120, v98
	v_mov_b32_e32 v116, v101
	s_nop 1
	v_permlane16_swap_b32_e32 v116, v101
	v_lshl_add_u64 v[118:119], s[12:13], 0, v[236:237]
	v_lshl_add_u64 v[98:99], s[48:49], 1, v[118:119]
	v_lshl_add_u64 v[114:115], v[98:99], 0, v[202:203]
	v_cvt_pk_bf16_f32 v100, v102, v103
	s_waitcnt lgkmcnt(0)
	v_add_f32_e32 v98, v101, v116
	v_mov_b32_e32 v99, v98
	s_nop 1
	v_permlane32_swap_b32_e32 v99, v98
	v_cvt_pk_bf16_f32 v101, v104, v105
	v_cvt_pk_bf16_f32 v102, v112, v113
	v_cvt_pk_bf16_f32 v103, v110, v111
	global_store_dwordx4 v[114:115], v[106:109], off
	global_store_dwordx4 v[114:115], v[100:103], off offset:256
	s_and_saveexec_b64 s[50:51], s[4:5]
	s_cbranch_execz .LBB0_746
	v_lshl_add_u64 v[100:101], v[234:235], 2, s[14:15]
	s_waitcnt lgkmcnt(0)
	v_add_f32_e32 v98, v98, v99
	global_atomic_add_f32 v[100:101], v98, off
.LBB0_746:
	s_or_b64 exec, exec, s[50:51]
	v_lshlrev_b32_e32 v98, 16, v174
	s_waitcnt lgkmcnt(0)
	v_and_b32_e32 v99, 0xffff0000, v174
	v_lshlrev_b32_e32 v100, 16, v175
	v_and_b32_e32 v101, 0xffff0000, v175
	v_lshlrev_b32_e32 v102, 16, v176
	v_and_b32_e32 v103, 0xffff0000, v176
	v_pk_add_f32 v[94:95], v[94:95], v[98:99]
	v_pk_add_f32 v[96:97], v[96:97], v[100:101]
	v_pk_add_f32 v[100:101], v[90:91], v[102:103]
	v_cvt_pk_bf16_f32 v90, v94, v95
	v_mul_f32_e32 v95, v95, v95
	v_lshlrev_b32_e32 v104, 16, v177
	v_and_b32_e32 v105, 0xffff0000, v177
	v_fmac_f32_e32 v95, v94, v94
	v_mul_f32_e32 v94, v97, v97
	v_pk_add_f32 v[98:99], v[92:93], v[104:105]
	v_fmac_f32_e32 v94, v96, v96
	v_cvt_pk_bf16_f32 v91, v96, v97
	v_add_f32_e32 v94, v95, v94
	v_mul_f32_e32 v95, v101, v101
	v_mul_f32_e32 v96, v99, v99
	v_fmac_f32_e32 v95, v100, v100
	v_fmac_f32_e32 v96, v98, v98
	v_add_f32_e32 v95, v95, v96
	v_add_f32_e32 v104, v94, v95
	v_lshlrev_b32_e32 v94, 16, v170
	v_and_b32_e32 v95, 0xffff0000, v170
	v_lshlrev_b32_e32 v96, 16, v171
	v_and_b32_e32 v97, 0xffff0000, v171
	v_cvt_pk_bf16_f32 v93, v98, v99
	v_lshlrev_b32_e32 v98, 16, v172
	v_and_b32_e32 v99, 0xffff0000, v172
	v_pk_add_f32 v[88:89], v[88:89], v[96:97]
	v_pk_add_f32 v[86:87], v[86:87], v[94:95]
	v_cvt_pk_bf16_f32 v92, v100, v101
	v_lshlrev_b32_e32 v100, 16, v173
	v_and_b32_e32 v101, 0xffff0000, v173
	v_pk_add_f32 v[96:97], v[82:83], v[98:99]
	v_mul_f32_e32 v82, v87, v87
	v_mul_f32_e32 v83, v89, v89
	v_pk_add_f32 v[94:95], v[84:85], v[100:101]
	v_fmac_f32_e32 v82, v86, v86
	v_fmac_f32_e32 v83, v88, v88
	v_add_f32_e32 v82, v82, v83
	v_mul_f32_e32 v83, v97, v97
	v_mul_f32_e32 v84, v95, v95
	v_fmac_f32_e32 v83, v96, v96
	v_fmac_f32_e32 v84, v94, v94
	v_add_f32_e32 v83, v83, v84
	v_add_f32_e32 v82, v82, v83
	v_add_f32_e32 v85, v104, v82
	v_mov_b32_e32 v100, v85
	s_nop 1
	v_permlane16_swap_b32_e32 v100, v85
	v_lshl_add_u64 v[102:103], s[12:13], 0, v[232:233]
	v_lshl_add_u64 v[82:83], s[48:49], 1, v[102:103]
	v_lshl_add_u64 v[98:99], v[82:83], 0, v[202:203]
	v_cvt_pk_bf16_f32 v84, v86, v87
	s_waitcnt lgkmcnt(0)
	v_add_f32_e32 v82, v85, v100
	v_mov_b32_e32 v83, v82
	s_nop 1
	v_permlane32_swap_b32_e32 v83, v82
	v_cvt_pk_bf16_f32 v85, v88, v89
	v_cvt_pk_bf16_f32 v86, v96, v97
	v_cvt_pk_bf16_f32 v87, v94, v95
	global_store_dwordx4 v[98:99], v[90:93], off
	global_store_dwordx4 v[98:99], v[84:87], off offset:256
	s_and_saveexec_b64 s[50:51], s[4:5]
	s_cbranch_execz .LBB0_748
	v_lshl_add_u64 v[84:85], v[230:231], 2, s[14:15]
	s_waitcnt lgkmcnt(0)
	v_add_f32_e32 v82, v82, v83
	global_atomic_add_f32 v[84:85], v82, off
.LBB0_748:
	s_or_b64 exec, exec, s[50:51]
	v_lshlrev_b32_e32 v82, 16, v166
	s_waitcnt lgkmcnt(0)
	v_and_b32_e32 v83, 0xffff0000, v166
	v_lshlrev_b32_e32 v84, 16, v167
	v_and_b32_e32 v85, 0xffff0000, v167
	v_lshlrev_b32_e32 v86, 16, v168
	v_and_b32_e32 v87, 0xffff0000, v168
	v_pk_add_f32 v[78:79], v[78:79], v[82:83]
	v_pk_add_f32 v[80:81], v[80:81], v[84:85]
	v_pk_add_f32 v[84:85], v[74:75], v[86:87]
	v_cvt_pk_bf16_f32 v74, v78, v79
	v_mul_f32_e32 v79, v79, v79
	v_lshlrev_b32_e32 v88, 16, v169
	v_and_b32_e32 v89, 0xffff0000, v169
	v_fmac_f32_e32 v79, v78, v78
	v_mul_f32_e32 v78, v81, v81
	v_pk_add_f32 v[82:83], v[76:77], v[88:89]
	v_fmac_f32_e32 v78, v80, v80
	v_cvt_pk_bf16_f32 v75, v80, v81
	v_add_f32_e32 v78, v79, v78
	v_mul_f32_e32 v79, v85, v85
	v_mul_f32_e32 v80, v83, v83
	v_fmac_f32_e32 v79, v84, v84
	v_fmac_f32_e32 v80, v82, v82
	v_add_f32_e32 v79, v79, v80
	v_add_f32_e32 v88, v78, v79
	v_lshlrev_b32_e32 v78, 16, v162
	v_and_b32_e32 v79, 0xffff0000, v162
	v_lshlrev_b32_e32 v80, 16, v163
	v_and_b32_e32 v81, 0xffff0000, v163
	v_cvt_pk_bf16_f32 v77, v82, v83
	v_lshlrev_b32_e32 v82, 16, v164
	v_and_b32_e32 v83, 0xffff0000, v164
	v_pk_add_f32 v[72:73], v[72:73], v[80:81]
	v_pk_add_f32 v[70:71], v[70:71], v[78:79]
	v_cvt_pk_bf16_f32 v76, v84, v85
	v_lshlrev_b32_e32 v84, 16, v165
	v_and_b32_e32 v85, 0xffff0000, v165
	v_pk_add_f32 v[80:81], v[66:67], v[82:83]
	v_mul_f32_e32 v66, v71, v71
	v_mul_f32_e32 v67, v73, v73
	v_pk_add_f32 v[78:79], v[68:69], v[84:85]
	v_fmac_f32_e32 v66, v70, v70
	v_fmac_f32_e32 v67, v72, v72
	v_add_f32_e32 v66, v66, v67
	v_mul_f32_e32 v67, v81, v81
	v_mul_f32_e32 v68, v79, v79
	v_fmac_f32_e32 v67, v80, v80
	v_fmac_f32_e32 v68, v78, v78
	v_add_f32_e32 v67, v67, v68
	v_add_f32_e32 v66, v66, v67
	v_add_f32_e32 v69, v88, v66
	v_mov_b32_e32 v84, v69
	s_nop 1
	v_permlane16_swap_b32_e32 v84, v69
	v_lshl_add_u64 v[86:87], s[12:13], 0, v[228:229]
	v_lshl_add_u64 v[66:67], s[48:49], 1, v[86:87]
	v_lshl_add_u64 v[82:83], v[66:67], 0, v[202:203]
	v_cvt_pk_bf16_f32 v68, v70, v71
	s_waitcnt lgkmcnt(0)
	v_add_f32_e32 v66, v69, v84
	v_mov_b32_e32 v67, v66
	s_nop 1
	v_permlane32_swap_b32_e32 v67, v66
	v_cvt_pk_bf16_f32 v69, v72, v73
	v_cvt_pk_bf16_f32 v70, v80, v81
	v_cvt_pk_bf16_f32 v71, v78, v79
	global_store_dwordx4 v[82:83], v[74:77], off
	global_store_dwordx4 v[82:83], v[68:71], off offset:256
	s_and_saveexec_b64 s[50:51], s[4:5]
	s_cbranch_execz .LBB0_750
	v_lshl_add_u64 v[68:69], v[226:227], 2, s[14:15]
	s_waitcnt lgkmcnt(0)
	v_add_f32_e32 v66, v66, v67
	global_atomic_add_f32 v[68:69], v66, off
.LBB0_750:
	s_or_b64 exec, exec, s[50:51]
	v_lshlrev_b32_e32 v66, 16, v158
	s_waitcnt lgkmcnt(0)
	v_and_b32_e32 v67, 0xffff0000, v158
	v_lshlrev_b32_e32 v68, 16, v159
	v_and_b32_e32 v69, 0xffff0000, v159
	v_lshlrev_b32_e32 v70, 16, v160
	v_and_b32_e32 v71, 0xffff0000, v160
	v_pk_add_f32 v[62:63], v[62:63], v[66:67]
	v_pk_add_f32 v[64:65], v[64:65], v[68:69]
	v_pk_add_f32 v[68:69], v[58:59], v[70:71]
	v_cvt_pk_bf16_f32 v58, v62, v63
	v_mul_f32_e32 v63, v63, v63
	v_lshlrev_b32_e32 v72, 16, v161
	v_and_b32_e32 v73, 0xffff0000, v161
	v_fmac_f32_e32 v63, v62, v62
	v_mul_f32_e32 v62, v65, v65
	v_pk_add_f32 v[66:67], v[60:61], v[72:73]
	v_fmac_f32_e32 v62, v64, v64
	v_cvt_pk_bf16_f32 v59, v64, v65
	v_add_f32_e32 v62, v63, v62
	v_mul_f32_e32 v63, v69, v69
	v_mul_f32_e32 v64, v67, v67
	v_fmac_f32_e32 v63, v68, v68
	v_fmac_f32_e32 v64, v66, v66
	v_add_f32_e32 v63, v63, v64
	v_add_f32_e32 v72, v62, v63
	v_lshlrev_b32_e32 v62, 16, v146
	v_and_b32_e32 v63, 0xffff0000, v146
	v_lshlrev_b32_e32 v64, 16, v147
	v_and_b32_e32 v65, 0xffff0000, v147
	v_cvt_pk_bf16_f32 v61, v66, v67
	v_lshlrev_b32_e32 v66, 16, v148
	v_and_b32_e32 v67, 0xffff0000, v148
	v_pk_add_f32 v[56:57], v[56:57], v[64:65]
	v_pk_add_f32 v[54:55], v[54:55], v[62:63]
	v_cvt_pk_bf16_f32 v60, v68, v69
	v_lshlrev_b32_e32 v68, 16, v149
	v_and_b32_e32 v69, 0xffff0000, v149
	v_pk_add_f32 v[64:65], v[50:51], v[66:67]
	v_mul_f32_e32 v50, v55, v55
	v_mul_f32_e32 v51, v57, v57
	v_pk_add_f32 v[62:63], v[52:53], v[68:69]
	v_fmac_f32_e32 v50, v54, v54
	v_fmac_f32_e32 v51, v56, v56
	v_add_f32_e32 v50, v50, v51
	v_mul_f32_e32 v51, v65, v65
	v_mul_f32_e32 v52, v63, v63
	v_fmac_f32_e32 v51, v64, v64
	v_fmac_f32_e32 v52, v62, v62
	v_add_f32_e32 v51, v51, v52
	v_add_f32_e32 v50, v50, v51
	v_add_f32_e32 v53, v72, v50
	v_mov_b32_e32 v68, v53
	s_nop 1
	v_permlane16_swap_b32_e32 v68, v53
	v_lshl_add_u64 v[70:71], s[12:13], 0, v[224:225]
	v_lshl_add_u64 v[50:51], s[48:49], 1, v[70:71]
	v_lshl_add_u64 v[66:67], v[50:51], 0, v[202:203]
	v_cvt_pk_bf16_f32 v52, v54, v55
	s_waitcnt lgkmcnt(0)
	v_add_f32_e32 v50, v53, v68
	v_mov_b32_e32 v51, v50
	s_nop 1
	v_permlane32_swap_b32_e32 v51, v50
	v_cvt_pk_bf16_f32 v53, v56, v57
	v_cvt_pk_bf16_f32 v54, v64, v65
	v_cvt_pk_bf16_f32 v55, v62, v63
	global_store_dwordx4 v[66:67], v[58:61], off
	global_store_dwordx4 v[66:67], v[52:55], off offset:256
	s_and_saveexec_b64 s[50:51], s[4:5]
	s_cbranch_execz .LBB0_752
	v_lshl_add_u64 v[52:53], v[222:223], 2, s[14:15]
	s_waitcnt lgkmcnt(0)
	v_add_f32_e32 v50, v50, v51
	global_atomic_add_f32 v[52:53], v50, off
.LBB0_752:
	s_or_b64 exec, exec, s[50:51]
	v_lshlrev_b32_e32 v50, 16, v142
	s_waitcnt lgkmcnt(0)
	v_and_b32_e32 v51, 0xffff0000, v142
	v_lshlrev_b32_e32 v52, 16, v143
	v_and_b32_e32 v53, 0xffff0000, v143
	v_lshlrev_b32_e32 v54, 16, v144
	v_and_b32_e32 v55, 0xffff0000, v144
	v_pk_add_f32 v[46:47], v[46:47], v[50:51]
	v_pk_add_f32 v[48:49], v[48:49], v[52:53]
	v_pk_add_f32 v[52:53], v[42:43], v[54:55]
	v_cvt_pk_bf16_f32 v42, v46, v47
	v_mul_f32_e32 v47, v47, v47
	v_lshlrev_b32_e32 v56, 16, v145
	v_and_b32_e32 v57, 0xffff0000, v145
	v_fmac_f32_e32 v47, v46, v46
	v_mul_f32_e32 v46, v49, v49
	v_pk_add_f32 v[50:51], v[44:45], v[56:57]
	v_fmac_f32_e32 v46, v48, v48
	v_cvt_pk_bf16_f32 v43, v48, v49
	v_add_f32_e32 v46, v47, v46
	v_mul_f32_e32 v47, v53, v53
	v_mul_f32_e32 v48, v51, v51
	v_fmac_f32_e32 v47, v52, v52
	v_fmac_f32_e32 v48, v50, v50
	v_add_f32_e32 v47, v47, v48
	v_add_f32_e32 v56, v46, v47
	v_lshlrev_b32_e32 v46, 16, v138
	v_and_b32_e32 v47, 0xffff0000, v138
	v_lshlrev_b32_e32 v48, 16, v139
	v_and_b32_e32 v49, 0xffff0000, v139
	v_cvt_pk_bf16_f32 v45, v50, v51
	v_lshlrev_b32_e32 v50, 16, v140
	v_and_b32_e32 v51, 0xffff0000, v140
	v_pk_add_f32 v[40:41], v[40:41], v[48:49]
	v_pk_add_f32 v[38:39], v[38:39], v[46:47]
	v_cvt_pk_bf16_f32 v44, v52, v53
	v_lshlrev_b32_e32 v52, 16, v141
	v_and_b32_e32 v53, 0xffff0000, v141
	v_pk_add_f32 v[48:49], v[34:35], v[50:51]
	v_mul_f32_e32 v34, v39, v39
	v_mul_f32_e32 v35, v41, v41
	v_pk_add_f32 v[46:47], v[36:37], v[52:53]
	v_fmac_f32_e32 v34, v38, v38
	v_fmac_f32_e32 v35, v40, v40
	v_add_f32_e32 v34, v34, v35
	v_mul_f32_e32 v35, v49, v49
	v_mul_f32_e32 v36, v47, v47
	v_fmac_f32_e32 v35, v48, v48
	v_fmac_f32_e32 v36, v46, v46
	v_add_f32_e32 v35, v35, v36
	v_add_f32_e32 v34, v34, v35
	v_add_f32_e32 v37, v56, v34
	v_mov_b32_e32 v52, v37
	s_nop 1
	v_permlane16_swap_b32_e32 v52, v37
	v_lshl_add_u64 v[54:55], s[12:13], 0, v[220:221]
	v_lshl_add_u64 v[34:35], s[48:49], 1, v[54:55]
	v_lshl_add_u64 v[50:51], v[34:35], 0, v[202:203]
	v_cvt_pk_bf16_f32 v36, v38, v39
	s_waitcnt lgkmcnt(0)
	v_add_f32_e32 v34, v37, v52
	v_mov_b32_e32 v35, v34
	s_nop 1
	v_permlane32_swap_b32_e32 v35, v34
	v_cvt_pk_bf16_f32 v37, v40, v41
	v_cvt_pk_bf16_f32 v38, v48, v49
	v_cvt_pk_bf16_f32 v39, v46, v47
	global_store_dwordx4 v[50:51], v[42:45], off
	global_store_dwordx4 v[50:51], v[36:39], off offset:256
	s_and_saveexec_b64 s[50:51], s[4:5]
	s_cbranch_execz .LBB0_754
	v_lshl_add_u64 v[36:37], v[218:219], 2, s[14:15]
	s_waitcnt lgkmcnt(0)
	v_add_f32_e32 v34, v34, v35
	global_atomic_add_f32 v[36:37], v34, off
.LBB0_754:
	s_or_b64 exec, exec, s[50:51]
	v_lshlrev_b32_e32 v34, 16, v130
	s_waitcnt lgkmcnt(0)
	v_and_b32_e32 v35, 0xffff0000, v130
	v_lshlrev_b32_e32 v36, 16, v131
	v_and_b32_e32 v37, 0xffff0000, v131
	v_lshlrev_b32_e32 v38, 16, v132
	v_and_b32_e32 v39, 0xffff0000, v132
	v_pk_add_f32 v[30:31], v[30:31], v[34:35]
	v_pk_add_f32 v[32:33], v[32:33], v[36:37]
	v_pk_add_f32 v[36:37], v[26:27], v[38:39]
	v_cvt_pk_bf16_f32 v26, v30, v31
	v_mul_f32_e32 v31, v31, v31
	v_lshlrev_b32_e32 v40, 16, v133
	v_and_b32_e32 v41, 0xffff0000, v133
	v_fmac_f32_e32 v31, v30, v30
	v_mul_f32_e32 v30, v33, v33
	v_pk_add_f32 v[34:35], v[28:29], v[40:41]
	v_fmac_f32_e32 v30, v32, v32
	v_cvt_pk_bf16_f32 v27, v32, v33
	v_add_f32_e32 v30, v31, v30
	v_mul_f32_e32 v31, v37, v37
	v_mul_f32_e32 v32, v35, v35
	v_fmac_f32_e32 v31, v36, v36
	v_fmac_f32_e32 v32, v34, v34
	v_add_f32_e32 v31, v31, v32
	v_add_f32_e32 v40, v30, v31
	v_lshlrev_b32_e32 v30, 16, v122
	v_and_b32_e32 v31, 0xffff0000, v122
	v_lshlrev_b32_e32 v32, 16, v123
	v_and_b32_e32 v33, 0xffff0000, v123
	v_cvt_pk_bf16_f32 v29, v34, v35
	v_lshlrev_b32_e32 v34, 16, v124
	v_and_b32_e32 v35, 0xffff0000, v124
	v_pk_add_f32 v[24:25], v[24:25], v[32:33]
	v_pk_add_f32 v[22:23], v[22:23], v[30:31]
	v_cvt_pk_bf16_f32 v28, v36, v37
	v_lshlrev_b32_e32 v36, 16, v125
	v_and_b32_e32 v37, 0xffff0000, v125
	v_pk_add_f32 v[32:33], v[18:19], v[34:35]
	v_mul_f32_e32 v18, v23, v23
	v_mul_f32_e32 v19, v25, v25
	v_pk_add_f32 v[30:31], v[20:21], v[36:37]
	v_fmac_f32_e32 v18, v22, v22
	v_fmac_f32_e32 v19, v24, v24
	v_add_f32_e32 v18, v18, v19
	v_mul_f32_e32 v19, v33, v33
	v_mul_f32_e32 v20, v31, v31
	v_fmac_f32_e32 v19, v32, v32
	v_fmac_f32_e32 v20, v30, v30
	v_add_f32_e32 v19, v19, v20
	v_add_f32_e32 v18, v18, v19
	v_add_f32_e32 v21, v40, v18
	v_mov_b32_e32 v36, v21
	s_nop 1
	v_permlane16_swap_b32_e32 v36, v21
	v_lshl_add_u64 v[38:39], s[12:13], 0, v[216:217]
	v_lshl_add_u64 v[18:19], s[48:49], 1, v[38:39]
	v_lshl_add_u64 v[34:35], v[18:19], 0, v[202:203]
	v_cvt_pk_bf16_f32 v20, v22, v23
	s_waitcnt lgkmcnt(0)
	v_add_f32_e32 v18, v21, v36
	v_mov_b32_e32 v19, v18
	s_nop 1
	v_permlane32_swap_b32_e32 v19, v18
	v_cvt_pk_bf16_f32 v21, v24, v25
	v_cvt_pk_bf16_f32 v22, v32, v33
	v_cvt_pk_bf16_f32 v23, v30, v31
	global_store_dwordx4 v[34:35], v[26:29], off
	global_store_dwordx4 v[34:35], v[20:23], off offset:256
	s_and_saveexec_b64 s[50:51], s[4:5]
	s_cbranch_execz .LBB0_756
	v_lshl_add_u64 v[20:21], v[212:213], 2, s[14:15]
	s_waitcnt lgkmcnt(0)
	v_add_f32_e32 v18, v18, v19
	global_atomic_add_f32 v[20:21], v18, off
.LBB0_756:
	s_or_b64 exec, exec, s[50:51]
	v_lshlrev_b32_e32 v18, 16, v134
	s_waitcnt lgkmcnt(0)
	v_and_b32_e32 v19, 0xffff0000, v134
	v_lshlrev_b32_e32 v20, 16, v135
	v_and_b32_e32 v21, 0xffff0000, v135
	v_lshlrev_b32_e32 v22, 16, v136
	v_and_b32_e32 v23, 0xffff0000, v136
	v_pk_add_f32 v[14:15], v[14:15], v[18:19]
	v_pk_add_f32 v[16:17], v[16:17], v[20:21]
	v_pk_add_f32 v[20:21], v[10:11], v[22:23]
	v_cvt_pk_bf16_f32 v10, v14, v15
	v_mul_f32_e32 v15, v15, v15
	v_lshlrev_b32_e32 v24, 16, v137
	v_and_b32_e32 v25, 0xffff0000, v137
	v_fmac_f32_e32 v15, v14, v14
	v_mul_f32_e32 v14, v17, v17
	v_pk_add_f32 v[18:19], v[12:13], v[24:25]
	v_fmac_f32_e32 v14, v16, v16
	v_cvt_pk_bf16_f32 v11, v16, v17
	v_add_f32_e32 v14, v15, v14
	v_mul_f32_e32 v15, v21, v21
	v_mul_f32_e32 v16, v19, v19
	v_fmac_f32_e32 v15, v20, v20
	v_fmac_f32_e32 v16, v18, v18
	v_add_f32_e32 v15, v15, v16
	v_add_f32_e32 v24, v14, v15
	v_lshlrev_b32_e32 v14, 16, v126
	v_and_b32_e32 v15, 0xffff0000, v126
	v_lshlrev_b32_e32 v16, 16, v127
	v_and_b32_e32 v17, 0xffff0000, v127
	v_cvt_pk_bf16_f32 v13, v18, v19
	v_lshlrev_b32_e32 v18, 16, v128
	v_and_b32_e32 v19, 0xffff0000, v128
	v_pk_add_f32 v[8:9], v[8:9], v[16:17]
	v_pk_add_f32 v[6:7], v[6:7], v[14:15]
	v_cvt_pk_bf16_f32 v12, v20, v21
	v_lshlrev_b32_e32 v20, 16, v129
	v_and_b32_e32 v21, 0xffff0000, v129
	v_pk_add_f32 v[16:17], v[2:3], v[18:19]
	v_mul_f32_e32 v2, v7, v7
	v_mul_f32_e32 v3, v9, v9
	v_pk_add_f32 v[14:15], v[4:5], v[20:21]
	v_fmac_f32_e32 v2, v6, v6
	v_fmac_f32_e32 v3, v8, v8
	v_add_f32_e32 v2, v2, v3
	v_mul_f32_e32 v3, v17, v17
	v_mul_f32_e32 v4, v15, v15
	v_fmac_f32_e32 v3, v16, v16
	v_fmac_f32_e32 v4, v14, v14
	v_add_f32_e32 v3, v3, v4
	v_add_f32_e32 v2, v2, v3
	v_add_f32_e32 v5, v24, v2
	v_mov_b32_e32 v20, v5
	s_nop 1
	v_permlane16_swap_b32_e32 v20, v5
	v_lshl_add_u64 v[22:23], s[12:13], 0, v[214:215]
	v_lshl_add_u64 v[2:3], s[48:49], 1, v[22:23]
	v_lshl_add_u64 v[18:19], v[2:3], 0, v[202:203]
	v_cvt_pk_bf16_f32 v4, v6, v7
	s_waitcnt lgkmcnt(0)
	v_add_f32_e32 v2, v5, v20
	v_mov_b32_e32 v3, v2
	s_nop 1
	v_permlane32_swap_b32_e32 v3, v2
	v_cvt_pk_bf16_f32 v5, v8, v9
	v_cvt_pk_bf16_f32 v6, v16, v17
	v_cvt_pk_bf16_f32 v7, v14, v15
	global_store_dwordx4 v[18:19], v[10:13], off
	global_store_dwordx4 v[18:19], v[4:7], off offset:256
	s_and_saveexec_b64 s[48:49], s[4:5]
	s_cbranch_execz .LBB0_758
	v_lshl_add_u64 v[4:5], v[210:211], 2, s[14:15]
	s_waitcnt lgkmcnt(0)
	v_add_f32_e32 v2, v2, v3
	global_atomic_add_f32 v[4:5], v2, off

.LBB0_1057:
.LBB0_1058:
	v_pk_mul_f32 v[128:129], v[128:129], v[152:153] op_sel_hi:[1,0]
	v_pk_mul_f32 v[126:127], v[126:127], v[152:153] op_sel_hi:[1,0]
	v_pk_mul_f32 v[164:165], v[124:125], v[152:153] op_sel_hi:[1,0]
	v_pk_mul_f32 v[124:125], v[122:123], v[152:153] op_sel_hi:[1,0]
	v_mul_f32_e32 v122, v127, v127
	v_mul_f32_e32 v123, v129, v129
	v_fmac_f32_e32 v122, v126, v126
	v_fmac_f32_e32 v123, v128, v128
	v_add_f32_e32 v122, v122, v123
	v_mul_f32_e32 v123, v125, v125
	v_mul_f32_e32 v161, v165, v165
	v_fmac_f32_e32 v123, v124, v124
	v_fmac_f32_e32 v161, v164, v164
	v_add_f32_e32 v123, v123, v161
	v_pk_mul_f32 v[120:121], v[120:121], v[152:153] op_sel_hi:[1,0]
	v_pk_mul_f32 v[118:119], v[118:119], v[152:153] op_sel_hi:[1,0]
	v_add_f32_e32 v161, v122, v123
	v_cvt_pk_bf16_f32 v123, v128, v129
	v_pk_mul_f32 v[128:129], v[114:115], v[152:153] op_sel_hi:[1,0]
	v_mul_f32_e32 v114, v119, v119
	v_mul_f32_e32 v115, v121, v121
	v_cvt_pk_bf16_f32 v122, v126, v127
	v_pk_mul_f32 v[126:127], v[116:117], v[152:153] op_sel_hi:[1,0]
	v_fmac_f32_e32 v114, v118, v118
	v_fmac_f32_e32 v115, v120, v120
	v_add_f32_e32 v114, v114, v115
	v_mul_f32_e32 v115, v129, v129
	v_mul_f32_e32 v116, v127, v127
	v_fmac_f32_e32 v115, v128, v128
	v_fmac_f32_e32 v116, v126, v126
	v_add_f32_e32 v115, v115, v116
	v_and_b32_e32 v116, 64, v160
	v_add_f32_e32 v114, v114, v115
	v_xor_b32_e32 v115, 16, v160
	v_add_u32_e32 v117, 64, v116
	v_cmp_lt_i32_e32 vcc, v115, v117
	v_add_f32_e32 v114, v161, v114
	v_lshlrev_b64 v[162:163], 9, v[150:151]
	v_cndmask_b32_e32 v115, v160, v115, vcc
	v_lshlrev_b32_e32 v115, 2, v115
	v_mov_b32_e32 v115, v114
	s_nop 1
	v_permlane16_swap_b32_e32 v115, v114
	v_cvt_pk_bf16_f32 v124, v124, v125
	v_cvt_pk_bf16_f32 v125, v164, v165
	v_lshl_add_u64 v[162:163], v[140:141], 0, v[162:163]
	v_cvt_pk_bf16_f32 v116, v118, v119
	s_waitcnt lgkmcnt(0)
	v_add_f32_e32 v114, v114, v115
	v_xor_b32_e32 v115, 32, v160
	v_cmp_lt_i32_e32 vcc, v115, v117
	v_cvt_pk_bf16_f32 v117, v120, v121
	v_cvt_pk_bf16_f32 v118, v128, v129
	v_cndmask_b32_e32 v115, v160, v115, vcc
	v_lshlrev_b32_e32 v115, 2, v115
	v_mov_b32_e32 v115, v114
	s_nop 1
	v_permlane32_swap_b32_e32 v115, v114
	v_cvt_pk_bf16_f32 v119, v126, v127
	global_store_dwordx4 v[162:163], v[122:125], off
	global_store_dwordx4 v[162:163], v[116:119], off offset:256
	s_and_saveexec_b64 s[10:11], s[4:5]
	s_cbranch_execz .LBB0_1060
	v_lshl_add_u64 v[116:117], v[150:151], 2, s[24:25]
	s_waitcnt lgkmcnt(0)
	v_add_f32_e32 v114, v114, v115
	global_atomic_add_f32 v[116:117], v114, off

.LBB0_1065:
.LBB0_1066:
	v_pk_mul_f32 v[112:113], v[112:113], v[116:117] op_sel_hi:[1,0]
	v_pk_mul_f32 v[110:111], v[110:111], v[116:117] op_sel_hi:[1,0]
	v_pk_mul_f32 v[120:121], v[108:109], v[116:117] op_sel_hi:[1,0]
	v_pk_mul_f32 v[108:109], v[106:107], v[116:117] op_sel_hi:[1,0]
	v_mul_f32_e32 v106, v111, v111
	v_mul_f32_e32 v107, v113, v113
	v_fmac_f32_e32 v106, v110, v110
	v_fmac_f32_e32 v107, v112, v112
	v_add_f32_e32 v106, v106, v107
	v_mul_f32_e32 v107, v109, v109
	v_mul_f32_e32 v117, v121, v121
	v_fmac_f32_e32 v107, v108, v108
	v_fmac_f32_e32 v117, v120, v120
	v_add_f32_e32 v107, v107, v117
	v_add_f32_e32 v117, v106, v107
	v_pk_mul_f32 v[104:105], v[104:105], v[116:117] op_sel_hi:[1,0]
	v_pk_mul_f32 v[102:103], v[102:103], v[116:117] op_sel_hi:[1,0]
	v_cvt_pk_bf16_f32 v107, v112, v113
	v_pk_mul_f32 v[112:113], v[98:99], v[116:117] op_sel_hi:[1,0]
	v_mul_f32_e32 v98, v103, v103
	v_mul_f32_e32 v99, v105, v105
	v_cvt_pk_bf16_f32 v106, v110, v111
	v_pk_mul_f32 v[110:111], v[100:101], v[116:117] op_sel_hi:[1,0]
	v_fmac_f32_e32 v98, v102, v102
	v_fmac_f32_e32 v99, v104, v104
	v_add_f32_e32 v98, v98, v99
	v_mul_f32_e32 v99, v113, v113
	v_mul_f32_e32 v100, v111, v111
	v_fmac_f32_e32 v99, v112, v112
	v_fmac_f32_e32 v100, v110, v110
	v_add_f32_e32 v99, v99, v100
	v_and_b32_e32 v100, 64, v160
	v_add_f32_e32 v98, v98, v99
	v_xor_b32_e32 v99, 16, v160
	v_add_u32_e32 v101, 64, v100
	v_cmp_lt_i32_e32 vcc, v99, v101
	v_add_f32_e32 v98, v117, v98
	v_lshlrev_b64 v[118:119], 9, v[114:115]
	v_cndmask_b32_e32 v99, v160, v99, vcc
	v_lshlrev_b32_e32 v99, 2, v99
	v_mov_b32_e32 v99, v98
	s_nop 1
	v_permlane16_swap_b32_e32 v99, v98
	v_cvt_pk_bf16_f32 v108, v108, v109
	v_cvt_pk_bf16_f32 v109, v120, v121
	v_lshl_add_u64 v[116:117], v[140:141], 0, v[118:119]
	v_cvt_pk_bf16_f32 v100, v102, v103
	s_waitcnt lgkmcnt(0)
	v_add_f32_e32 v98, v98, v99
	v_xor_b32_e32 v99, 32, v160
	v_cmp_lt_i32_e32 vcc, v99, v101
	v_cvt_pk_bf16_f32 v101, v104, v105
	v_cvt_pk_bf16_f32 v102, v112, v113
	v_cndmask_b32_e32 v99, v160, v99, vcc
	v_lshlrev_b32_e32 v99, 2, v99
	v_mov_b32_e32 v99, v98
	s_nop 1
	v_permlane32_swap_b32_e32 v99, v98
	v_cvt_pk_bf16_f32 v103, v110, v111
	global_store_dwordx4 v[116:117], v[106:109], off
	global_store_dwordx4 v[116:117], v[100:103], off offset:256
	s_and_saveexec_b64 s[56:57], s[4:5]
	s_cbranch_execz .LBB0_1068
	v_lshl_add_u64 v[100:101], v[114:115], 2, s[24:25]
	s_waitcnt lgkmcnt(0)
	v_add_f32_e32 v98, v98, v99
	global_atomic_add_f32 v[100:101], v98, off

.LBB0_1073:
.LBB0_1074:
	v_pk_mul_f32 v[96:97], v[96:97], v[100:101] op_sel_hi:[1,0]
	v_pk_mul_f32 v[94:95], v[94:95], v[100:101] op_sel_hi:[1,0]
	v_pk_mul_f32 v[104:105], v[92:93], v[100:101] op_sel_hi:[1,0]
	v_pk_mul_f32 v[92:93], v[90:91], v[100:101] op_sel_hi:[1,0]
	v_mul_f32_e32 v90, v95, v95
	v_mul_f32_e32 v91, v97, v97
	v_fmac_f32_e32 v90, v94, v94
	v_fmac_f32_e32 v91, v96, v96
	v_add_f32_e32 v90, v90, v91
	v_mul_f32_e32 v91, v93, v93
	v_mul_f32_e32 v101, v105, v105
	v_fmac_f32_e32 v91, v92, v92
	v_fmac_f32_e32 v101, v104, v104
	v_add_f32_e32 v91, v91, v101
	v_add_f32_e32 v101, v90, v91
	v_pk_mul_f32 v[88:89], v[88:89], v[100:101] op_sel_hi:[1,0]
	v_pk_mul_f32 v[86:87], v[86:87], v[100:101] op_sel_hi:[1,0]
	v_cvt_pk_bf16_f32 v91, v96, v97
	v_pk_mul_f32 v[96:97], v[82:83], v[100:101] op_sel_hi:[1,0]
	v_mul_f32_e32 v82, v87, v87
	v_mul_f32_e32 v83, v89, v89
	v_cvt_pk_bf16_f32 v90, v94, v95
	v_pk_mul_f32 v[94:95], v[84:85], v[100:101] op_sel_hi:[1,0]
	v_fmac_f32_e32 v82, v86, v86
	v_fmac_f32_e32 v83, v88, v88
	v_add_f32_e32 v82, v82, v83
	v_mul_f32_e32 v83, v97, v97
	v_mul_f32_e32 v84, v95, v95
	v_fmac_f32_e32 v83, v96, v96
	v_fmac_f32_e32 v84, v94, v94
	v_add_f32_e32 v83, v83, v84
	v_and_b32_e32 v84, 64, v160
	v_add_f32_e32 v82, v82, v83
	v_xor_b32_e32 v83, 16, v160
	v_add_u32_e32 v85, 64, v84
	v_cmp_lt_i32_e32 vcc, v83, v85
	v_add_f32_e32 v82, v101, v82
	v_lshlrev_b64 v[102:103], 9, v[98:99]
	v_cndmask_b32_e32 v83, v160, v83, vcc
	v_lshlrev_b32_e32 v83, 2, v83
	v_mov_b32_e32 v83, v82
	s_nop 1
	v_permlane16_swap_b32_e32 v83, v82
	v_cvt_pk_bf16_f32 v92, v92, v93
	v_cvt_pk_bf16_f32 v93, v104, v105
	v_lshl_add_u64 v[100:101], v[140:141], 0, v[102:103]
	v_cvt_pk_bf16_f32 v84, v86, v87
	s_waitcnt lgkmcnt(0)
	v_add_f32_e32 v82, v82, v83
	v_xor_b32_e32 v83, 32, v160
	v_cmp_lt_i32_e32 vcc, v83, v85
	v_cvt_pk_bf16_f32 v85, v88, v89
	v_cvt_pk_bf16_f32 v86, v96, v97
	v_cndmask_b32_e32 v83, v160, v83, vcc
	v_lshlrev_b32_e32 v83, 2, v83
	v_mov_b32_e32 v83, v82
	s_nop 1
	v_permlane32_swap_b32_e32 v83, v82
	v_cvt_pk_bf16_f32 v87, v94, v95
	global_store_dwordx4 v[100:101], v[90:93], off
	global_store_dwordx4 v[100:101], v[84:87], off offset:256
	s_and_saveexec_b64 s[56:57], s[4:5]
	s_cbranch_execz .LBB0_1076
	v_lshl_add_u64 v[84:85], v[98:99], 2, s[24:25]
	s_waitcnt lgkmcnt(0)
	v_add_f32_e32 v82, v82, v83
	global_atomic_add_f32 v[84:85], v82, off

.LBB0_1081:
.LBB0_1082:
	v_pk_mul_f32 v[80:81], v[80:81], v[84:85] op_sel_hi:[1,0]
	v_pk_mul_f32 v[78:79], v[78:79], v[84:85] op_sel_hi:[1,0]
	v_pk_mul_f32 v[88:89], v[76:77], v[84:85] op_sel_hi:[1,0]
	v_pk_mul_f32 v[76:77], v[74:75], v[84:85] op_sel_hi:[1,0]
	v_mul_f32_e32 v74, v79, v79
	v_mul_f32_e32 v75, v81, v81
	v_fmac_f32_e32 v74, v78, v78
	v_fmac_f32_e32 v75, v80, v80
	v_add_f32_e32 v74, v74, v75
	v_mul_f32_e32 v75, v77, v77
	v_mul_f32_e32 v85, v89, v89
	v_fmac_f32_e32 v75, v76, v76
	v_fmac_f32_e32 v85, v88, v88
	v_add_f32_e32 v75, v75, v85
	v_add_f32_e32 v85, v74, v75
	v_pk_mul_f32 v[72:73], v[72:73], v[84:85] op_sel_hi:[1,0]
	v_pk_mul_f32 v[70:71], v[70:71], v[84:85] op_sel_hi:[1,0]
	v_cvt_pk_bf16_f32 v75, v80, v81
	v_pk_mul_f32 v[80:81], v[66:67], v[84:85] op_sel_hi:[1,0]
	v_mul_f32_e32 v66, v71, v71
	v_mul_f32_e32 v67, v73, v73
	v_cvt_pk_bf16_f32 v74, v78, v79
	v_pk_mul_f32 v[78:79], v[68:69], v[84:85] op_sel_hi:[1,0]
	v_fmac_f32_e32 v66, v70, v70
	v_fmac_f32_e32 v67, v72, v72
	v_add_f32_e32 v66, v66, v67
	v_mul_f32_e32 v67, v81, v81
	v_mul_f32_e32 v68, v79, v79
	v_fmac_f32_e32 v67, v80, v80
	v_fmac_f32_e32 v68, v78, v78
	v_add_f32_e32 v67, v67, v68
	v_and_b32_e32 v68, 64, v160
	v_add_f32_e32 v66, v66, v67
	v_xor_b32_e32 v67, 16, v160
	v_add_u32_e32 v69, 64, v68
	v_cmp_lt_i32_e32 vcc, v67, v69
	v_add_f32_e32 v66, v85, v66
	v_lshlrev_b64 v[86:87], 9, v[82:83]
	v_cndmask_b32_e32 v67, v160, v67, vcc
	v_lshlrev_b32_e32 v67, 2, v67
	v_mov_b32_e32 v67, v66
	s_nop 1
	v_permlane16_swap_b32_e32 v67, v66
	v_cvt_pk_bf16_f32 v76, v76, v77
	v_cvt_pk_bf16_f32 v77, v88, v89
	v_lshl_add_u64 v[84:85], v[140:141], 0, v[86:87]
	v_cvt_pk_bf16_f32 v68, v70, v71
	s_waitcnt lgkmcnt(0)
	v_add_f32_e32 v66, v66, v67
	v_xor_b32_e32 v67, 32, v160
	v_cmp_lt_i32_e32 vcc, v67, v69
	v_cvt_pk_bf16_f32 v69, v72, v73
	v_cvt_pk_bf16_f32 v70, v80, v81
	v_cndmask_b32_e32 v67, v160, v67, vcc
	v_lshlrev_b32_e32 v67, 2, v67
	v_mov_b32_e32 v67, v66
	s_nop 1
	v_permlane32_swap_b32_e32 v67, v66
	v_cvt_pk_bf16_f32 v71, v78, v79
	global_store_dwordx4 v[84:85], v[74:77], off
	global_store_dwordx4 v[84:85], v[68:71], off offset:256
	s_and_saveexec_b64 s[56:57], s[4:5]
	s_cbranch_execz .LBB0_1084
	v_lshl_add_u64 v[68:69], v[82:83], 2, s[24:25]
	s_waitcnt lgkmcnt(0)
	v_add_f32_e32 v66, v66, v67
	global_atomic_add_f32 v[68:69], v66, off

.LBB0_1089:
.LBB0_1090:
	v_pk_mul_f32 v[64:65], v[64:65], v[68:69] op_sel_hi:[1,0]
	v_pk_mul_f32 v[62:63], v[62:63], v[68:69] op_sel_hi:[1,0]
	v_pk_mul_f32 v[72:73], v[60:61], v[68:69] op_sel_hi:[1,0]
	v_pk_mul_f32 v[60:61], v[58:59], v[68:69] op_sel_hi:[1,0]
	v_mul_f32_e32 v58, v63, v63
	v_mul_f32_e32 v59, v65, v65
	v_fmac_f32_e32 v58, v62, v62
	v_fmac_f32_e32 v59, v64, v64
	v_add_f32_e32 v58, v58, v59
	v_mul_f32_e32 v59, v61, v61
	v_mul_f32_e32 v69, v73, v73
	v_fmac_f32_e32 v59, v60, v60
	v_fmac_f32_e32 v69, v72, v72
	v_add_f32_e32 v59, v59, v69
	v_add_f32_e32 v69, v58, v59
	v_pk_mul_f32 v[56:57], v[56:57], v[68:69] op_sel_hi:[1,0]
	v_pk_mul_f32 v[54:55], v[54:55], v[68:69] op_sel_hi:[1,0]
	v_cvt_pk_bf16_f32 v59, v64, v65
	v_pk_mul_f32 v[64:65], v[50:51], v[68:69] op_sel_hi:[1,0]
	v_mul_f32_e32 v50, v55, v55
	v_mul_f32_e32 v51, v57, v57
	v_cvt_pk_bf16_f32 v58, v62, v63
	v_pk_mul_f32 v[62:63], v[52:53], v[68:69] op_sel_hi:[1,0]
	v_fmac_f32_e32 v50, v54, v54
	v_fmac_f32_e32 v51, v56, v56
	v_add_f32_e32 v50, v50, v51
	v_mul_f32_e32 v51, v65, v65
	v_mul_f32_e32 v52, v63, v63
	v_fmac_f32_e32 v51, v64, v64
	v_fmac_f32_e32 v52, v62, v62
	v_add_f32_e32 v51, v51, v52
	v_and_b32_e32 v52, 64, v160
	v_add_f32_e32 v50, v50, v51
	v_xor_b32_e32 v51, 16, v160
	v_add_u32_e32 v53, 64, v52
	v_cmp_lt_i32_e32 vcc, v51, v53
	v_add_f32_e32 v50, v69, v50
	v_lshlrev_b64 v[70:71], 9, v[66:67]
	v_cndmask_b32_e32 v51, v160, v51, vcc
	v_lshlrev_b32_e32 v51, 2, v51
	v_mov_b32_e32 v51, v50
	s_nop 1
	v_permlane16_swap_b32_e32 v51, v50
	v_cvt_pk_bf16_f32 v60, v60, v61
	v_cvt_pk_bf16_f32 v61, v72, v73
	v_lshl_add_u64 v[68:69], v[140:141], 0, v[70:71]
	v_cvt_pk_bf16_f32 v52, v54, v55
	s_waitcnt lgkmcnt(0)
	v_add_f32_e32 v50, v50, v51
	v_xor_b32_e32 v51, 32, v160
	v_cmp_lt_i32_e32 vcc, v51, v53
	v_cvt_pk_bf16_f32 v53, v56, v57
	v_cvt_pk_bf16_f32 v54, v64, v65
	v_cndmask_b32_e32 v51, v160, v51, vcc
	v_lshlrev_b32_e32 v51, 2, v51
	v_mov_b32_e32 v51, v50
	s_nop 1
	v_permlane32_swap_b32_e32 v51, v50
	v_cvt_pk_bf16_f32 v55, v62, v63
	global_store_dwordx4 v[68:69], v[58:61], off
	global_store_dwordx4 v[68:69], v[52:55], off offset:256
	s_and_saveexec_b64 s[56:57], s[4:5]
	s_cbranch_execz .LBB0_1092
	v_lshl_add_u64 v[52:53], v[66:67], 2, s[24:25]
	s_waitcnt lgkmcnt(0)
	v_add_f32_e32 v50, v50, v51
	global_atomic_add_f32 v[52:53], v50, off

.LBB0_1097:
.LBB0_1098:
	v_pk_mul_f32 v[48:49], v[48:49], v[52:53] op_sel_hi:[1,0]
	v_pk_mul_f32 v[46:47], v[46:47], v[52:53] op_sel_hi:[1,0]
	v_pk_mul_f32 v[56:57], v[44:45], v[52:53] op_sel_hi:[1,0]
	v_pk_mul_f32 v[44:45], v[42:43], v[52:53] op_sel_hi:[1,0]
	v_mul_f32_e32 v42, v47, v47
	v_mul_f32_e32 v43, v49, v49
	v_fmac_f32_e32 v42, v46, v46
	v_fmac_f32_e32 v43, v48, v48
	v_add_f32_e32 v42, v42, v43
	v_mul_f32_e32 v43, v45, v45
	v_mul_f32_e32 v53, v57, v57
	v_fmac_f32_e32 v43, v44, v44
	v_fmac_f32_e32 v53, v56, v56
	v_add_f32_e32 v43, v43, v53
	v_add_f32_e32 v53, v42, v43
	v_pk_mul_f32 v[40:41], v[40:41], v[52:53] op_sel_hi:[1,0]
	v_pk_mul_f32 v[38:39], v[38:39], v[52:53] op_sel_hi:[1,0]
	v_cvt_pk_bf16_f32 v43, v48, v49
	v_pk_mul_f32 v[48:49], v[34:35], v[52:53] op_sel_hi:[1,0]
	v_mul_f32_e32 v34, v39, v39
	v_mul_f32_e32 v35, v41, v41
	v_cvt_pk_bf16_f32 v42, v46, v47
	v_pk_mul_f32 v[46:47], v[36:37], v[52:53] op_sel_hi:[1,0]
	v_fmac_f32_e32 v34, v38, v38
	v_fmac_f32_e32 v35, v40, v40
	v_add_f32_e32 v34, v34, v35
	v_mul_f32_e32 v35, v49, v49
	v_mul_f32_e32 v36, v47, v47
	v_fmac_f32_e32 v35, v48, v48
	v_fmac_f32_e32 v36, v46, v46
	v_add_f32_e32 v35, v35, v36
	v_and_b32_e32 v36, 64, v160
	v_add_f32_e32 v34, v34, v35
	v_xor_b32_e32 v35, 16, v160
	v_add_u32_e32 v37, 64, v36
	v_cmp_lt_i32_e32 vcc, v35, v37
	v_add_f32_e32 v34, v53, v34
	v_lshlrev_b64 v[54:55], 9, v[50:51]
	v_cndmask_b32_e32 v35, v160, v35, vcc
	v_lshlrev_b32_e32 v35, 2, v35
	v_mov_b32_e32 v35, v34
	s_nop 1
	v_permlane16_swap_b32_e32 v35, v34
	v_cvt_pk_bf16_f32 v44, v44, v45
	v_cvt_pk_bf16_f32 v45, v56, v57
	v_lshl_add_u64 v[52:53], v[140:141], 0, v[54:55]
	v_cvt_pk_bf16_f32 v36, v38, v39
	s_waitcnt lgkmcnt(0)
	v_add_f32_e32 v34, v34, v35
	v_xor_b32_e32 v35, 32, v160
	v_cmp_lt_i32_e32 vcc, v35, v37
	v_cvt_pk_bf16_f32 v37, v40, v41
	v_cvt_pk_bf16_f32 v38, v48, v49
	v_cndmask_b32_e32 v35, v160, v35, vcc
	v_lshlrev_b32_e32 v35, 2, v35
	v_mov_b32_e32 v35, v34
	s_nop 1
	v_permlane32_swap_b32_e32 v35, v34
	v_cvt_pk_bf16_f32 v39, v46, v47
	global_store_dwordx4 v[52:53], v[42:45], off
	global_store_dwordx4 v[52:53], v[36:39], off offset:256
	s_and_saveexec_b64 s[56:57], s[4:5]
	s_cbranch_execz .LBB0_1100
	v_lshl_add_u64 v[36:37], v[50:51], 2, s[24:25]
	s_waitcnt lgkmcnt(0)
	v_add_f32_e32 v34, v34, v35
	global_atomic_add_f32 v[36:37], v34, off

.LBB0_1105:
.LBB0_1106:
	v_pk_mul_f32 v[32:33], v[32:33], v[36:37] op_sel_hi:[1,0]
	v_pk_mul_f32 v[30:31], v[30:31], v[36:37] op_sel_hi:[1,0]
	v_pk_mul_f32 v[40:41], v[28:29], v[36:37] op_sel_hi:[1,0]
	v_pk_mul_f32 v[28:29], v[26:27], v[36:37] op_sel_hi:[1,0]
	v_mul_f32_e32 v26, v31, v31
	v_mul_f32_e32 v27, v33, v33
	v_fmac_f32_e32 v26, v30, v30
	v_fmac_f32_e32 v27, v32, v32
	v_add_f32_e32 v26, v26, v27
	v_mul_f32_e32 v27, v29, v29
	v_mul_f32_e32 v37, v41, v41
	v_fmac_f32_e32 v27, v28, v28
	v_fmac_f32_e32 v37, v40, v40
	v_add_f32_e32 v27, v27, v37
	v_add_f32_e32 v37, v26, v27
	v_pk_mul_f32 v[24:25], v[24:25], v[36:37] op_sel_hi:[1,0]
	v_pk_mul_f32 v[22:23], v[22:23], v[36:37] op_sel_hi:[1,0]
	v_cvt_pk_bf16_f32 v27, v32, v33
	v_pk_mul_f32 v[32:33], v[18:19], v[36:37] op_sel_hi:[1,0]
	v_mul_f32_e32 v18, v23, v23
	v_mul_f32_e32 v19, v25, v25
	v_cvt_pk_bf16_f32 v26, v30, v31
	v_pk_mul_f32 v[30:31], v[20:21], v[36:37] op_sel_hi:[1,0]
	v_fmac_f32_e32 v18, v22, v22
	v_fmac_f32_e32 v19, v24, v24
	v_add_f32_e32 v18, v18, v19
	v_mul_f32_e32 v19, v33, v33
	v_mul_f32_e32 v20, v31, v31
	v_fmac_f32_e32 v19, v32, v32
	v_fmac_f32_e32 v20, v30, v30
	v_add_f32_e32 v19, v19, v20
	v_and_b32_e32 v20, 64, v160
	v_add_f32_e32 v18, v18, v19
	v_xor_b32_e32 v19, 16, v160
	v_add_u32_e32 v21, 64, v20
	v_cmp_lt_i32_e32 vcc, v19, v21
	v_add_f32_e32 v18, v37, v18
	v_lshlrev_b64 v[38:39], 9, v[34:35]
	v_cndmask_b32_e32 v19, v160, v19, vcc
	v_lshlrev_b32_e32 v19, 2, v19
	v_mov_b32_e32 v19, v18
	s_nop 1
	v_permlane16_swap_b32_e32 v19, v18
	v_cvt_pk_bf16_f32 v28, v28, v29
	v_cvt_pk_bf16_f32 v29, v40, v41
	v_lshl_add_u64 v[36:37], v[140:141], 0, v[38:39]
	v_cvt_pk_bf16_f32 v20, v22, v23
	s_waitcnt lgkmcnt(0)
	v_add_f32_e32 v18, v18, v19
	v_xor_b32_e32 v19, 32, v160
	v_cmp_lt_i32_e32 vcc, v19, v21
	v_cvt_pk_bf16_f32 v21, v24, v25
	v_cvt_pk_bf16_f32 v22, v32, v33
	v_cndmask_b32_e32 v19, v160, v19, vcc
	v_lshlrev_b32_e32 v19, 2, v19
	v_mov_b32_e32 v19, v18
	s_nop 1
	v_permlane32_swap_b32_e32 v19, v18
	v_cvt_pk_bf16_f32 v23, v30, v31
	global_store_dwordx4 v[36:37], v[26:29], off
	global_store_dwordx4 v[36:37], v[20:23], off offset:256
	s_and_saveexec_b64 s[56:57], s[4:5]
	s_cbranch_execz .LBB0_1108
	v_lshl_add_u64 v[20:21], v[34:35], 2, s[24:25]
	s_waitcnt lgkmcnt(0)
	v_add_f32_e32 v18, v18, v19
	global_atomic_add_f32 v[20:21], v18, off

.LBB0_1114:
.LBB0_1115:
	v_pk_mul_f32 v[16:17], v[16:17], v[20:21] op_sel_hi:[1,0]
	v_pk_mul_f32 v[14:15], v[14:15], v[20:21] op_sel_hi:[1,0]
	v_pk_mul_f32 v[24:25], v[12:13], v[20:21] op_sel_hi:[1,0]
	v_pk_mul_f32 v[12:13], v[10:11], v[20:21] op_sel_hi:[1,0]
	v_mul_f32_e32 v10, v15, v15
	v_mul_f32_e32 v11, v17, v17
	v_fmac_f32_e32 v10, v14, v14
	v_fmac_f32_e32 v11, v16, v16
	v_add_f32_e32 v10, v10, v11
	v_mul_f32_e32 v11, v13, v13
	v_mul_f32_e32 v21, v25, v25
	v_fmac_f32_e32 v11, v12, v12
	v_fmac_f32_e32 v21, v24, v24
	v_add_f32_e32 v11, v11, v21
	v_add_f32_e32 v21, v10, v11
	v_pk_mul_f32 v[8:9], v[8:9], v[20:21] op_sel_hi:[1,0]
	v_pk_mul_f32 v[6:7], v[6:7], v[20:21] op_sel_hi:[1,0]
	v_cvt_pk_bf16_f32 v11, v16, v17
	v_pk_mul_f32 v[16:17], v[2:3], v[20:21] op_sel_hi:[1,0]
	v_mul_f32_e32 v2, v7, v7
	v_mul_f32_e32 v3, v9, v9
	v_cvt_pk_bf16_f32 v10, v14, v15
	v_pk_mul_f32 v[14:15], v[4:5], v[20:21] op_sel_hi:[1,0]
	v_fmac_f32_e32 v2, v6, v6
	v_fmac_f32_e32 v3, v8, v8
	v_add_f32_e32 v2, v2, v3
	v_mul_f32_e32 v3, v17, v17
	v_mul_f32_e32 v4, v15, v15
	v_fmac_f32_e32 v3, v16, v16
	v_fmac_f32_e32 v4, v14, v14
	v_add_f32_e32 v3, v3, v4
	v_and_b32_e32 v4, 64, v160
	v_add_f32_e32 v2, v2, v3
	v_xor_b32_e32 v3, 16, v160
	v_add_u32_e32 v5, 64, v4
	v_cmp_lt_i32_e32 vcc, v3, v5
	v_add_f32_e32 v2, v21, v2
	v_lshlrev_b64 v[22:23], 9, v[18:19]
	v_cndmask_b32_e32 v3, v160, v3, vcc
	v_lshlrev_b32_e32 v3, 2, v3
	v_mov_b32_e32 v3, v2
	s_nop 1
	v_permlane16_swap_b32_e32 v3, v2
	v_cvt_pk_bf16_f32 v12, v12, v13
	v_cvt_pk_bf16_f32 v13, v24, v25
	v_lshl_add_u64 v[20:21], v[140:141], 0, v[22:23]
	v_cvt_pk_bf16_f32 v4, v6, v7
	s_waitcnt lgkmcnt(0)
	v_add_f32_e32 v2, v2, v3
	v_xor_b32_e32 v3, 32, v160
	v_cmp_lt_i32_e32 vcc, v3, v5
	v_cvt_pk_bf16_f32 v5, v8, v9
	v_cvt_pk_bf16_f32 v6, v16, v17
	v_cndmask_b32_e32 v3, v160, v3, vcc
	v_lshlrev_b32_e32 v3, 2, v3
	v_mov_b32_e32 v3, v2
	s_nop 1
	v_permlane32_swap_b32_e32 v3, v2
	v_cvt_pk_bf16_f32 v7, v14, v15
	global_store_dwordx4 v[20:21], v[10:13], off
	global_store_dwordx4 v[20:21], v[4:7], off offset:256
	s_and_saveexec_b64 s[8:9], s[4:5]
	s_cbranch_execz .LBB0_1117
	v_lshl_add_u64 v[4:5], v[18:19], 2, s[24:25]
	s_waitcnt lgkmcnt(0)
	v_add_f32_e32 v2, v2, v3
	global_atomic_add_f32 v[4:5], v2, off

.LBB0_1360:
	v_lshl_add_u32 v148, s52, 8, v150
	v_ashrrev_i32_e32 v149, 31, v148
	v_lshl_add_u64 v[158:159], v[148:149], 2, s[12:13]
	global_load_dword v232, v[158:159], off offset:64
	global_load_dword v233, v[158:159], off offset:128
	global_load_dword v234, v[158:159], off offset:192
	global_load_dword v235, v[158:159], off offset:512
	global_load_dword v236, v[158:159], off offset:576
	global_load_dword v237, v[158:159], off offset:640
	global_load_dword v238, v[158:159], off offset:704
	global_load_dword v157, v[158:159], off
	v_and_b32_e32 v160, 64, v155
	v_xor_b32_e32 v162, 16, v155
	v_add_u32_e32 v164, 64, v160
	v_mov_b64_e32 v[158:159], s[14:15]
	v_cmp_lt_i32_e32 vcc, v162, v164
	v_mad_i64_i32 v[160:161], s[52:53], v148, s73, v[158:159]
	s_nop 0
	v_cndmask_b32_e32 v158, v155, v162, vcc
	v_xor_b32_e32 v163, 32, v155
	v_cmp_lt_i32_e32 vcc, v163, v164
	v_lshlrev_b32_e32 v158, 2, v158
	s_lshl_b32 s50, s50, 8
	s_ashr_i32 s51, s50, 31
	s_waitcnt vmcnt(0)
	v_fmamk_f32 v157, v157, 0x3a800000, v156
	v_rsq_f32_e32 v162, v157
	v_cndmask_b32_e32 v157, v155, v163, vcc
	v_lshlrev_b32_e32 v157, 2, v157
	v_pk_mul_f32 v[128:129], v[128:129], v[162:163] op_sel_hi:[1,0]
	v_pk_mul_f32 v[126:127], v[126:127], v[162:163] op_sel_hi:[1,0]
	v_pk_mul_f32 v[124:125], v[124:125], v[162:163] op_sel_hi:[1,0]
	v_pk_mul_f32 v[122:123], v[122:123], v[162:163] op_sel_hi:[1,0]
	v_pk_mul_f32 v[120:121], v[120:121], v[162:163] op_sel_hi:[1,0]
	v_pk_mul_f32 v[118:119], v[118:119], v[162:163] op_sel_hi:[1,0]
	v_pk_mul_f32 v[164:165], v[116:117], v[162:163] op_sel_hi:[1,0]
	v_pk_mul_f32 v[162:163], v[114:115], v[162:163] op_sel_hi:[1,0]
	v_mul_f32_e32 v159, v127, v127
	v_mul_f32_e32 v166, v129, v129
	v_mul_f32_e32 v167, v123, v123
	v_mul_f32_e32 v168, v125, v125
	v_cvt_pk_bf16_f32 v114, v126, v127
	v_cvt_pk_bf16_f32 v115, v128, v129
	v_cvt_pk_bf16_f32 v116, v122, v123
	v_cvt_pk_bf16_f32 v117, v124, v125
	v_mul_f32_e32 v123, v119, v119
	v_mul_f32_e32 v125, v121, v121
	v_mul_f32_e32 v127, v163, v163
	v_mul_f32_e32 v129, v165, v165
	v_fmac_f32_e32 v159, v126, v126
	v_fmac_f32_e32 v166, v128, v128
	v_fmac_f32_e32 v167, v122, v122
	v_fmac_f32_e32 v168, v124, v124
	v_fmac_f32_e32 v123, v118, v118
	v_fmac_f32_e32 v125, v120, v120
	v_fmac_f32_e32 v127, v162, v162
	v_fmac_f32_e32 v129, v164, v164
	v_add_f32_e32 v122, v159, v166
	v_add_f32_e32 v124, v167, v168
	v_add_f32_e32 v123, v123, v125
	v_add_f32_e32 v125, v127, v129
	v_add_f32_e32 v122, v122, v124
	v_add_f32_e32 v123, v123, v125
	v_add_f32_e32 v124, v122, v123
	v_mov_b32_e32 v125, v124
	s_nop 1
	v_permlane16_swap_b32_e32 v125, v124
	v_lshl_add_u64 v[122:123], s[50:51], 1, v[160:161]
	v_lshl_add_u64 v[122:123], v[122:123], 0, v[138:139]
	global_store_dwordx4 v[122:123], v[114:117], off
	s_waitcnt lgkmcnt(0)
	s_nop 0
	v_add_f32_e32 v114, v124, v125
	v_mov_b32_e32 v115, v114
	s_nop 1
	v_permlane32_swap_b32_e32 v115, v114
	v_cvt_pk_bf16_f32 v116, v118, v119
	v_cvt_pk_bf16_f32 v117, v120, v121
	v_cvt_pk_bf16_f32 v118, v162, v163
	v_cvt_pk_bf16_f32 v119, v164, v165
	global_store_dwordx4 v[122:123], v[116:119], off offset:256
	s_and_saveexec_b64 s[52:53], s[4:5]
	s_cbranch_execz .LBB0_1362
	v_lshl_add_u64 v[116:117], v[148:149], 2, s[16:17]
	s_waitcnt lgkmcnt(0)
	v_add_f32_e32 v114, v114, v115
	global_atomic_add_f32 v[116:117], v114, off
.LBB0_1362:
	s_or_b64 exec, exec, s[52:53]
	v_or_b32_e32 v114, 16, v148
	s_waitcnt lgkmcnt(0)
	v_ashrrev_i32_e32 v115, 31, v114
	v_mov_b64_e32 v[118:119], s[14:15]
	v_mad_i64_i32 v[118:119], s[52:53], v114, s73, v[118:119]
	v_fmamk_f32 v116, v232, 0x3a800000, v156
	v_rsq_f32_e32 v116, v116
	s_nop 0
	v_pk_mul_f32 v[112:113], v[112:113], v[116:117] op_sel_hi:[1,0]
	v_pk_mul_f32 v[110:111], v[110:111], v[116:117] op_sel_hi:[1,0]
	v_pk_mul_f32 v[108:109], v[108:109], v[116:117] op_sel_hi:[1,0]
	v_pk_mul_f32 v[106:107], v[106:107], v[116:117] op_sel_hi:[1,0]
	v_pk_mul_f32 v[104:105], v[104:105], v[116:117] op_sel_hi:[1,0]
	v_pk_mul_f32 v[102:103], v[102:103], v[116:117] op_sel_hi:[1,0]
	v_pk_mul_f32 v[120:121], v[100:101], v[116:117] op_sel_hi:[1,0]
	v_pk_mul_f32 v[116:117], v[98:99], v[116:117] op_sel_hi:[1,0]
	v_mul_f32_e32 v122, v111, v111
	v_mul_f32_e32 v123, v113, v113
	v_mul_f32_e32 v124, v107, v107
	v_mul_f32_e32 v125, v109, v109
	v_cvt_pk_bf16_f32 v98, v110, v111
	v_cvt_pk_bf16_f32 v99, v112, v113
	v_cvt_pk_bf16_f32 v100, v106, v107
	v_cvt_pk_bf16_f32 v101, v108, v109
	v_mul_f32_e32 v107, v103, v103
	v_mul_f32_e32 v109, v105, v105
	v_mul_f32_e32 v111, v117, v117
	v_mul_f32_e32 v113, v121, v121
	v_fmac_f32_e32 v122, v110, v110
	v_fmac_f32_e32 v123, v112, v112
	v_fmac_f32_e32 v124, v106, v106
	v_fmac_f32_e32 v125, v108, v108
	v_fmac_f32_e32 v107, v102, v102
	v_fmac_f32_e32 v109, v104, v104
	v_fmac_f32_e32 v111, v116, v116
	v_fmac_f32_e32 v113, v120, v120
	v_add_f32_e32 v106, v122, v123
	v_add_f32_e32 v108, v124, v125
	v_add_f32_e32 v107, v107, v109
	v_add_f32_e32 v109, v111, v113
	v_add_f32_e32 v106, v106, v108
	v_add_f32_e32 v107, v107, v109
	v_add_f32_e32 v108, v106, v107
	v_mov_b32_e32 v109, v108
	s_nop 1
	v_permlane16_swap_b32_e32 v109, v108
	v_lshl_add_u64 v[106:107], s[50:51], 1, v[118:119]
	v_lshl_add_u64 v[106:107], v[106:107], 0, v[138:139]
	global_store_dwordx4 v[106:107], v[98:101], off
	s_waitcnt lgkmcnt(0)
	s_nop 0
	v_add_f32_e32 v98, v108, v109
	v_mov_b32_e32 v99, v98
	s_nop 1
	v_permlane32_swap_b32_e32 v99, v98
	v_cvt_pk_bf16_f32 v100, v102, v103
	v_cvt_pk_bf16_f32 v101, v104, v105
	v_cvt_pk_bf16_f32 v102, v116, v117
	v_cvt_pk_bf16_f32 v103, v120, v121
	global_store_dwordx4 v[106:107], v[100:103], off offset:256
	s_and_saveexec_b64 s[52:53], s[4:5]
	s_cbranch_execz .LBB0_1364
	v_lshl_add_u64 v[100:101], v[114:115], 2, s[16:17]
	s_waitcnt lgkmcnt(0)
	v_add_f32_e32 v98, v98, v99
	global_atomic_add_f32 v[100:101], v98, off
.LBB0_1364:
	s_or_b64 exec, exec, s[52:53]
	v_or_b32_e32 v98, 32, v148
	s_waitcnt lgkmcnt(0)
	v_ashrrev_i32_e32 v99, 31, v98
	v_mov_b64_e32 v[102:103], s[14:15]
	v_mad_i64_i32 v[102:103], s[52:53], v98, s73, v[102:103]
	v_fmamk_f32 v100, v233, 0x3a800000, v156
	v_rsq_f32_e32 v100, v100
	s_nop 0
	v_pk_mul_f32 v[96:97], v[96:97], v[100:101] op_sel_hi:[1,0]
	v_pk_mul_f32 v[94:95], v[94:95], v[100:101] op_sel_hi:[1,0]
	v_pk_mul_f32 v[92:93], v[92:93], v[100:101] op_sel_hi:[1,0]
	v_pk_mul_f32 v[90:91], v[90:91], v[100:101] op_sel_hi:[1,0]
	v_pk_mul_f32 v[88:89], v[88:89], v[100:101] op_sel_hi:[1,0]
	v_pk_mul_f32 v[86:87], v[86:87], v[100:101] op_sel_hi:[1,0]
	v_pk_mul_f32 v[104:105], v[84:85], v[100:101] op_sel_hi:[1,0]
	v_pk_mul_f32 v[100:101], v[82:83], v[100:101] op_sel_hi:[1,0]
	v_mul_f32_e32 v106, v95, v95
	v_mul_f32_e32 v107, v97, v97
	v_mul_f32_e32 v108, v91, v91
	v_mul_f32_e32 v109, v93, v93
	v_cvt_pk_bf16_f32 v82, v94, v95
	v_cvt_pk_bf16_f32 v83, v96, v97
	v_cvt_pk_bf16_f32 v84, v90, v91
	v_cvt_pk_bf16_f32 v85, v92, v93
	v_mul_f32_e32 v91, v87, v87
	v_mul_f32_e32 v93, v89, v89
	v_mul_f32_e32 v95, v101, v101
	v_mul_f32_e32 v97, v105, v105
	v_fmac_f32_e32 v106, v94, v94
	v_fmac_f32_e32 v107, v96, v96
	v_fmac_f32_e32 v108, v90, v90
	v_fmac_f32_e32 v109, v92, v92
	v_fmac_f32_e32 v91, v86, v86
	v_fmac_f32_e32 v93, v88, v88
	v_fmac_f32_e32 v95, v100, v100
	v_fmac_f32_e32 v97, v104, v104
	v_add_f32_e32 v90, v106, v107
	v_add_f32_e32 v92, v108, v109
	v_add_f32_e32 v91, v91, v93
	v_add_f32_e32 v93, v95, v97
	v_add_f32_e32 v90, v90, v92
	v_add_f32_e32 v91, v91, v93
	v_add_f32_e32 v92, v90, v91
	v_mov_b32_e32 v93, v92
	s_nop 1
	v_permlane16_swap_b32_e32 v93, v92
	v_lshl_add_u64 v[90:91], s[50:51], 1, v[102:103]
	v_lshl_add_u64 v[90:91], v[90:91], 0, v[138:139]
	global_store_dwordx4 v[90:91], v[82:85], off
	s_waitcnt lgkmcnt(0)
	s_nop 0
	v_add_f32_e32 v82, v92, v93
	v_mov_b32_e32 v83, v82
	s_nop 1
	v_permlane32_swap_b32_e32 v83, v82
	v_cvt_pk_bf16_f32 v84, v86, v87
	v_cvt_pk_bf16_f32 v85, v88, v89
	v_cvt_pk_bf16_f32 v86, v100, v101
	v_cvt_pk_bf16_f32 v87, v104, v105
	global_store_dwordx4 v[90:91], v[84:87], off offset:256
	s_and_saveexec_b64 s[52:53], s[4:5]
	s_cbranch_execz .LBB0_1366
	v_lshl_add_u64 v[84:85], v[98:99], 2, s[16:17]
	s_waitcnt lgkmcnt(0)
	v_add_f32_e32 v82, v82, v83
	global_atomic_add_f32 v[84:85], v82, off
.LBB0_1366:
	s_or_b64 exec, exec, s[52:53]
	v_or_b32_e32 v82, 48, v148
	s_waitcnt lgkmcnt(0)
	v_ashrrev_i32_e32 v83, 31, v82
	v_mov_b64_e32 v[86:87], s[14:15]
	v_mad_i64_i32 v[86:87], s[52:53], v82, s73, v[86:87]
	v_fmamk_f32 v84, v234, 0x3a800000, v156
	v_rsq_f32_e32 v84, v84
	s_nop 0
	v_pk_mul_f32 v[80:81], v[80:81], v[84:85] op_sel_hi:[1,0]
	v_pk_mul_f32 v[78:79], v[78:79], v[84:85] op_sel_hi:[1,0]
	v_pk_mul_f32 v[76:77], v[76:77], v[84:85] op_sel_hi:[1,0]
	v_pk_mul_f32 v[74:75], v[74:75], v[84:85] op_sel_hi:[1,0]
	v_pk_mul_f32 v[72:73], v[72:73], v[84:85] op_sel_hi:[1,0]
	v_pk_mul_f32 v[70:71], v[70:71], v[84:85] op_sel_hi:[1,0]
	v_pk_mul_f32 v[88:89], v[68:69], v[84:85] op_sel_hi:[1,0]
	v_pk_mul_f32 v[84:85], v[66:67], v[84:85] op_sel_hi:[1,0]
	v_mul_f32_e32 v90, v79, v79
	v_mul_f32_e32 v91, v81, v81
	v_mul_f32_e32 v92, v75, v75
	v_mul_f32_e32 v93, v77, v77
	v_cvt_pk_bf16_f32 v66, v78, v79
	v_cvt_pk_bf16_f32 v67, v80, v81
	v_cvt_pk_bf16_f32 v68, v74, v75
	v_cvt_pk_bf16_f32 v69, v76, v77
	v_mul_f32_e32 v75, v71, v71
	v_mul_f32_e32 v77, v73, v73
	v_mul_f32_e32 v79, v85, v85
	v_mul_f32_e32 v81, v89, v89
	v_fmac_f32_e32 v90, v78, v78
	v_fmac_f32_e32 v91, v80, v80
	v_fmac_f32_e32 v92, v74, v74
	v_fmac_f32_e32 v93, v76, v76
	v_fmac_f32_e32 v75, v70, v70
	v_fmac_f32_e32 v77, v72, v72
	v_fmac_f32_e32 v79, v84, v84
	v_fmac_f32_e32 v81, v88, v88
	v_add_f32_e32 v74, v90, v91
	v_add_f32_e32 v76, v92, v93
	v_add_f32_e32 v75, v75, v77
	v_add_f32_e32 v77, v79, v81
	v_add_f32_e32 v74, v74, v76
	v_add_f32_e32 v75, v75, v77
	v_add_f32_e32 v76, v74, v75
	v_mov_b32_e32 v77, v76
	s_nop 1
	v_permlane16_swap_b32_e32 v77, v76
	v_lshl_add_u64 v[74:75], s[50:51], 1, v[86:87]
	v_lshl_add_u64 v[74:75], v[74:75], 0, v[138:139]
	global_store_dwordx4 v[74:75], v[66:69], off
	s_waitcnt lgkmcnt(0)
	s_nop 0
	v_add_f32_e32 v66, v76, v77
	v_mov_b32_e32 v67, v66
	s_nop 1
	v_permlane32_swap_b32_e32 v67, v66
	v_cvt_pk_bf16_f32 v68, v70, v71
	v_cvt_pk_bf16_f32 v69, v72, v73
	v_cvt_pk_bf16_f32 v70, v84, v85
	v_cvt_pk_bf16_f32 v71, v88, v89
	global_store_dwordx4 v[74:75], v[68:71], off offset:256
	s_and_saveexec_b64 s[52:53], s[4:5]
	s_cbranch_execz .LBB0_1368
	v_lshl_add_u64 v[68:69], v[82:83], 2, s[16:17]
	s_waitcnt lgkmcnt(0)
	v_add_f32_e32 v66, v66, v67
	global_atomic_add_f32 v[68:69], v66, off
.LBB0_1368:
	s_or_b64 exec, exec, s[52:53]
	v_add_u32_e32 v66, 0x80, v148
	s_waitcnt lgkmcnt(0)
	v_ashrrev_i32_e32 v67, 31, v66
	v_mov_b64_e32 v[70:71], s[14:15]
	v_mad_i64_i32 v[70:71], s[52:53], v66, s73, v[70:71]
	v_fmamk_f32 v68, v235, 0x3a800000, v156
	v_rsq_f32_e32 v68, v68
	s_nop 0
	v_pk_mul_f32 v[64:65], v[64:65], v[68:69] op_sel_hi:[1,0]
	v_pk_mul_f32 v[62:63], v[62:63], v[68:69] op_sel_hi:[1,0]
	v_pk_mul_f32 v[60:61], v[60:61], v[68:69] op_sel_hi:[1,0]
	v_pk_mul_f32 v[58:59], v[58:59], v[68:69] op_sel_hi:[1,0]
	v_pk_mul_f32 v[56:57], v[56:57], v[68:69] op_sel_hi:[1,0]
	v_pk_mul_f32 v[54:55], v[54:55], v[68:69] op_sel_hi:[1,0]
	v_pk_mul_f32 v[72:73], v[52:53], v[68:69] op_sel_hi:[1,0]
	v_pk_mul_f32 v[68:69], v[50:51], v[68:69] op_sel_hi:[1,0]
	v_mul_f32_e32 v74, v63, v63
	v_mul_f32_e32 v75, v65, v65
	v_mul_f32_e32 v76, v59, v59
	v_mul_f32_e32 v77, v61, v61
	v_cvt_pk_bf16_f32 v50, v62, v63
	v_cvt_pk_bf16_f32 v51, v64, v65
	v_cvt_pk_bf16_f32 v52, v58, v59
	v_cvt_pk_bf16_f32 v53, v60, v61
	v_mul_f32_e32 v59, v55, v55
	v_mul_f32_e32 v61, v57, v57
	v_mul_f32_e32 v63, v69, v69
	v_mul_f32_e32 v65, v73, v73
	v_fmac_f32_e32 v74, v62, v62
	v_fmac_f32_e32 v75, v64, v64
	v_fmac_f32_e32 v76, v58, v58
	v_fmac_f32_e32 v77, v60, v60
	v_fmac_f32_e32 v59, v54, v54
	v_fmac_f32_e32 v61, v56, v56
	v_fmac_f32_e32 v63, v68, v68
	v_fmac_f32_e32 v65, v72, v72
	v_add_f32_e32 v58, v74, v75
	v_add_f32_e32 v60, v76, v77
	v_add_f32_e32 v59, v59, v61
	v_add_f32_e32 v61, v63, v65
	v_add_f32_e32 v58, v58, v60
	v_add_f32_e32 v59, v59, v61
	v_add_f32_e32 v60, v58, v59
	v_mov_b32_e32 v61, v60
	s_nop 1
	v_permlane16_swap_b32_e32 v61, v60
	v_lshl_add_u64 v[58:59], s[50:51], 1, v[70:71]
	v_lshl_add_u64 v[58:59], v[58:59], 0, v[138:139]
	global_store_dwordx4 v[58:59], v[50:53], off
	s_waitcnt lgkmcnt(0)
	s_nop 0
	v_add_f32_e32 v50, v60, v61
	v_mov_b32_e32 v51, v50
	s_nop 1
	v_permlane32_swap_b32_e32 v51, v50
	v_cvt_pk_bf16_f32 v52, v54, v55
	v_cvt_pk_bf16_f32 v53, v56, v57
	v_cvt_pk_bf16_f32 v54, v68, v69
	v_cvt_pk_bf16_f32 v55, v72, v73
	global_store_dwordx4 v[58:59], v[52:55], off offset:256
	s_and_saveexec_b64 s[52:53], s[4:5]
	s_cbranch_execz .LBB0_1370
	v_lshl_add_u64 v[52:53], v[66:67], 2, s[16:17]
	s_waitcnt lgkmcnt(0)
	v_add_f32_e32 v50, v50, v51
	global_atomic_add_f32 v[52:53], v50, off
.LBB0_1370:
	s_or_b64 exec, exec, s[52:53]
	v_add_u32_e32 v50, 0x90, v148
	s_waitcnt lgkmcnt(0)
	v_ashrrev_i32_e32 v51, 31, v50
	v_mov_b64_e32 v[54:55], s[14:15]
	v_mad_i64_i32 v[54:55], s[52:53], v50, s73, v[54:55]
	v_fmamk_f32 v52, v236, 0x3a800000, v156
	v_rsq_f32_e32 v52, v52
	s_nop 0
	v_pk_mul_f32 v[48:49], v[48:49], v[52:53] op_sel_hi:[1,0]
	v_pk_mul_f32 v[46:47], v[46:47], v[52:53] op_sel_hi:[1,0]
	v_pk_mul_f32 v[44:45], v[44:45], v[52:53] op_sel_hi:[1,0]
	v_pk_mul_f32 v[42:43], v[42:43], v[52:53] op_sel_hi:[1,0]
	v_pk_mul_f32 v[40:41], v[40:41], v[52:53] op_sel_hi:[1,0]
	v_pk_mul_f32 v[38:39], v[38:39], v[52:53] op_sel_hi:[1,0]
	v_pk_mul_f32 v[56:57], v[36:37], v[52:53] op_sel_hi:[1,0]
	v_pk_mul_f32 v[52:53], v[34:35], v[52:53] op_sel_hi:[1,0]
	v_mul_f32_e32 v58, v47, v47
	v_mul_f32_e32 v59, v49, v49
	v_mul_f32_e32 v60, v43, v43
	v_mul_f32_e32 v61, v45, v45
	v_cvt_pk_bf16_f32 v34, v46, v47
	v_cvt_pk_bf16_f32 v35, v48, v49
	v_cvt_pk_bf16_f32 v36, v42, v43
	v_cvt_pk_bf16_f32 v37, v44, v45
	v_mul_f32_e32 v43, v39, v39
	v_mul_f32_e32 v45, v41, v41
	v_mul_f32_e32 v47, v53, v53
	v_mul_f32_e32 v49, v57, v57
	v_fmac_f32_e32 v58, v46, v46
	v_fmac_f32_e32 v59, v48, v48
	v_fmac_f32_e32 v60, v42, v42
	v_fmac_f32_e32 v61, v44, v44
	v_fmac_f32_e32 v43, v38, v38
	v_fmac_f32_e32 v45, v40, v40
	v_fmac_f32_e32 v47, v52, v52
	v_fmac_f32_e32 v49, v56, v56
	v_add_f32_e32 v42, v58, v59
	v_add_f32_e32 v44, v60, v61
	v_add_f32_e32 v43, v43, v45
	v_add_f32_e32 v45, v47, v49
	v_add_f32_e32 v42, v42, v44
	v_add_f32_e32 v43, v43, v45
	v_add_f32_e32 v44, v42, v43
	v_mov_b32_e32 v45, v44
	s_nop 1
	v_permlane16_swap_b32_e32 v45, v44
	v_lshl_add_u64 v[42:43], s[50:51], 1, v[54:55]
	v_lshl_add_u64 v[42:43], v[42:43], 0, v[138:139]
	global_store_dwordx4 v[42:43], v[34:37], off
	s_waitcnt lgkmcnt(0)
	s_nop 0
	v_add_f32_e32 v34, v44, v45
	v_mov_b32_e32 v35, v34
	s_nop 1
	v_permlane32_swap_b32_e32 v35, v34
	v_cvt_pk_bf16_f32 v36, v38, v39
	v_cvt_pk_bf16_f32 v37, v40, v41
	v_cvt_pk_bf16_f32 v38, v52, v53
	v_cvt_pk_bf16_f32 v39, v56, v57
	global_store_dwordx4 v[42:43], v[36:39], off offset:256
	s_and_saveexec_b64 s[52:53], s[4:5]
	s_cbranch_execz .LBB0_1372
	v_lshl_add_u64 v[36:37], v[50:51], 2, s[16:17]
	s_waitcnt lgkmcnt(0)
	v_add_f32_e32 v34, v34, v35
	global_atomic_add_f32 v[36:37], v34, off
.LBB0_1372:
	s_or_b64 exec, exec, s[52:53]
	v_add_u32_e32 v34, 0xa0, v148
	s_waitcnt lgkmcnt(0)
	v_ashrrev_i32_e32 v35, 31, v34
	v_mov_b64_e32 v[38:39], s[14:15]
	v_mad_i64_i32 v[38:39], s[52:53], v34, s73, v[38:39]
	v_fmamk_f32 v36, v237, 0x3a800000, v156
	v_rsq_f32_e32 v36, v36
	s_nop 0
	v_pk_mul_f32 v[32:33], v[32:33], v[36:37] op_sel_hi:[1,0]
	v_pk_mul_f32 v[30:31], v[30:31], v[36:37] op_sel_hi:[1,0]
	v_pk_mul_f32 v[28:29], v[28:29], v[36:37] op_sel_hi:[1,0]
	v_pk_mul_f32 v[26:27], v[26:27], v[36:37] op_sel_hi:[1,0]
	v_pk_mul_f32 v[24:25], v[24:25], v[36:37] op_sel_hi:[1,0]
	v_pk_mul_f32 v[22:23], v[22:23], v[36:37] op_sel_hi:[1,0]
	v_pk_mul_f32 v[40:41], v[20:21], v[36:37] op_sel_hi:[1,0]
	v_pk_mul_f32 v[36:37], v[18:19], v[36:37] op_sel_hi:[1,0]
	v_mul_f32_e32 v42, v31, v31
	v_mul_f32_e32 v43, v33, v33
	v_mul_f32_e32 v44, v27, v27
	v_mul_f32_e32 v45, v29, v29
	v_cvt_pk_bf16_f32 v18, v30, v31
	v_cvt_pk_bf16_f32 v19, v32, v33
	v_cvt_pk_bf16_f32 v20, v26, v27
	v_cvt_pk_bf16_f32 v21, v28, v29
	v_mul_f32_e32 v27, v23, v23
	v_mul_f32_e32 v29, v25, v25
	v_mul_f32_e32 v31, v37, v37
	v_mul_f32_e32 v33, v41, v41
	v_fmac_f32_e32 v42, v30, v30
	v_fmac_f32_e32 v43, v32, v32
	v_fmac_f32_e32 v44, v26, v26
	v_fmac_f32_e32 v45, v28, v28
	v_fmac_f32_e32 v27, v22, v22
	v_fmac_f32_e32 v29, v24, v24
	v_fmac_f32_e32 v31, v36, v36
	v_fmac_f32_e32 v33, v40, v40
	v_add_f32_e32 v26, v42, v43
	v_add_f32_e32 v28, v44, v45
	v_add_f32_e32 v27, v27, v29
	v_add_f32_e32 v29, v31, v33
	v_add_f32_e32 v26, v26, v28
	v_add_f32_e32 v27, v27, v29
	v_add_f32_e32 v28, v26, v27
	v_mov_b32_e32 v29, v28
	s_nop 1
	v_permlane16_swap_b32_e32 v29, v28
	v_lshl_add_u64 v[26:27], s[50:51], 1, v[38:39]
	v_lshl_add_u64 v[26:27], v[26:27], 0, v[138:139]
	global_store_dwordx4 v[26:27], v[18:21], off
	s_waitcnt lgkmcnt(0)
	s_nop 0
	v_add_f32_e32 v18, v28, v29
	v_mov_b32_e32 v19, v18
	s_nop 1
	v_permlane32_swap_b32_e32 v19, v18
	v_cvt_pk_bf16_f32 v20, v22, v23
	v_cvt_pk_bf16_f32 v21, v24, v25
	v_cvt_pk_bf16_f32 v22, v36, v37
	v_cvt_pk_bf16_f32 v23, v40, v41
	global_store_dwordx4 v[26:27], v[20:23], off offset:256
	s_and_saveexec_b64 s[52:53], s[4:5]
	s_cbranch_execz .LBB0_1374
	v_lshl_add_u64 v[20:21], v[34:35], 2, s[16:17]
	s_waitcnt lgkmcnt(0)
	v_add_f32_e32 v18, v18, v19
	global_atomic_add_f32 v[20:21], v18, off
.LBB0_1374:
	s_or_b64 exec, exec, s[52:53]
	v_add_u32_e32 v18, 0xb0, v148
	s_waitcnt lgkmcnt(0)
	v_ashrrev_i32_e32 v19, 31, v18
	v_mov_b64_e32 v[22:23], s[14:15]
	v_mad_i64_i32 v[22:23], s[52:53], v18, s73, v[22:23]
	v_fmamk_f32 v20, v238, 0x3a800000, v156
	v_rsq_f32_e32 v20, v20
	s_nop 0
	v_pk_mul_f32 v[16:17], v[16:17], v[20:21] op_sel_hi:[1,0]
	v_pk_mul_f32 v[14:15], v[14:15], v[20:21] op_sel_hi:[1,0]
	v_pk_mul_f32 v[12:13], v[12:13], v[20:21] op_sel_hi:[1,0]
	v_pk_mul_f32 v[10:11], v[10:11], v[20:21] op_sel_hi:[1,0]
	v_pk_mul_f32 v[8:9], v[8:9], v[20:21] op_sel_hi:[1,0]
	v_pk_mul_f32 v[6:7], v[6:7], v[20:21] op_sel_hi:[1,0]
	v_pk_mul_f32 v[24:25], v[4:5], v[20:21] op_sel_hi:[1,0]
	v_pk_mul_f32 v[20:21], v[2:3], v[20:21] op_sel_hi:[1,0]
	v_mul_f32_e32 v26, v15, v15
	v_mul_f32_e32 v27, v17, v17
	v_mul_f32_e32 v28, v11, v11
	v_mul_f32_e32 v29, v13, v13
	v_cvt_pk_bf16_f32 v2, v14, v15
	v_cvt_pk_bf16_f32 v3, v16, v17
	v_cvt_pk_bf16_f32 v4, v10, v11
	v_cvt_pk_bf16_f32 v5, v12, v13
	v_mul_f32_e32 v11, v7, v7
	v_mul_f32_e32 v13, v9, v9
	v_mul_f32_e32 v15, v21, v21
	v_mul_f32_e32 v17, v25, v25
	v_fmac_f32_e32 v26, v14, v14
	v_fmac_f32_e32 v27, v16, v16
	v_fmac_f32_e32 v28, v10, v10
	v_fmac_f32_e32 v29, v12, v12
	v_fmac_f32_e32 v11, v6, v6
	v_fmac_f32_e32 v13, v8, v8
	v_fmac_f32_e32 v15, v20, v20
	v_fmac_f32_e32 v17, v24, v24
	v_add_f32_e32 v10, v26, v27
	v_add_f32_e32 v12, v28, v29
	v_add_f32_e32 v11, v11, v13
	v_add_f32_e32 v13, v15, v17
	v_add_f32_e32 v10, v10, v12
	v_add_f32_e32 v11, v11, v13
	v_add_f32_e32 v12, v10, v11
	v_mov_b32_e32 v13, v12
	s_nop 1
	v_permlane16_swap_b32_e32 v13, v12
	v_lshl_add_u64 v[10:11], s[50:51], 1, v[22:23]
	v_lshl_add_u64 v[10:11], v[10:11], 0, v[138:139]
	global_store_dwordx4 v[10:11], v[2:5], off
	s_waitcnt lgkmcnt(0)
	s_nop 0
	v_add_f32_e32 v2, v12, v13
	v_mov_b32_e32 v3, v2
	s_nop 1
	v_permlane32_swap_b32_e32 v3, v2
	v_cvt_pk_bf16_f32 v4, v6, v7
	v_cvt_pk_bf16_f32 v5, v8, v9
	v_cvt_pk_bf16_f32 v6, v20, v21
	v_cvt_pk_bf16_f32 v7, v24, v25
	global_store_dwordx4 v[10:11], v[4:7], off offset:256
	s_and_saveexec_b64 s[50:51], s[4:5]
	s_cbranch_execz .LBB0_1376
	v_lshl_add_u64 v[4:5], v[18:19], 2, s[16:17]
	s_waitcnt lgkmcnt(0)
	v_add_f32_e32 v2, v2, v3
	global_atomic_add_f32 v[4:5], v2, off

.LBB0_1597:
	v_mov_b32_e32 v68, v234
	s_nop 1
	v_permlane32_swap_b32_e32 v68, v234
	v_lshl_add_u64 v[66:67], s[46:47], 0, v[200:201]
	v_lshl_add_u64 v[66:67], s[54:55], 1, v[66:67]
	v_lshl_add_u64 v[66:67], v[66:67], 0, v[166:167]
	s_add_i32 s23, s23, s38
	s_waitcnt lgkmcnt(0)
	v_add_f32_e32 v68, v234, v68
	v_div_scale_f32 v69, s[54:55], v68, v68, 1.0
	v_rcp_f32_e32 v70, v69
	v_div_scale_f32 v71, vcc, 1.0, v68, 1.0
	s_cmpk_gt_i32 s23, 0x3ff
	v_fma_f32 v72, -v69, v70, 1.0
	v_fmac_f32_e32 v70, v72, v70
	v_mul_f32_e32 v72, v71, v70
	v_fma_f32 v73, -v69, v72, v71
	v_fmac_f32_e32 v72, v73, v70
	v_fma_f32 v69, -v69, v72, v71
	v_div_fmas_f32 v69, v69, v70, v72
	v_div_fixup_f32 v68, v69, v68, 1.0
	v_pk_mul_f32 v[50:51], v[50:51], v[68:69] op_sel_hi:[1,0]
	v_pk_mul_f32 v[52:53], v[52:53], v[68:69] op_sel_hi:[1,0]
	v_pk_mul_f32 v[34:35], v[34:35], v[68:69] op_sel_hi:[1,0]
	v_pk_mul_f32 v[36:37], v[36:37], v[68:69] op_sel_hi:[1,0]
	v_pk_mul_f32 v[18:19], v[18:19], v[68:69] op_sel_hi:[1,0]
	v_pk_mul_f32 v[20:21], v[20:21], v[68:69] op_sel_hi:[1,0]
	v_pk_mul_f32 v[2:3], v[2:3], v[68:69] op_sel_hi:[1,0]
	v_pk_mul_f32 v[4:5], v[4:5], v[68:69] op_sel_hi:[1,0]
	v_cvt_pk_bf16_f32 v50, v50, v51
	v_cvt_pk_bf16_f32 v51, v52, v53
	v_pk_mul_f32 v[52:53], v[54:55], v[68:69] op_sel_hi:[1,0]
	v_pk_mul_f32 v[54:55], v[56:57], v[68:69] op_sel_hi:[1,0]
	v_cvt_pk_bf16_f32 v34, v34, v35
	v_cvt_pk_bf16_f32 v35, v36, v37
	v_pk_mul_f32 v[36:37], v[38:39], v[68:69] op_sel_hi:[1,0]
	v_pk_mul_f32 v[38:39], v[40:41], v[68:69] op_sel_hi:[1,0]
	v_cvt_pk_bf16_f32 v18, v18, v19
	v_cvt_pk_bf16_f32 v19, v20, v21
	v_pk_mul_f32 v[20:21], v[22:23], v[68:69] op_sel_hi:[1,0]
	v_pk_mul_f32 v[22:23], v[24:25], v[68:69] op_sel_hi:[1,0]
	v_cvt_pk_bf16_f32 v2, v2, v3
	v_cvt_pk_bf16_f32 v3, v4, v5
	v_pk_mul_f32 v[4:5], v[6:7], v[68:69] op_sel_hi:[1,0]
	v_pk_mul_f32 v[6:7], v[8:9], v[68:69] op_sel_hi:[1,0]
	v_cvt_pk_bf16_f32 v52, v52, v53
	v_cvt_pk_bf16_f32 v53, v54, v55
	v_cvt_pk_bf16_f32 v36, v36, v37
	v_cvt_pk_bf16_f32 v37, v38, v39
	v_cvt_pk_bf16_f32 v20, v20, v21
	v_cvt_pk_bf16_f32 v21, v22, v23
	v_cvt_pk_bf16_f32 v4, v4, v5
	v_cvt_pk_bf16_f32 v5, v6, v7
	v_permlane32_swap_b32_e32 v50, v52
	v_permlane32_swap_b32_e32 v51, v53
	v_permlane32_swap_b32_e32 v34, v36
	v_permlane32_swap_b32_e32 v35, v37
	v_permlane32_swap_b32_e32 v18, v20
	v_permlane32_swap_b32_e32 v19, v21
	v_permlane32_swap_b32_e32 v2, v4
	v_permlane32_swap_b32_e32 v3, v5
	global_store_dwordx4 v[66:67], v[50:53], off
	global_store_dwordx4 v[66:67], v[34:37], off offset:64
	global_store_dwordx4 v[66:67], v[18:21], off offset:128
	v_pk_mul_f32 v[50:51], v[58:59], v[68:69] op_sel_hi:[1,0]
	v_pk_mul_f32 v[52:53], v[60:61], v[68:69] op_sel_hi:[1,0]
	v_pk_mul_f32 v[34:35], v[42:43], v[68:69] op_sel_hi:[1,0]
	v_pk_mul_f32 v[36:37], v[44:45], v[68:69] op_sel_hi:[1,0]
	v_pk_mul_f32 v[18:19], v[26:27], v[68:69] op_sel_hi:[1,0]
	v_pk_mul_f32 v[20:21], v[28:29], v[68:69] op_sel_hi:[1,0]
	global_store_dwordx4 v[66:67], v[2:5], off offset:192
	v_cvt_pk_bf16_f32 v50, v50, v51
	v_cvt_pk_bf16_f32 v51, v52, v53
	v_pk_mul_f32 v[2:3], v[10:11], v[68:69] op_sel_hi:[1,0]
	v_pk_mul_f32 v[4:5], v[12:13], v[68:69] op_sel_hi:[1,0]
	v_pk_mul_f32 v[52:53], v[62:63], v[68:69] op_sel_hi:[1,0]
	v_pk_mul_f32 v[54:55], v[64:65], v[68:69] op_sel_hi:[1,0]
	v_cvt_pk_bf16_f32 v34, v34, v35
	v_cvt_pk_bf16_f32 v35, v36, v37
	v_pk_mul_f32 v[36:37], v[46:47], v[68:69] op_sel_hi:[1,0]
	v_pk_mul_f32 v[38:39], v[48:49], v[68:69] op_sel_hi:[1,0]
	v_cvt_pk_bf16_f32 v18, v18, v19
	v_cvt_pk_bf16_f32 v19, v20, v21
	v_pk_mul_f32 v[20:21], v[30:31], v[68:69] op_sel_hi:[1,0]
	v_pk_mul_f32 v[22:23], v[32:33], v[68:69] op_sel_hi:[1,0]
	v_cvt_pk_bf16_f32 v2, v2, v3
	v_cvt_pk_bf16_f32 v3, v4, v5
	v_pk_mul_f32 v[4:5], v[14:15], v[68:69] op_sel_hi:[1,0]
	v_pk_mul_f32 v[6:7], v[16:17], v[68:69] op_sel_hi:[1,0]
	v_cvt_pk_bf16_f32 v52, v52, v53
	v_cvt_pk_bf16_f32 v53, v54, v55
	v_cvt_pk_bf16_f32 v36, v36, v37
	v_cvt_pk_bf16_f32 v37, v38, v39
	v_cvt_pk_bf16_f32 v20, v20, v21
	v_cvt_pk_bf16_f32 v21, v22, v23
	v_cvt_pk_bf16_f32 v4, v4, v5
	v_cvt_pk_bf16_f32 v5, v6, v7
	v_permlane32_swap_b32_e32 v50, v52
	v_permlane32_swap_b32_e32 v51, v53
	v_permlane32_swap_b32_e32 v34, v36
	v_permlane32_swap_b32_e32 v35, v37
	v_permlane32_swap_b32_e32 v18, v20
	v_permlane32_swap_b32_e32 v19, v21
	v_permlane32_swap_b32_e32 v2, v4
	v_permlane32_swap_b32_e32 v3, v5
	global_store_dwordx4 v[66:67], v[50:53], off offset:32
	global_store_dwordx4 v[66:67], v[34:37], off offset:96
	global_store_dwordx4 v[66:67], v[18:21], off offset:160
	global_store_dwordx4 v[66:67], v[2:5], off offset:224
	s_barrier
	s_cbranch_scc1 .LBB0_1621

.LBB0_1912:
	v_lshl_add_u32 v222, s67, 8, v195
	s_lshl_b32 s44, s68, 8
	s_ashr_i32 s45, s44, 31
	v_ashrrev_i32_e32 v223, 31, v222
	v_lshl_add_u64 v[114:115], s[44:45], 1, v[196:197]
	v_lshlrev_b64 v[116:117], 11, v[222:223]
	v_lshl_add_u64 v[116:117], v[114:115], 0, v[116:117]
	global_load_dwordx4 v[230:233], v[116:117], off
	global_load_dwordx4 v[234:237], v[116:117], off offset:256
	v_or_b32_e32 v220, 16, v222
	v_or_b32_e32 v218, 32, v222
	v_or_b32_e32 v216, 48, v222
	v_add_u32_e32 v214, 0x80, v222
	v_add_u32_e32 v212, 0x90, v222
	v_add_u32_e32 v210, 0xa0, v222
	v_add_u32_e32 v206, 0xb0, v222
	v_ashrrev_i32_e32 v221, 31, v220
	v_ashrrev_i32_e32 v219, 31, v218
	v_ashrrev_i32_e32 v217, 31, v216
	v_ashrrev_i32_e32 v215, 31, v214
	v_ashrrev_i32_e32 v213, 31, v212
	v_ashrrev_i32_e32 v211, 31, v210
	v_ashrrev_i32_e32 v207, 31, v206
	v_lshlrev_b64 v[116:117], 11, v[220:221]
	v_lshlrev_b64 v[126:127], 11, v[218:219]
	v_lshlrev_b64 v[128:129], 11, v[216:217]
	v_lshlrev_b64 v[138:139], 11, v[214:215]
	v_lshlrev_b64 v[140:141], 11, v[212:213]
	v_lshlrev_b64 v[142:143], 11, v[210:211]
	v_lshlrev_b64 v[144:145], 11, v[206:207]
	v_lshl_add_u64 v[116:117], v[114:115], 0, v[116:117]
	v_lshl_add_u64 v[126:127], v[114:115], 0, v[126:127]
	v_lshl_add_u64 v[128:129], v[114:115], 0, v[128:129]
	v_lshl_add_u64 v[138:139], v[114:115], 0, v[138:139]
	v_lshl_add_u64 v[140:141], v[114:115], 0, v[140:141]
	v_lshl_add_u64 v[208:209], v[114:115], 0, v[142:143]
	v_lshl_add_u64 v[114:115], v[114:115], 0, v[144:145]
	global_load_dwordx4 v[182:185], v[116:117], off
	global_load_dwordx4 v[178:181], v[116:117], off offset:256
	global_load_dwordx4 v[174:177], v[126:127], off
	global_load_dwordx4 v[170:173], v[126:127], off offset:256
	global_load_dwordx4 v[166:169], v[128:129], off
	global_load_dwordx4 v[162:165], v[128:129], off offset:256
	global_load_dwordx4 v[158:161], v[138:139], off
	global_load_dwordx4 v[154:157], v[138:139], off offset:256
	global_load_dwordx4 v[150:153], v[140:141], off
	global_load_dwordx4 v[146:149], v[140:141], off offset:256
	global_load_dwordx4 v[142:145], v[208:209], off
	s_nop 0
	global_load_dwordx4 v[138:141], v[208:209], off offset:256
	global_load_dwordx4 v[126:129], v[114:115], off
	s_nop 0
	global_load_dwordx4 v[114:117], v[114:115], off offset:256
	v_and_b32_e32 v209, 64, v228
	v_xor_b32_e32 v229, 16, v228
	v_add_u32_e32 v239, 64, v209
	v_xor_b32_e32 v238, 32, v228
	v_cmp_lt_i32_e32 vcc, v229, v239
	v_or_b32_e32 v208, s44, v194
	v_mov_b32_e32 v209, s45
	v_cndmask_b32_e32 v229, v228, v229, vcc
	v_cmp_lt_i32_e32 vcc, v238, v239
	v_lshlrev_b32_e32 v229, 2, v229
	s_waitcnt vmcnt(0)
	v_and_b32_e32 v239, 0xffff0000, v230
	v_cndmask_b32_e32 v243, v228, v238, vcc
	v_lshlrev_b32_e32 v238, 16, v230
	v_lshlrev_b32_e32 v230, 16, v231
	v_and_b32_e32 v231, 0xffff0000, v231
	v_lshlrev_b32_e32 v240, 16, v232
	v_and_b32_e32 v241, 0xffff0000, v232
	v_lshlrev_b32_e32 v232, 16, v233
	v_and_b32_e32 v233, 0xffff0000, v233
	v_pk_fma_f32 v[136:137], v[136:137], 0.5, v[230:231] op_sel_hi:[1,0,1]
	v_pk_fma_f32 v[134:135], v[134:135], 0.5, v[238:239] op_sel_hi:[1,0,1]
	v_pk_fma_f32 v[132:133], v[132:133], 0.5, v[232:233] op_sel_hi:[1,0,1]
	v_pk_fma_f32 v[130:131], v[130:131], 0.5, v[240:241] op_sel_hi:[1,0,1]
	v_mul_f32_e32 v230, v135, v135
	v_mul_f32_e32 v231, v137, v137
	v_mul_f32_e32 v232, v131, v131
	v_mul_f32_e32 v233, v133, v133
	v_fmac_f32_e32 v230, v134, v134
	v_fmac_f32_e32 v231, v136, v136
	v_fmac_f32_e32 v232, v130, v130
	v_fmac_f32_e32 v233, v132, v132
	v_lshlrev_b32_e32 v244, 16, v234
	v_and_b32_e32 v245, 0xffff0000, v234
	v_lshlrev_b32_e32 v234, 16, v235
	v_and_b32_e32 v235, 0xffff0000, v235
	v_add_f32_e32 v230, v230, v231
	v_add_f32_e32 v231, v232, v233
	v_lshlrev_b32_e32 v246, 16, v236
	v_add_f32_e32 v238, v230, v231
	v_and_b32_e32 v247, 0xffff0000, v236
	v_lshlrev_b32_e32 v230, 16, v237
	v_and_b32_e32 v231, 0xffff0000, v237
	v_pk_fma_f32 v[124:125], v[124:125], 0.5, v[234:235] op_sel_hi:[1,0,1]
	v_pk_fma_f32 v[122:123], v[122:123], 0.5, v[244:245] op_sel_hi:[1,0,1]
	v_pk_fma_f32 v[232:233], v[120:121], 0.5, v[230:231] op_sel_hi:[1,0,1]
	v_pk_fma_f32 v[230:231], v[118:119], 0.5, v[246:247] op_sel_hi:[1,0,1]
	v_mul_f32_e32 v118, v123, v123
	v_mul_f32_e32 v119, v125, v125
	v_fmac_f32_e32 v118, v122, v122
	v_fmac_f32_e32 v119, v124, v124
	v_add_f32_e32 v118, v118, v119
	v_mul_f32_e32 v119, v231, v231
	v_mul_f32_e32 v120, v233, v233
	v_fmac_f32_e32 v119, v230, v230
	v_fmac_f32_e32 v120, v232, v232
	v_add_f32_e32 v119, v119, v120
	v_add_f32_e32 v118, v118, v119
	v_add_f32_e32 v119, v238, v118
	v_mov_b32_e32 v236, v119
	s_nop 1
	v_permlane16_swap_b32_e32 v236, v119
	v_lshlrev_b64 v[120:121], 12, v[222:223]
	v_lshlrev_b32_e32 v118, 2, v243
	v_lshl_add_u64 v[120:121], s[12:13], 0, v[120:121]
	v_lshl_add_u64 v[234:235], v[208:209], 2, v[120:121]
	s_waitcnt lgkmcnt(0)
	v_add_f32_e32 v119, v119, v236
	v_mov_b32_e32 v120, v119
	s_nop 1
	v_permlane32_swap_b32_e32 v120, v119
	global_store_dwordx4 v[234:235], v[134:137], off
	global_store_dwordx4 v[234:235], v[130:133], off offset:16
	global_store_dwordx4 v[234:235], v[122:125], off offset:512
	global_store_dwordx4 v[234:235], v[230:233], off offset:528
	s_and_saveexec_b64 s[44:45], s[4:5]
	s_cbranch_execz .LBB0_1914
	v_lshl_add_u64 v[122:123], v[222:223], 2, s[16:17]
	s_waitcnt lgkmcnt(0)
	v_add_f32_e32 v119, v119, v120
	global_atomic_add_f32 v[122:123], v119, off
.LBB0_1914:
	s_or_b64 exec, exec, s[44:45]
	s_waitcnt lgkmcnt(0)
	v_lshlrev_b32_e32 v120, 16, v182
	v_and_b32_e32 v121, 0xffff0000, v182
	v_lshlrev_b32_e32 v122, 16, v183
	v_and_b32_e32 v123, 0xffff0000, v183
	v_pk_fma_f32 v[112:113], v[112:113], 0.5, v[122:123] op_sel_hi:[1,0,1]
	v_pk_fma_f32 v[110:111], v[110:111], 0.5, v[120:121] op_sel_hi:[1,0,1]
	v_lshlrev_b32_e32 v124, 16, v184
	v_and_b32_e32 v125, 0xffff0000, v184
	v_lshlrev_b32_e32 v130, 16, v185
	v_and_b32_e32 v131, 0xffff0000, v185
	v_mul_f32_e32 v119, v111, v111
	v_mul_f32_e32 v120, v113, v113
	v_pk_fma_f32 v[108:109], v[108:109], 0.5, v[130:131] op_sel_hi:[1,0,1]
	v_pk_fma_f32 v[106:107], v[106:107], 0.5, v[124:125] op_sel_hi:[1,0,1]
	v_fmac_f32_e32 v119, v110, v110
	v_fmac_f32_e32 v120, v112, v112
	v_add_f32_e32 v119, v119, v120
	v_mul_f32_e32 v120, v107, v107
	v_mul_f32_e32 v121, v109, v109
	v_fmac_f32_e32 v120, v106, v106
	v_fmac_f32_e32 v121, v108, v108
	v_add_f32_e32 v120, v120, v121
	v_add_f32_e32 v119, v119, v120
	v_lshlrev_b32_e32 v120, 16, v178
	v_and_b32_e32 v121, 0xffff0000, v178
	v_lshlrev_b32_e32 v122, 16, v179
	v_and_b32_e32 v123, 0xffff0000, v179
	v_lshlrev_b32_e32 v124, 16, v180
	v_and_b32_e32 v125, 0xffff0000, v180
	v_pk_fma_f32 v[104:105], v[104:105], 0.5, v[122:123] op_sel_hi:[1,0,1]
	v_pk_fma_f32 v[102:103], v[102:103], 0.5, v[120:121] op_sel_hi:[1,0,1]
	v_lshlrev_b32_e32 v130, 16, v181
	v_and_b32_e32 v131, 0xffff0000, v181
	v_pk_fma_f32 v[120:121], v[98:99], 0.5, v[124:125] op_sel_hi:[1,0,1]
	v_mul_f32_e32 v98, v103, v103
	v_mul_f32_e32 v99, v105, v105
	v_pk_fma_f32 v[122:123], v[100:101], 0.5, v[130:131] op_sel_hi:[1,0,1]
	v_fmac_f32_e32 v98, v102, v102
	v_fmac_f32_e32 v99, v104, v104
	v_add_f32_e32 v98, v98, v99
	v_mul_f32_e32 v99, v121, v121
	v_mul_f32_e32 v100, v123, v123
	v_fmac_f32_e32 v99, v120, v120
	v_fmac_f32_e32 v100, v122, v122
	v_add_f32_e32 v99, v99, v100
	v_add_f32_e32 v98, v98, v99
	v_add_f32_e32 v119, v119, v98
	v_mov_b32_e32 v124, v119
	s_nop 1
	v_permlane16_swap_b32_e32 v124, v119
	v_lshlrev_b64 v[98:99], 12, v[220:221]
	v_lshl_add_u64 v[98:99], s[12:13], 0, v[98:99]
	v_lshl_add_u64 v[100:101], v[208:209], 2, v[98:99]
	global_store_dwordx4 v[100:101], v[110:113], off
	global_store_dwordx4 v[100:101], v[106:109], off offset:16
	global_store_dwordx4 v[100:101], v[102:105], off offset:512
	global_store_dwordx4 v[100:101], v[120:123], off offset:528
	s_waitcnt lgkmcnt(0)
	v_add_f32_e32 v98, v119, v124
	v_mov_b32_e32 v99, v98
	s_nop 1
	v_permlane32_swap_b32_e32 v99, v98
	s_and_saveexec_b64 s[44:45], s[4:5]
	s_cbranch_execz .LBB0_1916
	v_lshl_add_u64 v[100:101], v[220:221], 2, s[16:17]
	s_waitcnt lgkmcnt(0)
	v_add_f32_e32 v98, v98, v99
	global_atomic_add_f32 v[100:101], v98, off
.LBB0_1916:
	s_or_b64 exec, exec, s[44:45]
	v_lshlrev_b32_e32 v98, 16, v174
	s_waitcnt lgkmcnt(0)
	v_and_b32_e32 v99, 0xffff0000, v174
	v_lshlrev_b32_e32 v100, 16, v175
	v_and_b32_e32 v101, 0xffff0000, v175
	v_pk_fma_f32 v[96:97], v[96:97], 0.5, v[100:101] op_sel_hi:[1,0,1]
	v_pk_fma_f32 v[94:95], v[94:95], 0.5, v[98:99] op_sel_hi:[1,0,1]
	v_lshlrev_b32_e32 v102, 16, v176
	v_and_b32_e32 v103, 0xffff0000, v176
	v_lshlrev_b32_e32 v104, 16, v177
	v_and_b32_e32 v105, 0xffff0000, v177
	v_mul_f32_e32 v98, v95, v95
	v_mul_f32_e32 v99, v97, v97
	v_pk_fma_f32 v[92:93], v[92:93], 0.5, v[104:105] op_sel_hi:[1,0,1]
	v_pk_fma_f32 v[90:91], v[90:91], 0.5, v[102:103] op_sel_hi:[1,0,1]
	v_fmac_f32_e32 v98, v94, v94
	v_fmac_f32_e32 v99, v96, v96
	v_add_f32_e32 v98, v98, v99
	v_mul_f32_e32 v99, v91, v91
	v_mul_f32_e32 v100, v93, v93
	v_fmac_f32_e32 v99, v90, v90
	v_fmac_f32_e32 v100, v92, v92
	v_add_f32_e32 v99, v99, v100
	v_add_f32_e32 v106, v98, v99
	v_lshlrev_b32_e32 v98, 16, v170
	v_and_b32_e32 v99, 0xffff0000, v170
	v_lshlrev_b32_e32 v100, 16, v171
	v_and_b32_e32 v101, 0xffff0000, v171
	v_lshlrev_b32_e32 v102, 16, v172
	v_and_b32_e32 v103, 0xffff0000, v172
	v_pk_fma_f32 v[88:89], v[88:89], 0.5, v[100:101] op_sel_hi:[1,0,1]
	v_pk_fma_f32 v[86:87], v[86:87], 0.5, v[98:99] op_sel_hi:[1,0,1]
	v_lshlrev_b32_e32 v104, 16, v173
	v_and_b32_e32 v105, 0xffff0000, v173
	v_pk_fma_f32 v[98:99], v[82:83], 0.5, v[102:103] op_sel_hi:[1,0,1]
	v_mul_f32_e32 v82, v87, v87
	v_mul_f32_e32 v83, v89, v89
	v_pk_fma_f32 v[100:101], v[84:85], 0.5, v[104:105] op_sel_hi:[1,0,1]
	v_fmac_f32_e32 v82, v86, v86
	v_fmac_f32_e32 v83, v88, v88
	v_add_f32_e32 v82, v82, v83
	v_mul_f32_e32 v83, v99, v99
	v_mul_f32_e32 v84, v101, v101
	v_fmac_f32_e32 v83, v98, v98
	v_fmac_f32_e32 v84, v100, v100
	v_add_f32_e32 v83, v83, v84
	v_add_f32_e32 v82, v82, v83
	v_add_f32_e32 v102, v106, v82
	v_mov_b32_e32 v103, v102
	s_nop 1
	v_permlane16_swap_b32_e32 v103, v102
	v_lshlrev_b64 v[82:83], 12, v[218:219]
	v_lshl_add_u64 v[82:83], s[12:13], 0, v[82:83]
	v_lshl_add_u64 v[84:85], v[208:209], 2, v[82:83]
	global_store_dwordx4 v[84:85], v[94:97], off
	global_store_dwordx4 v[84:85], v[90:93], off offset:16
	global_store_dwordx4 v[84:85], v[86:89], off offset:512
	global_store_dwordx4 v[84:85], v[98:101], off offset:528
	s_waitcnt lgkmcnt(0)
	v_add_f32_e32 v82, v102, v103
	v_mov_b32_e32 v83, v82
	s_nop 1
	v_permlane32_swap_b32_e32 v83, v82
	s_and_saveexec_b64 s[44:45], s[4:5]
	s_cbranch_execz .LBB0_1918
	v_lshl_add_u64 v[84:85], v[218:219], 2, s[16:17]
	s_waitcnt lgkmcnt(0)
	v_add_f32_e32 v82, v82, v83
	global_atomic_add_f32 v[84:85], v82, off
.LBB0_1918:
	s_or_b64 exec, exec, s[44:45]
	v_lshlrev_b32_e32 v82, 16, v166
	s_waitcnt lgkmcnt(0)
	v_and_b32_e32 v83, 0xffff0000, v166
	v_lshlrev_b32_e32 v84, 16, v167
	v_and_b32_e32 v85, 0xffff0000, v167
	v_pk_fma_f32 v[80:81], v[80:81], 0.5, v[84:85] op_sel_hi:[1,0,1]
	v_pk_fma_f32 v[78:79], v[78:79], 0.5, v[82:83] op_sel_hi:[1,0,1]
	v_lshlrev_b32_e32 v86, 16, v168
	v_and_b32_e32 v87, 0xffff0000, v168
	v_lshlrev_b32_e32 v88, 16, v169
	v_and_b32_e32 v89, 0xffff0000, v169
	v_mul_f32_e32 v82, v79, v79
	v_mul_f32_e32 v83, v81, v81
	v_pk_fma_f32 v[76:77], v[76:77], 0.5, v[88:89] op_sel_hi:[1,0,1]
	v_pk_fma_f32 v[74:75], v[74:75], 0.5, v[86:87] op_sel_hi:[1,0,1]
	v_fmac_f32_e32 v82, v78, v78
	v_fmac_f32_e32 v83, v80, v80
	v_add_f32_e32 v82, v82, v83
	v_mul_f32_e32 v83, v75, v75
	v_mul_f32_e32 v84, v77, v77
	v_fmac_f32_e32 v83, v74, v74
	v_fmac_f32_e32 v84, v76, v76
	v_add_f32_e32 v83, v83, v84
	v_add_f32_e32 v90, v82, v83
	v_lshlrev_b32_e32 v82, 16, v162
	v_and_b32_e32 v83, 0xffff0000, v162
	v_lshlrev_b32_e32 v84, 16, v163
	v_and_b32_e32 v85, 0xffff0000, v163
	v_lshlrev_b32_e32 v86, 16, v164
	v_and_b32_e32 v87, 0xffff0000, v164
	v_pk_fma_f32 v[72:73], v[72:73], 0.5, v[84:85] op_sel_hi:[1,0,1]
	v_pk_fma_f32 v[70:71], v[70:71], 0.5, v[82:83] op_sel_hi:[1,0,1]
	v_lshlrev_b32_e32 v88, 16, v165
	v_and_b32_e32 v89, 0xffff0000, v165
	v_pk_fma_f32 v[82:83], v[66:67], 0.5, v[86:87] op_sel_hi:[1,0,1]
	v_mul_f32_e32 v66, v71, v71
	v_mul_f32_e32 v67, v73, v73
	v_pk_fma_f32 v[84:85], v[68:69], 0.5, v[88:89] op_sel_hi:[1,0,1]
	v_fmac_f32_e32 v66, v70, v70
	v_fmac_f32_e32 v67, v72, v72
	v_add_f32_e32 v66, v66, v67
	v_mul_f32_e32 v67, v83, v83
	v_mul_f32_e32 v68, v85, v85
	v_fmac_f32_e32 v67, v82, v82
	v_fmac_f32_e32 v68, v84, v84
	v_add_f32_e32 v67, v67, v68
	v_add_f32_e32 v66, v66, v67
	v_add_f32_e32 v86, v90, v66
	v_mov_b32_e32 v87, v86
	s_nop 1
	v_permlane16_swap_b32_e32 v87, v86
	v_lshlrev_b64 v[66:67], 12, v[216:217]
	v_lshl_add_u64 v[66:67], s[12:13], 0, v[66:67]
	v_lshl_add_u64 v[68:69], v[208:209], 2, v[66:67]
	global_store_dwordx4 v[68:69], v[78:81], off
	global_store_dwordx4 v[68:69], v[74:77], off offset:16
	global_store_dwordx4 v[68:69], v[70:73], off offset:512
	global_store_dwordx4 v[68:69], v[82:85], off offset:528
	s_waitcnt lgkmcnt(0)
	v_add_f32_e32 v66, v86, v87
	v_mov_b32_e32 v67, v66
	s_nop 1
	v_permlane32_swap_b32_e32 v67, v66
	s_and_saveexec_b64 s[44:45], s[4:5]
	s_cbranch_execz .LBB0_1920
	v_lshl_add_u64 v[68:69], v[216:217], 2, s[16:17]
	s_waitcnt lgkmcnt(0)
	v_add_f32_e32 v66, v66, v67
	global_atomic_add_f32 v[68:69], v66, off
.LBB0_1920:
	s_or_b64 exec, exec, s[44:45]
	v_lshlrev_b32_e32 v66, 16, v158
	s_waitcnt lgkmcnt(0)
	v_and_b32_e32 v67, 0xffff0000, v158
	v_lshlrev_b32_e32 v68, 16, v159
	v_and_b32_e32 v69, 0xffff0000, v159
	v_pk_fma_f32 v[64:65], v[64:65], 0.5, v[68:69] op_sel_hi:[1,0,1]
	v_pk_fma_f32 v[62:63], v[62:63], 0.5, v[66:67] op_sel_hi:[1,0,1]
	v_lshlrev_b32_e32 v70, 16, v160
	v_and_b32_e32 v71, 0xffff0000, v160
	v_lshlrev_b32_e32 v72, 16, v161
	v_and_b32_e32 v73, 0xffff0000, v161
	v_mul_f32_e32 v66, v63, v63
	v_mul_f32_e32 v67, v65, v65
	v_pk_fma_f32 v[60:61], v[60:61], 0.5, v[72:73] op_sel_hi:[1,0,1]
	v_pk_fma_f32 v[58:59], v[58:59], 0.5, v[70:71] op_sel_hi:[1,0,1]
	v_fmac_f32_e32 v66, v62, v62
	v_fmac_f32_e32 v67, v64, v64
	v_add_f32_e32 v66, v66, v67
	v_mul_f32_e32 v67, v59, v59
	v_mul_f32_e32 v68, v61, v61
	v_fmac_f32_e32 v67, v58, v58
	v_fmac_f32_e32 v68, v60, v60
	v_add_f32_e32 v67, v67, v68
	v_add_f32_e32 v74, v66, v67
	v_lshlrev_b32_e32 v66, 16, v154
	v_and_b32_e32 v67, 0xffff0000, v154
	v_lshlrev_b32_e32 v68, 16, v155
	v_and_b32_e32 v69, 0xffff0000, v155
	v_lshlrev_b32_e32 v70, 16, v156
	v_and_b32_e32 v71, 0xffff0000, v156
	v_pk_fma_f32 v[56:57], v[56:57], 0.5, v[68:69] op_sel_hi:[1,0,1]
	v_pk_fma_f32 v[54:55], v[54:55], 0.5, v[66:67] op_sel_hi:[1,0,1]
	v_lshlrev_b32_e32 v72, 16, v157
	v_and_b32_e32 v73, 0xffff0000, v157
	v_pk_fma_f32 v[66:67], v[50:51], 0.5, v[70:71] op_sel_hi:[1,0,1]
	v_mul_f32_e32 v50, v55, v55
	v_mul_f32_e32 v51, v57, v57
	v_pk_fma_f32 v[68:69], v[52:53], 0.5, v[72:73] op_sel_hi:[1,0,1]
	v_fmac_f32_e32 v50, v54, v54
	v_fmac_f32_e32 v51, v56, v56
	v_add_f32_e32 v50, v50, v51
	v_mul_f32_e32 v51, v67, v67
	v_mul_f32_e32 v52, v69, v69
	v_fmac_f32_e32 v51, v66, v66
	v_fmac_f32_e32 v52, v68, v68
	v_add_f32_e32 v51, v51, v52
	v_add_f32_e32 v50, v50, v51
	v_add_f32_e32 v70, v74, v50
	v_mov_b32_e32 v71, v70
	s_nop 1
	v_permlane16_swap_b32_e32 v71, v70
	v_lshlrev_b64 v[50:51], 12, v[214:215]
	v_lshl_add_u64 v[50:51], s[12:13], 0, v[50:51]
	v_lshl_add_u64 v[52:53], v[208:209], 2, v[50:51]
	global_store_dwordx4 v[52:53], v[62:65], off
	global_store_dwordx4 v[52:53], v[58:61], off offset:16
	global_store_dwordx4 v[52:53], v[54:57], off offset:512
	global_store_dwordx4 v[52:53], v[66:69], off offset:528
	s_waitcnt lgkmcnt(0)
	v_add_f32_e32 v50, v70, v71
	v_mov_b32_e32 v51, v50
	s_nop 1
	v_permlane32_swap_b32_e32 v51, v50
	s_and_saveexec_b64 s[44:45], s[4:5]
	s_cbranch_execz .LBB0_1922
	v_lshl_add_u64 v[52:53], v[214:215], 2, s[16:17]
	s_waitcnt lgkmcnt(0)
	v_add_f32_e32 v50, v50, v51
	global_atomic_add_f32 v[52:53], v50, off
.LBB0_1922:
	s_or_b64 exec, exec, s[44:45]
	v_lshlrev_b32_e32 v50, 16, v150
	s_waitcnt lgkmcnt(0)
	v_and_b32_e32 v51, 0xffff0000, v150
	v_lshlrev_b32_e32 v52, 16, v151
	v_and_b32_e32 v53, 0xffff0000, v151
	v_pk_fma_f32 v[48:49], v[48:49], 0.5, v[52:53] op_sel_hi:[1,0,1]
	v_pk_fma_f32 v[46:47], v[46:47], 0.5, v[50:51] op_sel_hi:[1,0,1]
	v_lshlrev_b32_e32 v54, 16, v152
	v_and_b32_e32 v55, 0xffff0000, v152
	v_lshlrev_b32_e32 v56, 16, v153
	v_and_b32_e32 v57, 0xffff0000, v153
	v_mul_f32_e32 v50, v47, v47
	v_mul_f32_e32 v51, v49, v49
	v_pk_fma_f32 v[44:45], v[44:45], 0.5, v[56:57] op_sel_hi:[1,0,1]
	v_pk_fma_f32 v[42:43], v[42:43], 0.5, v[54:55] op_sel_hi:[1,0,1]
	v_fmac_f32_e32 v50, v46, v46
	v_fmac_f32_e32 v51, v48, v48
	v_add_f32_e32 v50, v50, v51
	v_mul_f32_e32 v51, v43, v43
	v_mul_f32_e32 v52, v45, v45
	v_fmac_f32_e32 v51, v42, v42
	v_fmac_f32_e32 v52, v44, v44
	v_add_f32_e32 v51, v51, v52
	v_add_f32_e32 v58, v50, v51
	v_lshlrev_b32_e32 v50, 16, v146
	v_and_b32_e32 v51, 0xffff0000, v146
	v_lshlrev_b32_e32 v52, 16, v147
	v_and_b32_e32 v53, 0xffff0000, v147
	v_lshlrev_b32_e32 v54, 16, v148
	v_and_b32_e32 v55, 0xffff0000, v148
	v_pk_fma_f32 v[40:41], v[40:41], 0.5, v[52:53] op_sel_hi:[1,0,1]
	v_pk_fma_f32 v[38:39], v[38:39], 0.5, v[50:51] op_sel_hi:[1,0,1]
	v_lshlrev_b32_e32 v56, 16, v149
	v_and_b32_e32 v57, 0xffff0000, v149
	v_pk_fma_f32 v[50:51], v[34:35], 0.5, v[54:55] op_sel_hi:[1,0,1]
	v_mul_f32_e32 v34, v39, v39
	v_mul_f32_e32 v35, v41, v41
	v_pk_fma_f32 v[52:53], v[36:37], 0.5, v[56:57] op_sel_hi:[1,0,1]
	v_fmac_f32_e32 v34, v38, v38
	v_fmac_f32_e32 v35, v40, v40
	v_add_f32_e32 v34, v34, v35
	v_mul_f32_e32 v35, v51, v51
	v_mul_f32_e32 v36, v53, v53
	v_fmac_f32_e32 v35, v50, v50
	v_fmac_f32_e32 v36, v52, v52
	v_add_f32_e32 v35, v35, v36
	v_add_f32_e32 v34, v34, v35
	v_add_f32_e32 v54, v58, v34
	v_mov_b32_e32 v55, v54
	s_nop 1
	v_permlane16_swap_b32_e32 v55, v54
	v_lshlrev_b64 v[34:35], 12, v[212:213]
	v_lshl_add_u64 v[34:35], s[12:13], 0, v[34:35]
	v_lshl_add_u64 v[36:37], v[208:209], 2, v[34:35]
	global_store_dwordx4 v[36:37], v[46:49], off
	global_store_dwordx4 v[36:37], v[42:45], off offset:16
	global_store_dwordx4 v[36:37], v[38:41], off offset:512
	global_store_dwordx4 v[36:37], v[50:53], off offset:528
	s_waitcnt lgkmcnt(0)
	v_add_f32_e32 v34, v54, v55
	v_mov_b32_e32 v35, v34
	s_nop 1
	v_permlane32_swap_b32_e32 v35, v34
	s_and_saveexec_b64 s[44:45], s[4:5]
	s_cbranch_execz .LBB0_1924
	v_lshl_add_u64 v[36:37], v[212:213], 2, s[16:17]
	s_waitcnt lgkmcnt(0)
	v_add_f32_e32 v34, v34, v35
	global_atomic_add_f32 v[36:37], v34, off
.LBB0_1924:
	s_or_b64 exec, exec, s[44:45]
	v_lshlrev_b32_e32 v34, 16, v142
	s_waitcnt lgkmcnt(0)
	v_and_b32_e32 v35, 0xffff0000, v142
	v_lshlrev_b32_e32 v36, 16, v143
	v_and_b32_e32 v37, 0xffff0000, v143
	v_pk_fma_f32 v[32:33], v[32:33], 0.5, v[36:37] op_sel_hi:[1,0,1]
	v_pk_fma_f32 v[30:31], v[30:31], 0.5, v[34:35] op_sel_hi:[1,0,1]
	v_lshlrev_b32_e32 v38, 16, v144
	v_and_b32_e32 v39, 0xffff0000, v144
	v_lshlrev_b32_e32 v40, 16, v145
	v_and_b32_e32 v41, 0xffff0000, v145
	v_mul_f32_e32 v34, v31, v31
	v_mul_f32_e32 v35, v33, v33
	v_pk_fma_f32 v[28:29], v[28:29], 0.5, v[40:41] op_sel_hi:[1,0,1]
	v_pk_fma_f32 v[26:27], v[26:27], 0.5, v[38:39] op_sel_hi:[1,0,1]
	v_fmac_f32_e32 v34, v30, v30
	v_fmac_f32_e32 v35, v32, v32
	v_add_f32_e32 v34, v34, v35
	v_mul_f32_e32 v35, v27, v27
	v_mul_f32_e32 v36, v29, v29
	v_fmac_f32_e32 v35, v26, v26
	v_fmac_f32_e32 v36, v28, v28
	v_add_f32_e32 v35, v35, v36
	v_add_f32_e32 v42, v34, v35
	v_lshlrev_b32_e32 v34, 16, v138
	v_and_b32_e32 v35, 0xffff0000, v138
	v_lshlrev_b32_e32 v36, 16, v139
	v_and_b32_e32 v37, 0xffff0000, v139
	v_lshlrev_b32_e32 v38, 16, v140
	v_and_b32_e32 v39, 0xffff0000, v140
	v_pk_fma_f32 v[24:25], v[24:25], 0.5, v[36:37] op_sel_hi:[1,0,1]
	v_pk_fma_f32 v[22:23], v[22:23], 0.5, v[34:35] op_sel_hi:[1,0,1]
	v_lshlrev_b32_e32 v40, 16, v141
	v_and_b32_e32 v41, 0xffff0000, v141
	v_pk_fma_f32 v[34:35], v[18:19], 0.5, v[38:39] op_sel_hi:[1,0,1]
	v_mul_f32_e32 v18, v23, v23
	v_mul_f32_e32 v19, v25, v25
	v_pk_fma_f32 v[36:37], v[20:21], 0.5, v[40:41] op_sel_hi:[1,0,1]
	v_fmac_f32_e32 v18, v22, v22
	v_fmac_f32_e32 v19, v24, v24
	v_add_f32_e32 v18, v18, v19
	v_mul_f32_e32 v19, v35, v35
	v_mul_f32_e32 v20, v37, v37
	v_fmac_f32_e32 v19, v34, v34
	v_fmac_f32_e32 v20, v36, v36
	v_add_f32_e32 v19, v19, v20
	v_add_f32_e32 v18, v18, v19
	v_add_f32_e32 v38, v42, v18
	v_mov_b32_e32 v39, v38
	s_nop 1
	v_permlane16_swap_b32_e32 v39, v38
	v_lshlrev_b64 v[18:19], 12, v[210:211]
	v_lshl_add_u64 v[18:19], s[12:13], 0, v[18:19]
	v_lshl_add_u64 v[20:21], v[208:209], 2, v[18:19]
	global_store_dwordx4 v[20:21], v[30:33], off
	global_store_dwordx4 v[20:21], v[26:29], off offset:16
	global_store_dwordx4 v[20:21], v[22:25], off offset:512
	global_store_dwordx4 v[20:21], v[34:37], off offset:528
	s_waitcnt lgkmcnt(0)
	v_add_f32_e32 v18, v38, v39
	v_mov_b32_e32 v19, v18
	s_nop 1
	v_permlane32_swap_b32_e32 v19, v18
	s_and_saveexec_b64 s[44:45], s[4:5]
	s_cbranch_execz .LBB0_1926
	v_lshl_add_u64 v[20:21], v[210:211], 2, s[16:17]
	s_waitcnt lgkmcnt(0)
	v_add_f32_e32 v18, v18, v19
	global_atomic_add_f32 v[20:21], v18, off
.LBB0_1926:
	s_or_b64 exec, exec, s[44:45]
	v_lshlrev_b32_e32 v18, 16, v126
	s_waitcnt lgkmcnt(0)
	v_and_b32_e32 v19, 0xffff0000, v126
	v_lshlrev_b32_e32 v20, 16, v127
	v_and_b32_e32 v21, 0xffff0000, v127
	v_pk_fma_f32 v[16:17], v[16:17], 0.5, v[20:21] op_sel_hi:[1,0,1]
	v_pk_fma_f32 v[14:15], v[14:15], 0.5, v[18:19] op_sel_hi:[1,0,1]
	v_lshlrev_b32_e32 v22, 16, v128
	v_and_b32_e32 v23, 0xffff0000, v128
	v_lshlrev_b32_e32 v24, 16, v129
	v_and_b32_e32 v25, 0xffff0000, v129
	v_mul_f32_e32 v18, v15, v15
	v_mul_f32_e32 v19, v17, v17
	v_pk_fma_f32 v[12:13], v[12:13], 0.5, v[24:25] op_sel_hi:[1,0,1]
	v_pk_fma_f32 v[10:11], v[10:11], 0.5, v[22:23] op_sel_hi:[1,0,1]
	v_fmac_f32_e32 v18, v14, v14
	v_fmac_f32_e32 v19, v16, v16
	v_add_f32_e32 v18, v18, v19
	v_mul_f32_e32 v19, v11, v11
	v_mul_f32_e32 v20, v13, v13
	v_fmac_f32_e32 v19, v10, v10
	v_fmac_f32_e32 v20, v12, v12
	v_add_f32_e32 v19, v19, v20
	v_add_f32_e32 v26, v18, v19
	v_lshlrev_b32_e32 v18, 16, v114
	v_and_b32_e32 v19, 0xffff0000, v114
	v_lshlrev_b32_e32 v20, 16, v115
	v_and_b32_e32 v21, 0xffff0000, v115
	v_lshlrev_b32_e32 v22, 16, v116
	v_and_b32_e32 v23, 0xffff0000, v116
	v_pk_fma_f32 v[8:9], v[8:9], 0.5, v[20:21] op_sel_hi:[1,0,1]
	v_pk_fma_f32 v[6:7], v[6:7], 0.5, v[18:19] op_sel_hi:[1,0,1]
	v_lshlrev_b32_e32 v24, 16, v117
	v_and_b32_e32 v25, 0xffff0000, v117
	v_pk_fma_f32 v[18:19], v[2:3], 0.5, v[22:23] op_sel_hi:[1,0,1]
	v_mul_f32_e32 v2, v7, v7
	v_mul_f32_e32 v3, v9, v9
	v_pk_fma_f32 v[20:21], v[4:5], 0.5, v[24:25] op_sel_hi:[1,0,1]
	v_fmac_f32_e32 v2, v6, v6
	v_fmac_f32_e32 v3, v8, v8
	v_add_f32_e32 v2, v2, v3
	v_mul_f32_e32 v3, v19, v19
	v_mul_f32_e32 v4, v21, v21
	v_fmac_f32_e32 v3, v18, v18
	v_fmac_f32_e32 v4, v20, v20
	v_add_f32_e32 v3, v3, v4
	v_add_f32_e32 v2, v2, v3
	v_add_f32_e32 v22, v26, v2
	v_mov_b32_e32 v23, v22
	s_nop 1
	v_permlane16_swap_b32_e32 v23, v22
	v_lshlrev_b64 v[2:3], 12, v[206:207]
	v_lshl_add_u64 v[2:3], s[12:13], 0, v[2:3]
	v_lshl_add_u64 v[4:5], v[208:209], 2, v[2:3]
	global_store_dwordx4 v[4:5], v[14:17], off
	global_store_dwordx4 v[4:5], v[10:13], off offset:16
	global_store_dwordx4 v[4:5], v[6:9], off offset:512
	global_store_dwordx4 v[4:5], v[18:21], off offset:528
	s_waitcnt lgkmcnt(0)
	v_add_f32_e32 v2, v22, v23
	v_mov_b32_e32 v3, v2
	s_nop 1
	v_permlane32_swap_b32_e32 v3, v2
	s_and_saveexec_b64 s[44:45], s[4:5]
	s_cbranch_execz .LBB0_1928
	v_lshl_add_u64 v[4:5], v[206:207], 2, s[16:17]
	s_waitcnt lgkmcnt(0)
	v_add_f32_e32 v2, v2, v3
	global_atomic_add_f32 v[4:5], v2, off
